# attention item loop: MFMAs woven between softmax/score VALU (in-wave MFMA-VALU overlap)
# baseline (speedup 1.0000x reference)
.Lat738_i0_nopend:
	s_add_u32 s83, s4, 1
	s_mov_b32 s84, s5
	s_mul_i32 s74, s84, 4096
	s_lshl_b32 s75, s83, 7
	s_add_u32 s74, s74, s75
	s_lshl_b32 s75, s74, 7
	s_add_u32 s16, s60, s75
	s_addc_u32 s17, s61, 0
	s_lshl_b32 s75, s74, 1
	s_add_u32 s24, s64, s75
	s_addc_u32 s25, s65, 0
	s_add_u32 m0, s70, 0x4000
	s_nop 0
	global_load_lds_dwordx4 v232, s[16:17]
	s_add_u32 m0, s70, 0x6000
	s_nop 0
	global_load_lds_dwordx4 v233, s[16:17]
	s_add_u32 m0, s70, 0x14000
	s_nop 0
	global_load_lds_dwordx4 v234, s[24:25]
	s_add_u32 m0, s70, 0x16000
	s_nop 0
	global_load_lds_dwordx4 v235, s[24:25]
	s_lshl_b32 s74, s83, 7
	s_add_u32 s74, s74, s84
	s_lshl_b32 s75, s74, 7
	s_add_u32 s10, s30, s75
	s_addc_u32 s11, s31, 0
	s_add_u32 s12, s34, s75
	s_addc_u32 s13, s35, 0
	s_lshl_b32 s75, s74, 2
	s_add_u32 s14, s58, s75
	s_addc_u32 s15, s59, 0
	global_load_dwordx4 v[104:107], v236, s[10:11]
	global_load_dwordx4 v[108:111], v236, s[10:11] offset:64
	s_waitcnt lgkmcnt(0)
	v_mfma_f32_16x16x32_bf16 v[44:47], v[4:7], v[96:99], 0
	v_mfma_f32_16x16x32_bf16 v[48:51], v[12:15], v[96:99], 0
	v_mfma_f32_16x16x32_bf16 v[52:55], v[20:23], v[96:99], 0
	v_mfma_f32_16x16x32_bf16 v[56:59], v[28:31], v[96:99], 0
	v_mfma_f32_16x16x32_bf16 v[60:63], v[36:39], v[96:99], 0
	v_mfma_f32_16x16x32_bf16 v[44:47], v[8:11], v[100:103], v[44:47]
	v_mfma_f32_16x16x32_bf16 v[48:51], v[16:19], v[100:103], v[48:51]
	v_mfma_f32_16x16x32_bf16 v[52:55], v[24:27], v[100:103], v[52:55]
	v_mfma_f32_16x16x32_bf16 v[56:59], v[32:35], v[100:103], v[56:59]
	v_mfma_f32_16x16x32_bf16 v[60:63], v[40:43], v[100:103], v[60:63]
	s_cmp_gt_u32 s6, 5
	s_cselect_b32 s74, s77, s78
	v_add_u32_e32 v146, s74, v230
	v_xor_b32_e32 v147, 64, v146
	ds_read_b128 v[4:7], v146 offset:10240
	ds_read_b128 v[8:11], v147 offset:10240
	s_cmp_gt_u32 s6, 6
	s_cselect_b32 s74, s77, s78
	v_add_u32_e32 v146, s74, v230
	v_xor_b32_e32 v147, 64, v146
	ds_read_b128 v[12:15], v146 offset:12288
	ds_read_b128 v[16:19], v147 offset:12288
	s_cmp_gt_u32 s6, 7
	s_cselect_b32 s74, s77, s78
	v_add_u32_e32 v146, s74, v230
	v_xor_b32_e32 v147, 64, v146
	ds_read_b128 v[20:23], v146 offset:14336
	ds_read_b128 v[24:27], v147 offset:14336
	s_cmp_gt_u32 s6, 8
	s_cselect_b32 s74, s77, s78
	v_add_u32_e32 v146, s74, v230
	v_xor_b32_e32 v147, 64, v146
	ds_read_b128 v[28:31], v146 offset:16384
	ds_read_b128 v[32:35], v147 offset:16384
	s_nop 1
	v_fma_f32 v44, v44, s79, v185
	v_fma_f32 v45, v45, s79, v186
	v_fma_f32 v46, v46, s79, v187
	v_fma_f32 v47, v47, s79, v188
	v_fma_f32 v48, v48, s79, v189
	v_fma_f32 v49, v49, s79, v190
	s_waitcnt lgkmcnt(0)
	v_mfma_f32_16x16x32_bf16 v[64:67], v[4:7], v[96:99], 0
	v_fma_f32 v50, v50, s79, v191
	v_fma_f32 v51, v51, s79, v192
	v_mfma_f32_16x16x32_bf16 v[68:71], v[12:15], v[96:99], 0
	v_fma_f32 v52, v52, s79, v193
	v_fma_f32 v53, v53, s79, v194
	v_mfma_f32_16x16x32_bf16 v[72:75], v[20:23], v[96:99], 0
	v_fma_f32 v54, v54, s79, v195
	v_fma_f32 v55, v55, s79, v196
	v_mfma_f32_16x16x32_bf16 v[76:79], v[28:31], v[96:99], 0
	v_fma_f32 v56, v56, s79, v197
	v_fma_f32 v57, v57, s79, v198
	v_mfma_f32_16x16x32_bf16 v[64:67], v[8:11], v[100:103], v[64:67]
	v_fma_f32 v58, v58, s79, v199
	v_fma_f32 v59, v59, s79, v200
	v_mfma_f32_16x16x32_bf16 v[68:71], v[16:19], v[100:103], v[68:71]
	v_fma_f32 v60, v60, s79, v201
	v_fma_f32 v61, v61, s79, v202
	v_mfma_f32_16x16x32_bf16 v[72:75], v[24:27], v[100:103], v[72:75]
	v_fma_f32 v62, v62, s79, v203
	v_fma_f32 v63, v63, s79, v204
	v_mfma_f32_16x16x32_bf16 v[76:79], v[32:35], v[100:103], v[76:79]
	s_cmp_gt_u32 s6, 0
	s_cselect_b32 s74, 0, 0xffff0000
	v_add_u32_e32 v146, s74, v221
	ds_read_b64 v[4:5], v146 offset:49152
	ds_read_b64 v[8:9], v146 offset:53248
	ds_read_b64 v[12:13], v146 offset:57344
	ds_read_b64 v[16:17], v146 offset:61440
	s_cmp_gt_u32 s6, 1
	s_cselect_b32 s74, 0, 0xffff0000
	v_add_u32_e32 v146, s74, v222
	ds_read_b64 v[6:7], v146 offset:49152
	ds_read_b64 v[10:11], v146 offset:53248
	ds_read_b64 v[14:15], v146 offset:57344
	ds_read_b64 v[18:19], v146 offset:61440
	s_nop 1
	v_fma_f32 v64, v64, s79, v205
	v_fma_f32 v65, v65, s79, v206
	v_fma_f32 v66, v66, s79, v207
	v_fma_f32 v67, v67, s79, v208
	v_fma_f32 v68, v68, s79, v209
	v_fma_f32 v69, v69, s79, v210
	v_fma_f32 v70, v70, s79, v211
	v_fma_f32 v71, v71, s79, v212
	v_fma_f32 v72, v72, s79, v213
	v_fma_f32 v73, v73, s79, v214
	v_fma_f32 v74, v74, s79, v215
	v_fma_f32 v75, v75, s79, v216
	v_fma_f32 v76, v76, s79, v217
	v_fma_f32 v77, v77, s79, v218
	v_fma_f32 v78, v78, s79, v219
	v_fma_f32 v79, v79, s79, v220
	s_cmp_gt_u32 s6, 2
	s_cselect_b32 s74, 0, 0xffff0000
	v_add_u32_e32 v146, s74, v223
	ds_read_b64 v[20:21], v146 offset:49152
	ds_read_b64 v[24:25], v146 offset:53248
	ds_read_b64 v[28:29], v146 offset:57344
	ds_read_b64 v[32:33], v146 offset:61440
	s_cmp_gt_u32 s6, 3
	s_cselect_b32 s74, 0, 0xffff0000
	v_add_u32_e32 v146, s74, v224
	ds_read_b64 v[22:23], v146 offset:49152
	ds_read_b64 v[26:27], v146 offset:53248
	ds_read_b64 v[30:31], v146 offset:57344
	ds_read_b64 v[34:35], v146 offset:61440
	s_cmp_lg_u32 s4, 0
	s_cbranch_scc1 .Lat738_i0_nomask
	s_cmp_le_u32 s6, 0
	s_cbranch_scc1 .Lat738_i0_nomask
	v_mov_b32_e32 v44, v244
	v_mov_b32_e32 v45, v244
	v_mov_b32_e32 v46, v244
	v_mov_b32_e32 v47, v244
	s_cmp_le_u32 s6, 1
	s_cbranch_scc1 .Lat738_i0_nomask
	v_mov_b32_e32 v48, v244
	v_mov_b32_e32 v49, v244
	v_mov_b32_e32 v50, v244
	v_mov_b32_e32 v51, v244
	s_cmp_le_u32 s6, 2
	s_cbranch_scc1 .Lat738_i0_nomask
	v_mov_b32_e32 v52, v244
	v_mov_b32_e32 v53, v244
	v_mov_b32_e32 v54, v244
	v_mov_b32_e32 v55, v244
	s_cmp_le_u32 s6, 3
	s_cbranch_scc1 .Lat738_i0_nomask
	v_mov_b32_e32 v56, v244
	v_mov_b32_e32 v57, v244
	v_mov_b32_e32 v58, v244
	v_mov_b32_e32 v59, v244
	s_cmp_le_u32 s6, 4
	s_cbranch_scc1 .Lat738_i0_nomask
	v_mov_b32_e32 v60, v244
	v_mov_b32_e32 v61, v244
	v_mov_b32_e32 v62, v244
	v_mov_b32_e32 v63, v244
	s_cmp_le_u32 s6, 5
	s_cbranch_scc1 .Lat738_i0_nomask
	v_mov_b32_e32 v64, v244
	v_mov_b32_e32 v65, v244
	v_mov_b32_e32 v66, v244
	v_mov_b32_e32 v67, v244
	s_cmp_le_u32 s6, 6
	s_cbranch_scc1 .Lat738_i0_nomask
	v_mov_b32_e32 v68, v244
	v_mov_b32_e32 v69, v244
	v_mov_b32_e32 v70, v244
	v_mov_b32_e32 v71, v244
	s_cmp_le_u32 s6, 7
	s_cbranch_scc1 .Lat738_i0_nomask
	v_mov_b32_e32 v72, v244
	v_mov_b32_e32 v73, v244
	v_mov_b32_e32 v74, v244
	v_mov_b32_e32 v75, v244
.Lat738_i0_nomask:
	v_max3_f32 v245, v44, v45, v46
	v_max3_f32 v245, v245, v47, v48
	v_max3_f32 v245, v245, v49, v50
	v_max3_f32 v245, v245, v51, v52
	v_max3_f32 v245, v245, v53, v54
	v_max3_f32 v245, v245, v55, v56
	v_max3_f32 v245, v245, v57, v58
	v_max3_f32 v245, v245, v59, v60
	v_max3_f32 v245, v245, v61, v62
	v_max3_f32 v245, v245, v63, v64
	v_max3_f32 v245, v245, v65, v66
	v_max3_f32 v245, v245, v67, v68
	v_max3_f32 v245, v245, v69, v70
	v_max3_f32 v245, v245, v71, v72
	v_max3_f32 v245, v245, v73, v74
	v_max3_f32 v245, v245, v75, v76
	v_max3_f32 v245, v245, v77, v78
	v_max_f32_e32 v245, v245, v79
	ds_bpermute_b32 v148, v239, v245
	s_waitcnt lgkmcnt(0)
	v_max_f32_e32 v245, v245, v148
	ds_bpermute_b32 v148, v240, v245
	s_waitcnt lgkmcnt(0)
	v_max_f32_e32 v245, v245, v148
	v_sub_f32_e32 v44, v44, v245
	v_sub_f32_e32 v45, v45, v245
	v_sub_f32_e32 v46, v46, v245
	v_sub_f32_e32 v47, v47, v245
	v_exp_f32_e32 v44, v44
	v_exp_f32_e32 v45, v45
	v_exp_f32_e32 v46, v46
	v_exp_f32_e32 v47, v47
	v_sub_f32_e32 v48, v48, v245
	v_sub_f32_e32 v49, v49, v245
	v_sub_f32_e32 v50, v50, v245
	v_sub_f32_e32 v51, v51, v245
	v_exp_f32_e32 v48, v48
	v_exp_f32_e32 v49, v49
	v_exp_f32_e32 v50, v50
	v_exp_f32_e32 v51, v51
	v_mov_b32_e32 v149, v44
	v_mov_b32_e32 v150, v45
	v_mov_b32_e32 v151, v46
	v_mov_b32_e32 v152, v47
	v_cvt_pk_bf16_f32 v44, v44, v45
	v_cvt_pk_bf16_f32 v45, v46, v47
	v_sub_f32_e32 v52, v52, v245
	v_sub_f32_e32 v53, v53, v245
	v_sub_f32_e32 v54, v54, v245
	v_sub_f32_e32 v55, v55, v245
	v_exp_f32_e32 v52, v52
	v_exp_f32_e32 v53, v53
	v_exp_f32_e32 v54, v54
	v_exp_f32_e32 v55, v55
	v_add_f32_e32 v149, v149, v48
	v_add_f32_e32 v150, v150, v49
	v_add_f32_e32 v151, v151, v50
	v_add_f32_e32 v152, v152, v51
	v_cvt_pk_bf16_f32 v46, v48, v49
	v_cvt_pk_bf16_f32 v47, v50, v51
	s_waitcnt lgkmcnt(0)
	v_sub_f32_e32 v56, v56, v245
	v_sub_f32_e32 v57, v57, v245
	v_mfma_f32_16x16x32_bf16 v[80:83], v[4:7], v[44:47], 0
	v_sub_f32_e32 v58, v58, v245
	v_sub_f32_e32 v59, v59, v245
	v_exp_f32_e32 v56, v56
	v_mfma_f32_16x16x32_bf16 v[84:87], v[8:11], v[44:47], 0
	v_exp_f32_e32 v57, v57
	v_exp_f32_e32 v58, v58
	v_exp_f32_e32 v59, v59
	v_mfma_f32_16x16x32_bf16 v[88:91], v[12:15], v[44:47], 0
	v_add_f32_e32 v149, v149, v52
	v_add_f32_e32 v150, v150, v53
	v_add_f32_e32 v151, v151, v54
	v_mfma_f32_16x16x32_bf16 v[92:95], v[16:19], v[44:47], 0
	v_add_f32_e32 v152, v152, v55
	v_cvt_pk_bf16_f32 v52, v52, v53
	v_cvt_pk_bf16_f32 v53, v54, v55
	s_cmp_gt_u32 s6, 4
	s_cselect_b32 s74, 0, 0xffff0000
	v_add_u32_e32 v146, s74, v225
	ds_read_b64 v[4:5], v146 offset:49152
	ds_read_b64 v[8:9], v146 offset:53248
	ds_read_b64 v[12:13], v146 offset:57344
	ds_read_b64 v[16:17], v146 offset:61440
	s_cmp_gt_u32 s6, 5
	s_cselect_b32 s74, 0, 0xffff0000
	v_add_u32_e32 v146, s74, v226
	ds_read_b64 v[6:7], v146 offset:49152
	ds_read_b64 v[10:11], v146 offset:53248
	ds_read_b64 v[14:15], v146 offset:57344
	ds_read_b64 v[18:19], v146 offset:61440
	v_sub_f32_e32 v60, v60, v245
	v_sub_f32_e32 v61, v61, v245
	v_sub_f32_e32 v62, v62, v245
	v_sub_f32_e32 v63, v63, v245
	v_exp_f32_e32 v60, v60
	v_exp_f32_e32 v61, v61
	v_exp_f32_e32 v62, v62
	v_exp_f32_e32 v63, v63
	v_add_f32_e32 v149, v149, v56
	v_add_f32_e32 v150, v150, v57
	v_add_f32_e32 v151, v151, v58
	v_add_f32_e32 v152, v152, v59
	v_cvt_pk_bf16_f32 v54, v56, v57
	v_cvt_pk_bf16_f32 v55, v58, v59
	v_sub_f32_e32 v64, v64, v245
	v_sub_f32_e32 v65, v65, v245
	v_mfma_f32_16x16x32_bf16 v[80:83], v[20:23], v[52:55], v[80:83]
	v_sub_f32_e32 v66, v66, v245
	v_sub_f32_e32 v67, v67, v245
	v_exp_f32_e32 v64, v64
	v_mfma_f32_16x16x32_bf16 v[84:87], v[24:27], v[52:55], v[84:87]
	v_exp_f32_e32 v65, v65
	v_exp_f32_e32 v66, v66
	v_exp_f32_e32 v67, v67
	v_mfma_f32_16x16x32_bf16 v[88:91], v[28:31], v[52:55], v[88:91]
	v_add_f32_e32 v149, v149, v60
	v_add_f32_e32 v150, v150, v61
	v_add_f32_e32 v151, v151, v62
	v_mfma_f32_16x16x32_bf16 v[92:95], v[32:35], v[52:55], v[92:95]
	v_add_f32_e32 v152, v152, v63
	v_cvt_pk_bf16_f32 v60, v60, v61
	v_cvt_pk_bf16_f32 v61, v62, v63
	s_cmp_gt_u32 s6, 6
	s_cselect_b32 s74, 0, 0xffff0000
	v_add_u32_e32 v146, s74, v227
	ds_read_b64 v[20:21], v146 offset:49152
	ds_read_b64 v[24:25], v146 offset:53248
	ds_read_b64 v[28:29], v146 offset:57344
	ds_read_b64 v[32:33], v146 offset:61440
	s_cmp_gt_u32 s6, 7
	s_cselect_b32 s74, 0, 0xffff0000
	v_add_u32_e32 v146, s74, v228
	ds_read_b64 v[22:23], v146 offset:49152
	ds_read_b64 v[26:27], v146 offset:53248
	ds_read_b64 v[30:31], v146 offset:57344
	ds_read_b64 v[34:35], v146 offset:61440
	v_sub_f32_e32 v68, v68, v245
	v_sub_f32_e32 v69, v69, v245
	v_sub_f32_e32 v70, v70, v245
	v_sub_f32_e32 v71, v71, v245
	v_exp_f32_e32 v68, v68
	v_exp_f32_e32 v69, v69
	v_exp_f32_e32 v70, v70
	v_exp_f32_e32 v71, v71
	v_add_f32_e32 v149, v149, v64
	v_add_f32_e32 v150, v150, v65
	v_add_f32_e32 v151, v151, v66
	v_add_f32_e32 v152, v152, v67
	v_cvt_pk_bf16_f32 v62, v64, v65
	v_cvt_pk_bf16_f32 v63, v66, v67
	s_waitcnt lgkmcnt(8)
	v_sub_f32_e32 v72, v72, v245
	v_sub_f32_e32 v73, v73, v245
	v_mfma_f32_16x16x32_bf16 v[80:83], v[4:7], v[60:63], v[80:83]
	v_sub_f32_e32 v74, v74, v245
	v_sub_f32_e32 v75, v75, v245
	v_exp_f32_e32 v72, v72
	v_mfma_f32_16x16x32_bf16 v[84:87], v[8:11], v[60:63], v[84:87]
	v_exp_f32_e32 v73, v73
	v_exp_f32_e32 v74, v74
	v_exp_f32_e32 v75, v75
	v_mfma_f32_16x16x32_bf16 v[88:91], v[12:15], v[60:63], v[88:91]
	v_add_f32_e32 v149, v149, v68
	v_add_f32_e32 v150, v150, v69
	v_add_f32_e32 v151, v151, v70
	v_mfma_f32_16x16x32_bf16 v[92:95], v[16:19], v[60:63], v[92:95]
	v_add_f32_e32 v152, v152, v71
	v_cvt_pk_bf16_f32 v68, v68, v69
	v_cvt_pk_bf16_f32 v69, v70, v71
	s_cmp_gt_u32 s6, 8
	s_cselect_b32 s74, 0, 0xffff0000
	v_add_u32_e32 v146, s74, v229
	ds_read_b64 v[4:5], v146 offset:49152
	ds_read_b64 v[8:9], v146 offset:53248
	ds_read_b64 v[12:13], v146 offset:57344
	ds_read_b64 v[16:17], v146 offset:61440
	v_mov_b32_e32 v6, 0
	v_mov_b32_e32 v7, 0
	v_mov_b32_e32 v10, 0
	v_mov_b32_e32 v11, 0
	v_mov_b32_e32 v14, 0
	v_mov_b32_e32 v15, 0
	v_mov_b32_e32 v18, 0
	v_mov_b32_e32 v19, 0
	v_sub_f32_e32 v76, v76, v245
	v_sub_f32_e32 v77, v77, v245
	v_sub_f32_e32 v78, v78, v245
	v_sub_f32_e32 v79, v79, v245
	v_exp_f32_e32 v76, v76
	v_exp_f32_e32 v77, v77
	v_exp_f32_e32 v78, v78
	v_exp_f32_e32 v79, v79
	v_add_f32_e32 v149, v149, v72
	v_add_f32_e32 v150, v150, v73
	v_add_f32_e32 v151, v151, v74
	v_add_f32_e32 v152, v152, v75
	v_cvt_pk_bf16_f32 v70, v72, v73
	v_cvt_pk_bf16_f32 v71, v74, v75
	s_waitcnt lgkmcnt(4)
	v_add_f32_e32 v149, v149, v76
	v_add_f32_e32 v150, v150, v77
	v_mfma_f32_16x16x32_bf16 v[80:83], v[20:23], v[68:71], v[80:83]
	v_add_f32_e32 v151, v151, v78
	v_add_f32_e32 v152, v152, v79
	v_mfma_f32_16x16x32_bf16 v[84:87], v[24:27], v[68:71], v[84:87]
	v_cvt_pk_bf16_f32 v76, v76, v77
	v_cvt_pk_bf16_f32 v77, v78, v79
	v_mfma_f32_16x16x32_bf16 v[88:91], v[28:31], v[68:71], v[88:91]
	v_mov_b32_e32 v78, 0
	v_mov_b32_e32 v79, 0
	v_mfma_f32_16x16x32_bf16 v[92:95], v[32:35], v[68:71], v[92:95]
	v_add_f32_e32 v149, v149, v150
	v_add_f32_e32 v151, v151, v152
	v_add_f32_e32 v246, v149, v151
	ds_bpermute_b32 v148, v239, v246
	s_waitcnt lgkmcnt(1)
	v_mfma_f32_16x16x32_bf16 v[80:83], v[4:7], v[76:79], v[80:83]
	v_mfma_f32_16x16x32_bf16 v[84:87], v[8:11], v[76:79], v[84:87]
	v_mfma_f32_16x16x32_bf16 v[88:91], v[12:15], v[76:79], v[88:91]
	v_mfma_f32_16x16x32_bf16 v[92:95], v[16:19], v[76:79], v[92:95]
	s_waitcnt lgkmcnt(0)
	v_add_f32_e32 v246, v246, v148
	ds_bpermute_b32 v148, v240, v246
	s_waitcnt lgkmcnt(0)
	v_add_f32_e32 v246, v246, v148
	v_rcp_f32_e32 v149, v246
	v_log_f32_e32 v150, v246
	s_nop 0
	v_add_f32_e32 v151, v245, v150
	v_mul_f32_e32 v151, 0x3f317218, v151
	v_mov_b32_e32 v140, v151
	v_mul_f32_e32 v80, v80, v149
	v_mul_f32_e32 v81, v81, v149
	v_mul_f32_e32 v82, v82, v149
	v_mul_f32_e32 v83, v83, v149
	v_mul_f32_e32 v84, v84, v149
	v_mul_f32_e32 v85, v85, v149
	v_mul_f32_e32 v86, v86, v149
	v_mul_f32_e32 v87, v87, v149
	v_mul_f32_e32 v88, v88, v149
	v_mul_f32_e32 v89, v89, v149
	v_mul_f32_e32 v90, v90, v149
	v_mul_f32_e32 v91, v91, v149
	v_mul_f32_e32 v92, v92, v149
	v_mul_f32_e32 v93, v93, v149
	v_mul_f32_e32 v94, v94, v149
	v_mul_f32_e32 v95, v95, v149
	v_cvt_pk_bf16_f32 v132, v80, v81
	v_cvt_pk_bf16_f32 v133, v82, v83
	v_cvt_pk_bf16_f32 v134, v84, v85
	v_cvt_pk_bf16_f32 v135, v86, v87
	v_cvt_pk_bf16_f32 v136, v88, v89
	v_cvt_pk_bf16_f32 v137, v90, v91
	v_cvt_pk_bf16_f32 v138, v92, v93
	v_cvt_pk_bf16_f32 v139, v94, v95
	s_mov_b64 s[26:27], s[86:87]
	s_mov_b64 s[28:29], s[88:89]
	s_mov_b64 s[86:87], s[12:13]
	s_mov_b64 s[88:89], s[14:15]
	s_mov_b32 s4, s83
	s_mov_b32 s5, s84
	s_waitcnt vmcnt(0)
	s_barrier
	ds_read_b128 v[4:7], v230 offset:0
	ds_read_b128 v[8:11], v231 offset:0
	ds_read_b128 v[12:15], v230 offset:2048
	ds_read_b128 v[16:19], v231 offset:2048
	ds_read_b128 v[20:23], v230 offset:4096
	ds_read_b128 v[24:27], v231 offset:4096
	ds_read_b128 v[28:31], v230 offset:6144
	ds_read_b128 v[32:35], v231 offset:6144
	ds_read_b128 v[36:39], v230 offset:8192
	ds_read_b128 v[40:43], v231 offset:8192
	global_store_dwordx2 v237, v[132:133], s[26:27]
	global_store_dwordx2 v237, v[134:135], s[26:27] offset:32
	global_store_dwordx2 v237, v[136:137], s[26:27] offset:64
	global_store_dwordx2 v237, v[138:139], s[26:27] offset:96
	s_mov_b64 s[90:91], exec
	s_mov_b64 exec, 0xffff
	global_store_dword v238, v140, s[28:29]
	s_mov_b64 exec, s[90:91]
	s_add_u32 s83, s4, 1
	s_mov_b32 s84, s5
	s_mul_i32 s74, s84, 4096
	s_lshl_b32 s75, s83, 7
	s_add_u32 s74, s74, s75
	s_lshl_b32 s75, s74, 7
	s_add_u32 s16, s60, s75
	s_addc_u32 s17, s61, 0
	s_lshl_b32 s75, s74, 1
	s_add_u32 s24, s64, s75
	s_addc_u32 s25, s65, 0
	s_add_u32 m0, s70, 0x8000
	s_nop 0
	global_load_lds_dwordx4 v232, s[16:17]
	s_add_u32 m0, s70, 0xa000
	s_nop 0
	global_load_lds_dwordx4 v233, s[16:17]
	s_add_u32 m0, s70, 0x18000
	s_nop 0
	global_load_lds_dwordx4 v234, s[24:25]
	s_add_u32 m0, s70, 0x1a000
	s_nop 0
	global_load_lds_dwordx4 v235, s[24:25]
	s_lshl_b32 s74, s83, 7
	s_add_u32 s74, s74, s84
	s_lshl_b32 s75, s74, 7
	s_add_u32 s10, s30, s75
	s_addc_u32 s11, s31, 0
	s_add_u32 s12, s34, s75
	s_addc_u32 s13, s35, 0
	s_lshl_b32 s75, s74, 2
	s_add_u32 s14, s58, s75
	s_addc_u32 s15, s59, 0
	global_load_dwordx4 v[96:99], v236, s[10:11]
	global_load_dwordx4 v[100:103], v236, s[10:11] offset:64
	s_waitcnt lgkmcnt(0)
	v_mfma_f32_16x16x32_bf16 v[44:47], v[4:7], v[104:107], 0
	v_mfma_f32_16x16x32_bf16 v[48:51], v[12:15], v[104:107], 0
	v_mfma_f32_16x16x32_bf16 v[52:55], v[20:23], v[104:107], 0
	v_mfma_f32_16x16x32_bf16 v[56:59], v[28:31], v[104:107], 0
	v_mfma_f32_16x16x32_bf16 v[60:63], v[36:39], v[104:107], 0
	v_mfma_f32_16x16x32_bf16 v[44:47], v[8:11], v[108:111], v[44:47]
	v_mfma_f32_16x16x32_bf16 v[48:51], v[16:19], v[108:111], v[48:51]
	v_mfma_f32_16x16x32_bf16 v[52:55], v[24:27], v[108:111], v[52:55]
	v_mfma_f32_16x16x32_bf16 v[56:59], v[32:35], v[108:111], v[56:59]
	v_mfma_f32_16x16x32_bf16 v[60:63], v[40:43], v[108:111], v[60:63]
	ds_read_b128 v[4:7], v230 offset:10240
	ds_read_b128 v[8:11], v231 offset:10240
	ds_read_b128 v[12:15], v230 offset:12288
	ds_read_b128 v[16:19], v231 offset:12288
	ds_read_b128 v[20:23], v230 offset:14336
	ds_read_b128 v[24:27], v231 offset:14336
	ds_read_b128 v[28:31], v230 offset:16384
	ds_read_b128 v[32:35], v231 offset:16384
	s_nop 1
	v_fma_f32 v44, v44, s79, v185
	v_fma_f32 v45, v45, s79, v186
	v_fma_f32 v46, v46, s79, v187
	v_fma_f32 v47, v47, s79, v188
	v_fma_f32 v48, v48, s79, v189
	v_fma_f32 v49, v49, s79, v190
	s_waitcnt lgkmcnt(0)
	v_mfma_f32_16x16x32_bf16 v[64:67], v[4:7], v[104:107], 0
	v_fma_f32 v50, v50, s79, v191
	v_fma_f32 v51, v51, s79, v192
	v_mfma_f32_16x16x32_bf16 v[68:71], v[12:15], v[104:107], 0
	v_fma_f32 v52, v52, s79, v193
	v_fma_f32 v53, v53, s79, v194
	v_mfma_f32_16x16x32_bf16 v[72:75], v[20:23], v[104:107], 0
	v_fma_f32 v54, v54, s79, v195
	v_fma_f32 v55, v55, s79, v196
	v_mfma_f32_16x16x32_bf16 v[76:79], v[28:31], v[104:107], 0
	v_fma_f32 v56, v56, s79, v197
	v_fma_f32 v57, v57, s79, v198
	v_mfma_f32_16x16x32_bf16 v[64:67], v[8:11], v[108:111], v[64:67]
	v_fma_f32 v58, v58, s79, v199
	v_fma_f32 v59, v59, s79, v200
	v_mfma_f32_16x16x32_bf16 v[68:71], v[16:19], v[108:111], v[68:71]
	v_fma_f32 v60, v60, s79, v201
	v_fma_f32 v61, v61, s79, v202
	v_mfma_f32_16x16x32_bf16 v[72:75], v[24:27], v[108:111], v[72:75]
	v_fma_f32 v62, v62, s79, v203
	v_fma_f32 v63, v63, s79, v204
	v_mfma_f32_16x16x32_bf16 v[76:79], v[32:35], v[108:111], v[76:79]
	ds_read_b64 v[4:5], v221 offset:0
	ds_read_b64 v[8:9], v221 offset:4096
	ds_read_b64 v[12:13], v221 offset:8192
	ds_read_b64 v[16:17], v221 offset:12288
	ds_read_b64 v[6:7], v222 offset:0
	ds_read_b64 v[10:11], v222 offset:4096
	ds_read_b64 v[14:15], v222 offset:8192
	ds_read_b64 v[18:19], v222 offset:12288
	s_nop 1
	v_fma_f32 v64, v64, s79, v205
	v_fma_f32 v65, v65, s79, v206
	v_fma_f32 v66, v66, s79, v207
	v_fma_f32 v67, v67, s79, v208
	v_fma_f32 v68, v68, s79, v209
	v_fma_f32 v69, v69, s79, v210
	v_fma_f32 v70, v70, s79, v211
	v_fma_f32 v71, v71, s79, v212
	v_fma_f32 v72, v72, s79, v213
	v_fma_f32 v73, v73, s79, v214
	v_fma_f32 v74, v74, s79, v215
	v_fma_f32 v75, v75, s79, v216
	v_fma_f32 v76, v76, s79, v217
	v_fma_f32 v77, v77, s79, v218
	v_fma_f32 v78, v78, s79, v219
	v_fma_f32 v79, v79, s79, v220
	ds_read_b64 v[20:21], v223 offset:0
	ds_read_b64 v[24:25], v223 offset:4096
	ds_read_b64 v[28:29], v223 offset:8192
	ds_read_b64 v[32:33], v223 offset:12288
	ds_read_b64 v[22:23], v224 offset:0
	ds_read_b64 v[26:27], v224 offset:4096
	ds_read_b64 v[30:31], v224 offset:8192
	ds_read_b64 v[34:35], v224 offset:12288
	s_cmp_lg_u32 s4, 0
	s_cbranch_scc1 .Lat738_i1_nomask
	s_cmp_le_u32 s6, 0
	s_cbranch_scc1 .Lat738_i1_nomask
	v_mov_b32_e32 v44, v244
	v_mov_b32_e32 v45, v244
	v_mov_b32_e32 v46, v244
	v_mov_b32_e32 v47, v244
	s_cmp_le_u32 s6, 1
	s_cbranch_scc1 .Lat738_i1_nomask
	v_mov_b32_e32 v48, v244
	v_mov_b32_e32 v49, v244
	v_mov_b32_e32 v50, v244
	v_mov_b32_e32 v51, v244
	s_cmp_le_u32 s6, 2
	s_cbranch_scc1 .Lat738_i1_nomask
	v_mov_b32_e32 v52, v244
	v_mov_b32_e32 v53, v244
	v_mov_b32_e32 v54, v244
	v_mov_b32_e32 v55, v244
	s_cmp_le_u32 s6, 3
	s_cbranch_scc1 .Lat738_i1_nomask
	v_mov_b32_e32 v56, v244
	v_mov_b32_e32 v57, v244
	v_mov_b32_e32 v58, v244
	v_mov_b32_e32 v59, v244
	s_cmp_le_u32 s6, 4
	s_cbranch_scc1 .Lat738_i1_nomask
	v_mov_b32_e32 v60, v244
	v_mov_b32_e32 v61, v244
	v_mov_b32_e32 v62, v244
	v_mov_b32_e32 v63, v244
	s_cmp_le_u32 s6, 5
	s_cbranch_scc1 .Lat738_i1_nomask
	v_mov_b32_e32 v64, v244
	v_mov_b32_e32 v65, v244
	v_mov_b32_e32 v66, v244
	v_mov_b32_e32 v67, v244
	s_cmp_le_u32 s6, 6
	s_cbranch_scc1 .Lat738_i1_nomask
	v_mov_b32_e32 v68, v244
	v_mov_b32_e32 v69, v244
	v_mov_b32_e32 v70, v244
	v_mov_b32_e32 v71, v244
	s_cmp_le_u32 s6, 7
	s_cbranch_scc1 .Lat738_i1_nomask
	v_mov_b32_e32 v72, v244
	v_mov_b32_e32 v73, v244
	v_mov_b32_e32 v74, v244
	v_mov_b32_e32 v75, v244
.Lat738_i1_nomask:
	v_max3_f32 v245, v44, v45, v46
	v_max3_f32 v245, v245, v47, v48
	v_max3_f32 v245, v245, v49, v50
	v_max3_f32 v245, v245, v51, v52
	v_max3_f32 v245, v245, v53, v54
	v_max3_f32 v245, v245, v55, v56
	v_max3_f32 v245, v245, v57, v58
	v_max3_f32 v245, v245, v59, v60
	v_max3_f32 v245, v245, v61, v62
	v_max3_f32 v245, v245, v63, v64
	v_max3_f32 v245, v245, v65, v66
	v_max3_f32 v245, v245, v67, v68
	v_max3_f32 v245, v245, v69, v70
	v_max3_f32 v245, v245, v71, v72
	v_max3_f32 v245, v245, v73, v74
	v_max3_f32 v245, v245, v75, v76
	v_max3_f32 v245, v245, v77, v78
	v_max_f32_e32 v245, v245, v79
	ds_bpermute_b32 v148, v239, v245
	s_waitcnt lgkmcnt(0)
	v_max_f32_e32 v245, v245, v148
	ds_bpermute_b32 v148, v240, v245
	s_waitcnt lgkmcnt(0)
	v_max_f32_e32 v245, v245, v148
	v_sub_f32_e32 v44, v44, v245
	v_sub_f32_e32 v45, v45, v245
	v_sub_f32_e32 v46, v46, v245
	v_sub_f32_e32 v47, v47, v245
	v_exp_f32_e32 v44, v44
	v_exp_f32_e32 v45, v45
	v_exp_f32_e32 v46, v46
	v_exp_f32_e32 v47, v47
	v_sub_f32_e32 v48, v48, v245
	v_sub_f32_e32 v49, v49, v245
	v_sub_f32_e32 v50, v50, v245
	v_sub_f32_e32 v51, v51, v245
	v_exp_f32_e32 v48, v48
	v_exp_f32_e32 v49, v49
	v_exp_f32_e32 v50, v50
	v_exp_f32_e32 v51, v51
	v_mov_b32_e32 v149, v44
	v_mov_b32_e32 v150, v45
	v_mov_b32_e32 v151, v46
	v_mov_b32_e32 v152, v47
	v_cvt_pk_bf16_f32 v44, v44, v45
	v_cvt_pk_bf16_f32 v45, v46, v47
	v_sub_f32_e32 v52, v52, v245
	v_sub_f32_e32 v53, v53, v245
	v_sub_f32_e32 v54, v54, v245
	v_sub_f32_e32 v55, v55, v245
	v_exp_f32_e32 v52, v52
	v_exp_f32_e32 v53, v53
	v_exp_f32_e32 v54, v54
	v_exp_f32_e32 v55, v55
	v_add_f32_e32 v149, v149, v48
	v_add_f32_e32 v150, v150, v49
	v_add_f32_e32 v151, v151, v50
	v_add_f32_e32 v152, v152, v51
	v_cvt_pk_bf16_f32 v46, v48, v49
	v_cvt_pk_bf16_f32 v47, v50, v51
	s_waitcnt lgkmcnt(0)
	v_sub_f32_e32 v56, v56, v245
	v_sub_f32_e32 v57, v57, v245
	v_mfma_f32_16x16x32_bf16 v[80:83], v[4:7], v[44:47], 0
	v_sub_f32_e32 v58, v58, v245
	v_sub_f32_e32 v59, v59, v245
	v_exp_f32_e32 v56, v56
	v_mfma_f32_16x16x32_bf16 v[84:87], v[8:11], v[44:47], 0
	v_exp_f32_e32 v57, v57
	v_exp_f32_e32 v58, v58
	v_exp_f32_e32 v59, v59
	v_mfma_f32_16x16x32_bf16 v[88:91], v[12:15], v[44:47], 0
	v_add_f32_e32 v149, v149, v52
	v_add_f32_e32 v150, v150, v53
	v_add_f32_e32 v151, v151, v54
	v_mfma_f32_16x16x32_bf16 v[92:95], v[16:19], v[44:47], 0
	v_add_f32_e32 v152, v152, v55
	v_cvt_pk_bf16_f32 v52, v52, v53
	v_cvt_pk_bf16_f32 v53, v54, v55
	ds_read_b64 v[4:5], v225 offset:0
	ds_read_b64 v[8:9], v225 offset:4096
	ds_read_b64 v[12:13], v225 offset:8192
	ds_read_b64 v[16:17], v225 offset:12288
	ds_read_b64 v[6:7], v226 offset:0
	ds_read_b64 v[10:11], v226 offset:4096
	ds_read_b64 v[14:15], v226 offset:8192
	ds_read_b64 v[18:19], v226 offset:12288
	v_sub_f32_e32 v60, v60, v245
	v_sub_f32_e32 v61, v61, v245
	v_sub_f32_e32 v62, v62, v245
	v_sub_f32_e32 v63, v63, v245
	v_exp_f32_e32 v60, v60
	v_exp_f32_e32 v61, v61
	v_exp_f32_e32 v62, v62
	v_exp_f32_e32 v63, v63
	v_add_f32_e32 v149, v149, v56
	v_add_f32_e32 v150, v150, v57
	v_add_f32_e32 v151, v151, v58
	v_add_f32_e32 v152, v152, v59
	v_cvt_pk_bf16_f32 v54, v56, v57
	v_cvt_pk_bf16_f32 v55, v58, v59
	v_sub_f32_e32 v64, v64, v245
	v_sub_f32_e32 v65, v65, v245
	v_mfma_f32_16x16x32_bf16 v[80:83], v[20:23], v[52:55], v[80:83]
	v_sub_f32_e32 v66, v66, v245
	v_sub_f32_e32 v67, v67, v245
	v_exp_f32_e32 v64, v64
	v_mfma_f32_16x16x32_bf16 v[84:87], v[24:27], v[52:55], v[84:87]
	v_exp_f32_e32 v65, v65
	v_exp_f32_e32 v66, v66
	v_exp_f32_e32 v67, v67
	v_mfma_f32_16x16x32_bf16 v[88:91], v[28:31], v[52:55], v[88:91]
	v_add_f32_e32 v149, v149, v60
	v_add_f32_e32 v150, v150, v61
	v_add_f32_e32 v151, v151, v62
	v_mfma_f32_16x16x32_bf16 v[92:95], v[32:35], v[52:55], v[92:95]
	v_add_f32_e32 v152, v152, v63
	v_cvt_pk_bf16_f32 v60, v60, v61
	v_cvt_pk_bf16_f32 v61, v62, v63
	ds_read_b64 v[20:21], v227 offset:0
	ds_read_b64 v[24:25], v227 offset:4096
	ds_read_b64 v[28:29], v227 offset:8192
	ds_read_b64 v[32:33], v227 offset:12288
	ds_read_b64 v[22:23], v228 offset:0
	ds_read_b64 v[26:27], v228 offset:4096
	ds_read_b64 v[30:31], v228 offset:8192
	ds_read_b64 v[34:35], v228 offset:12288
	v_sub_f32_e32 v68, v68, v245
	v_sub_f32_e32 v69, v69, v245
	v_sub_f32_e32 v70, v70, v245
	v_sub_f32_e32 v71, v71, v245
	v_exp_f32_e32 v68, v68
	v_exp_f32_e32 v69, v69
	v_exp_f32_e32 v70, v70
	v_exp_f32_e32 v71, v71
	v_add_f32_e32 v149, v149, v64
	v_add_f32_e32 v150, v150, v65
	v_add_f32_e32 v151, v151, v66
	v_add_f32_e32 v152, v152, v67
	v_cvt_pk_bf16_f32 v62, v64, v65
	v_cvt_pk_bf16_f32 v63, v66, v67
	s_waitcnt lgkmcnt(8)
	v_sub_f32_e32 v72, v72, v245
	v_sub_f32_e32 v73, v73, v245
	v_mfma_f32_16x16x32_bf16 v[80:83], v[4:7], v[60:63], v[80:83]
	v_sub_f32_e32 v74, v74, v245
	v_sub_f32_e32 v75, v75, v245
	v_exp_f32_e32 v72, v72
	v_mfma_f32_16x16x32_bf16 v[84:87], v[8:11], v[60:63], v[84:87]
	v_exp_f32_e32 v73, v73
	v_exp_f32_e32 v74, v74
	v_exp_f32_e32 v75, v75
	v_mfma_f32_16x16x32_bf16 v[88:91], v[12:15], v[60:63], v[88:91]
	v_add_f32_e32 v149, v149, v68
	v_add_f32_e32 v150, v150, v69
	v_add_f32_e32 v151, v151, v70
	v_mfma_f32_16x16x32_bf16 v[92:95], v[16:19], v[60:63], v[92:95]
	v_add_f32_e32 v152, v152, v71
	v_cvt_pk_bf16_f32 v68, v68, v69
	v_cvt_pk_bf16_f32 v69, v70, v71
	ds_read_b64 v[4:5], v229 offset:0
	ds_read_b64 v[8:9], v229 offset:4096
	ds_read_b64 v[12:13], v229 offset:8192
	ds_read_b64 v[16:17], v229 offset:12288
	v_mov_b32_e32 v6, 0
	v_mov_b32_e32 v7, 0
	v_mov_b32_e32 v10, 0
	v_mov_b32_e32 v11, 0
	v_mov_b32_e32 v14, 0
	v_mov_b32_e32 v15, 0
	v_mov_b32_e32 v18, 0
	v_mov_b32_e32 v19, 0
	v_sub_f32_e32 v76, v76, v245
	v_sub_f32_e32 v77, v77, v245
	v_sub_f32_e32 v78, v78, v245
	v_sub_f32_e32 v79, v79, v245
	v_exp_f32_e32 v76, v76
	v_exp_f32_e32 v77, v77
	v_exp_f32_e32 v78, v78
	v_exp_f32_e32 v79, v79
	v_add_f32_e32 v149, v149, v72
	v_add_f32_e32 v150, v150, v73
	v_add_f32_e32 v151, v151, v74
	v_add_f32_e32 v152, v152, v75
	v_cvt_pk_bf16_f32 v70, v72, v73
	v_cvt_pk_bf16_f32 v71, v74, v75
	s_waitcnt lgkmcnt(4)
	v_add_f32_e32 v149, v149, v76
	v_add_f32_e32 v150, v150, v77
	v_mfma_f32_16x16x32_bf16 v[80:83], v[20:23], v[68:71], v[80:83]
	v_add_f32_e32 v151, v151, v78
	v_add_f32_e32 v152, v152, v79
	v_mfma_f32_16x16x32_bf16 v[84:87], v[24:27], v[68:71], v[84:87]
	v_cvt_pk_bf16_f32 v76, v76, v77
	v_cvt_pk_bf16_f32 v77, v78, v79
	v_mfma_f32_16x16x32_bf16 v[88:91], v[28:31], v[68:71], v[88:91]
	v_mov_b32_e32 v78, 0
	v_mov_b32_e32 v79, 0
	v_mfma_f32_16x16x32_bf16 v[92:95], v[32:35], v[68:71], v[92:95]
	v_add_f32_e32 v149, v149, v150
	v_add_f32_e32 v151, v151, v152
	v_add_f32_e32 v246, v149, v151
	ds_bpermute_b32 v148, v239, v246
	s_waitcnt lgkmcnt(1)
	v_mfma_f32_16x16x32_bf16 v[80:83], v[4:7], v[76:79], v[80:83]
	v_mfma_f32_16x16x32_bf16 v[84:87], v[8:11], v[76:79], v[84:87]
	v_mfma_f32_16x16x32_bf16 v[88:91], v[12:15], v[76:79], v[88:91]
	v_mfma_f32_16x16x32_bf16 v[92:95], v[16:19], v[76:79], v[92:95]
	s_waitcnt lgkmcnt(0)
	v_add_f32_e32 v246, v246, v148
	ds_bpermute_b32 v148, v240, v246
	s_waitcnt lgkmcnt(0)
	v_add_f32_e32 v246, v246, v148
	v_rcp_f32_e32 v149, v246
	v_log_f32_e32 v150, v246
	s_nop 0
	v_add_f32_e32 v151, v245, v150
	v_mul_f32_e32 v151, 0x3f317218, v151
	v_mov_b32_e32 v140, v151
	v_mul_f32_e32 v80, v80, v149
	v_mul_f32_e32 v81, v81, v149
	v_mul_f32_e32 v82, v82, v149
	v_mul_f32_e32 v83, v83, v149
	v_mul_f32_e32 v84, v84, v149
	v_mul_f32_e32 v85, v85, v149
	v_mul_f32_e32 v86, v86, v149
	v_mul_f32_e32 v87, v87, v149
	v_mul_f32_e32 v88, v88, v149
	v_mul_f32_e32 v89, v89, v149
	v_mul_f32_e32 v90, v90, v149
	v_mul_f32_e32 v91, v91, v149
	v_mul_f32_e32 v92, v92, v149
	v_mul_f32_e32 v93, v93, v149
	v_mul_f32_e32 v94, v94, v149
	v_mul_f32_e32 v95, v95, v149
	v_cvt_pk_bf16_f32 v132, v80, v81
	v_cvt_pk_bf16_f32 v133, v82, v83
	v_cvt_pk_bf16_f32 v134, v84, v85
	v_cvt_pk_bf16_f32 v135, v86, v87
	v_cvt_pk_bf16_f32 v136, v88, v89
	v_cvt_pk_bf16_f32 v137, v90, v91
	v_cvt_pk_bf16_f32 v138, v92, v93
	v_cvt_pk_bf16_f32 v139, v94, v95
	s_mov_b64 s[26:27], s[86:87]
	s_mov_b64 s[28:29], s[88:89]
	s_mov_b64 s[86:87], s[12:13]
	s_mov_b64 s[88:89], s[14:15]
	s_mov_b32 s4, s83
	s_mov_b32 s5, s84
	s_waitcnt vmcnt(0)
	s_barrier
	ds_read_b128 v[4:7], v230 offset:16384
	ds_read_b128 v[8:11], v231 offset:16384
	ds_read_b128 v[12:15], v230 offset:18432
	ds_read_b128 v[16:19], v231 offset:18432
	ds_read_b128 v[20:23], v230 offset:20480
	ds_read_b128 v[24:27], v231 offset:20480
	ds_read_b128 v[28:31], v230 offset:22528
	ds_read_b128 v[32:35], v231 offset:22528
	ds_read_b128 v[36:39], v230 offset:24576
	ds_read_b128 v[40:43], v231 offset:24576
	global_store_dwordx2 v237, v[132:133], s[26:27]
	global_store_dwordx2 v237, v[134:135], s[26:27] offset:32
	global_store_dwordx2 v237, v[136:137], s[26:27] offset:64
	global_store_dwordx2 v237, v[138:139], s[26:27] offset:96
	s_mov_b64 s[90:91], exec
	s_mov_b64 exec, 0xffff
	global_store_dword v238, v140, s[28:29]
	s_mov_b64 exec, s[90:91]
	s_add_u32 s83, s4, 1
	s_mov_b32 s84, s5
	s_mul_i32 s74, s84, 4096
	s_lshl_b32 s75, s83, 7
	s_add_u32 s74, s74, s75
	s_lshl_b32 s75, s74, 7
	s_add_u32 s16, s60, s75
	s_addc_u32 s17, s61, 0
	s_lshl_b32 s75, s74, 1
	s_add_u32 s24, s64, s75
	s_addc_u32 s25, s65, 0
	s_add_u32 m0, s70, 0xc000
	s_nop 0
	global_load_lds_dwordx4 v232, s[16:17]
	s_add_u32 m0, s70, 0xe000
	s_nop 0
	global_load_lds_dwordx4 v233, s[16:17]
	s_add_u32 m0, s70, 0x1c000
	s_nop 0
	global_load_lds_dwordx4 v234, s[24:25]
	s_add_u32 m0, s70, 0x1e000
	s_nop 0
	global_load_lds_dwordx4 v235, s[24:25]
	s_lshl_b32 s74, s83, 7
	s_add_u32 s74, s74, s84
	s_lshl_b32 s75, s74, 7
	s_add_u32 s10, s30, s75
	s_addc_u32 s11, s31, 0
	s_add_u32 s12, s34, s75
	s_addc_u32 s13, s35, 0
	s_lshl_b32 s75, s74, 2
	s_add_u32 s14, s58, s75
	s_addc_u32 s15, s59, 0
	global_load_dwordx4 v[104:107], v236, s[10:11]
	global_load_dwordx4 v[108:111], v236, s[10:11] offset:64
	s_waitcnt lgkmcnt(0)
	v_mfma_f32_16x16x32_bf16 v[44:47], v[4:7], v[96:99], 0
	v_mfma_f32_16x16x32_bf16 v[48:51], v[12:15], v[96:99], 0
	v_mfma_f32_16x16x32_bf16 v[52:55], v[20:23], v[96:99], 0
	v_mfma_f32_16x16x32_bf16 v[56:59], v[28:31], v[96:99], 0
	v_mfma_f32_16x16x32_bf16 v[60:63], v[36:39], v[96:99], 0
	v_mfma_f32_16x16x32_bf16 v[44:47], v[8:11], v[100:103], v[44:47]
	v_mfma_f32_16x16x32_bf16 v[48:51], v[16:19], v[100:103], v[48:51]
	v_mfma_f32_16x16x32_bf16 v[52:55], v[24:27], v[100:103], v[52:55]
	v_mfma_f32_16x16x32_bf16 v[56:59], v[32:35], v[100:103], v[56:59]
	v_mfma_f32_16x16x32_bf16 v[60:63], v[40:43], v[100:103], v[60:63]
	ds_read_b128 v[4:7], v230 offset:26624
	ds_read_b128 v[8:11], v231 offset:26624
	ds_read_b128 v[12:15], v230 offset:28672
	ds_read_b128 v[16:19], v231 offset:28672
	ds_read_b128 v[20:23], v230 offset:30720
	ds_read_b128 v[24:27], v231 offset:30720
	ds_read_b128 v[28:31], v230 offset:32768
	ds_read_b128 v[32:35], v231 offset:32768
	s_nop 1
	v_fma_f32 v44, v44, s79, v185
	v_fma_f32 v45, v45, s79, v186
	v_fma_f32 v46, v46, s79, v187
	v_fma_f32 v47, v47, s79, v188
	v_fma_f32 v48, v48, s79, v189
	v_fma_f32 v49, v49, s79, v190
	s_waitcnt lgkmcnt(0)
	v_mfma_f32_16x16x32_bf16 v[64:67], v[4:7], v[96:99], 0
	v_fma_f32 v50, v50, s79, v191
	v_fma_f32 v51, v51, s79, v192
	v_mfma_f32_16x16x32_bf16 v[68:71], v[12:15], v[96:99], 0
	v_fma_f32 v52, v52, s79, v193
	v_fma_f32 v53, v53, s79, v194
	v_mfma_f32_16x16x32_bf16 v[72:75], v[20:23], v[96:99], 0
	v_fma_f32 v54, v54, s79, v195
	v_fma_f32 v55, v55, s79, v196
	v_mfma_f32_16x16x32_bf16 v[76:79], v[28:31], v[96:99], 0
	v_fma_f32 v56, v56, s79, v197
	v_fma_f32 v57, v57, s79, v198
	v_mfma_f32_16x16x32_bf16 v[64:67], v[8:11], v[100:103], v[64:67]
	v_fma_f32 v58, v58, s79, v199
	v_fma_f32 v59, v59, s79, v200
	v_mfma_f32_16x16x32_bf16 v[68:71], v[16:19], v[100:103], v[68:71]
	v_fma_f32 v60, v60, s79, v201
	v_fma_f32 v61, v61, s79, v202
	v_mfma_f32_16x16x32_bf16 v[72:75], v[24:27], v[100:103], v[72:75]
	v_fma_f32 v62, v62, s79, v203
	v_fma_f32 v63, v63, s79, v204
	v_mfma_f32_16x16x32_bf16 v[76:79], v[32:35], v[100:103], v[76:79]
	ds_read_b64 v[4:5], v221 offset:16384
	ds_read_b64 v[8:9], v221 offset:20480
	ds_read_b64 v[12:13], v221 offset:24576
	ds_read_b64 v[16:17], v221 offset:28672
	ds_read_b64 v[6:7], v222 offset:16384
	ds_read_b64 v[10:11], v222 offset:20480
	ds_read_b64 v[14:15], v222 offset:24576
	ds_read_b64 v[18:19], v222 offset:28672
	s_nop 1
	v_fma_f32 v64, v64, s79, v205
	v_fma_f32 v65, v65, s79, v206
	v_fma_f32 v66, v66, s79, v207
	v_fma_f32 v67, v67, s79, v208
	v_fma_f32 v68, v68, s79, v209
	v_fma_f32 v69, v69, s79, v210
	v_fma_f32 v70, v70, s79, v211
	v_fma_f32 v71, v71, s79, v212
	v_fma_f32 v72, v72, s79, v213
	v_fma_f32 v73, v73, s79, v214
	v_fma_f32 v74, v74, s79, v215
	v_fma_f32 v75, v75, s79, v216
	v_fma_f32 v76, v76, s79, v217
	v_fma_f32 v77, v77, s79, v218
	v_fma_f32 v78, v78, s79, v219
	v_fma_f32 v79, v79, s79, v220
	ds_read_b64 v[20:21], v223 offset:16384
	ds_read_b64 v[24:25], v223 offset:20480
	ds_read_b64 v[28:29], v223 offset:24576
	ds_read_b64 v[32:33], v223 offset:28672
	ds_read_b64 v[22:23], v224 offset:16384
	ds_read_b64 v[26:27], v224 offset:20480
	ds_read_b64 v[30:31], v224 offset:24576
	ds_read_b64 v[34:35], v224 offset:28672
	s_cmp_lg_u32 s4, 0
	s_cbranch_scc1 .Lat738_i2_nomask
	s_cmp_le_u32 s6, 0
	s_cbranch_scc1 .Lat738_i2_nomask
	v_mov_b32_e32 v44, v244
	v_mov_b32_e32 v45, v244
	v_mov_b32_e32 v46, v244
	v_mov_b32_e32 v47, v244
	s_cmp_le_u32 s6, 1
	s_cbranch_scc1 .Lat738_i2_nomask
	v_mov_b32_e32 v48, v244
	v_mov_b32_e32 v49, v244
	v_mov_b32_e32 v50, v244
	v_mov_b32_e32 v51, v244
	s_cmp_le_u32 s6, 2
	s_cbranch_scc1 .Lat738_i2_nomask
	v_mov_b32_e32 v52, v244
	v_mov_b32_e32 v53, v244
	v_mov_b32_e32 v54, v244
	v_mov_b32_e32 v55, v244
	s_cmp_le_u32 s6, 3
	s_cbranch_scc1 .Lat738_i2_nomask
	v_mov_b32_e32 v56, v244
	v_mov_b32_e32 v57, v244
	v_mov_b32_e32 v58, v244
	v_mov_b32_e32 v59, v244
	s_cmp_le_u32 s6, 4
	s_cbranch_scc1 .Lat738_i2_nomask
	v_mov_b32_e32 v60, v244
	v_mov_b32_e32 v61, v244
	v_mov_b32_e32 v62, v244
	v_mov_b32_e32 v63, v244
	s_cmp_le_u32 s6, 5
	s_cbranch_scc1 .Lat738_i2_nomask
	v_mov_b32_e32 v64, v244
	v_mov_b32_e32 v65, v244
	v_mov_b32_e32 v66, v244
	v_mov_b32_e32 v67, v244
	s_cmp_le_u32 s6, 6
	s_cbranch_scc1 .Lat738_i2_nomask
	v_mov_b32_e32 v68, v244
	v_mov_b32_e32 v69, v244
	v_mov_b32_e32 v70, v244
	v_mov_b32_e32 v71, v244
	s_cmp_le_u32 s6, 7
	s_cbranch_scc1 .Lat738_i2_nomask
	v_mov_b32_e32 v72, v244
	v_mov_b32_e32 v73, v244
	v_mov_b32_e32 v74, v244
	v_mov_b32_e32 v75, v244
.Lat738_i2_nomask:
	v_max3_f32 v245, v44, v45, v46
	v_max3_f32 v245, v245, v47, v48
	v_max3_f32 v245, v245, v49, v50
	v_max3_f32 v245, v245, v51, v52
	v_max3_f32 v245, v245, v53, v54
	v_max3_f32 v245, v245, v55, v56
	v_max3_f32 v245, v245, v57, v58
	v_max3_f32 v245, v245, v59, v60
	v_max3_f32 v245, v245, v61, v62
	v_max3_f32 v245, v245, v63, v64
	v_max3_f32 v245, v245, v65, v66
	v_max3_f32 v245, v245, v67, v68
	v_max3_f32 v245, v245, v69, v70
	v_max3_f32 v245, v245, v71, v72
	v_max3_f32 v245, v245, v73, v74
	v_max3_f32 v245, v245, v75, v76
	v_max3_f32 v245, v245, v77, v78
	v_max_f32_e32 v245, v245, v79
	ds_bpermute_b32 v148, v239, v245
	s_waitcnt lgkmcnt(0)
	v_max_f32_e32 v245, v245, v148
	ds_bpermute_b32 v148, v240, v245
	s_waitcnt lgkmcnt(0)
	v_max_f32_e32 v245, v245, v148
	v_sub_f32_e32 v44, v44, v245
	v_sub_f32_e32 v45, v45, v245
	v_sub_f32_e32 v46, v46, v245
	v_sub_f32_e32 v47, v47, v245
	v_exp_f32_e32 v44, v44
	v_exp_f32_e32 v45, v45
	v_exp_f32_e32 v46, v46
	v_exp_f32_e32 v47, v47
	v_sub_f32_e32 v48, v48, v245
	v_sub_f32_e32 v49, v49, v245
	v_sub_f32_e32 v50, v50, v245
	v_sub_f32_e32 v51, v51, v245
	v_exp_f32_e32 v48, v48
	v_exp_f32_e32 v49, v49
	v_exp_f32_e32 v50, v50
	v_exp_f32_e32 v51, v51
	v_mov_b32_e32 v149, v44
	v_mov_b32_e32 v150, v45
	v_mov_b32_e32 v151, v46
	v_mov_b32_e32 v152, v47
	v_cvt_pk_bf16_f32 v44, v44, v45
	v_cvt_pk_bf16_f32 v45, v46, v47
	v_sub_f32_e32 v52, v52, v245
	v_sub_f32_e32 v53, v53, v245
	v_sub_f32_e32 v54, v54, v245
	v_sub_f32_e32 v55, v55, v245
	v_exp_f32_e32 v52, v52
	v_exp_f32_e32 v53, v53
	v_exp_f32_e32 v54, v54
	v_exp_f32_e32 v55, v55
	v_add_f32_e32 v149, v149, v48
	v_add_f32_e32 v150, v150, v49
	v_add_f32_e32 v151, v151, v50
	v_add_f32_e32 v152, v152, v51
	v_cvt_pk_bf16_f32 v46, v48, v49
	v_cvt_pk_bf16_f32 v47, v50, v51
	s_waitcnt lgkmcnt(0)
	v_sub_f32_e32 v56, v56, v245
	v_sub_f32_e32 v57, v57, v245
	v_mfma_f32_16x16x32_bf16 v[80:83], v[4:7], v[44:47], 0
	v_sub_f32_e32 v58, v58, v245
	v_sub_f32_e32 v59, v59, v245
	v_exp_f32_e32 v56, v56
	v_mfma_f32_16x16x32_bf16 v[84:87], v[8:11], v[44:47], 0
	v_exp_f32_e32 v57, v57
	v_exp_f32_e32 v58, v58
	v_exp_f32_e32 v59, v59
	v_mfma_f32_16x16x32_bf16 v[88:91], v[12:15], v[44:47], 0
	v_add_f32_e32 v149, v149, v52
	v_add_f32_e32 v150, v150, v53
	v_add_f32_e32 v151, v151, v54
	v_mfma_f32_16x16x32_bf16 v[92:95], v[16:19], v[44:47], 0
	v_add_f32_e32 v152, v152, v55
	v_cvt_pk_bf16_f32 v52, v52, v53
	v_cvt_pk_bf16_f32 v53, v54, v55
	ds_read_b64 v[4:5], v225 offset:16384
	ds_read_b64 v[8:9], v225 offset:20480
	ds_read_b64 v[12:13], v225 offset:24576
	ds_read_b64 v[16:17], v225 offset:28672
	ds_read_b64 v[6:7], v226 offset:16384
	ds_read_b64 v[10:11], v226 offset:20480
	ds_read_b64 v[14:15], v226 offset:24576
	ds_read_b64 v[18:19], v226 offset:28672
	v_sub_f32_e32 v60, v60, v245
	v_sub_f32_e32 v61, v61, v245
	v_sub_f32_e32 v62, v62, v245
	v_sub_f32_e32 v63, v63, v245
	v_exp_f32_e32 v60, v60
	v_exp_f32_e32 v61, v61
	v_exp_f32_e32 v62, v62
	v_exp_f32_e32 v63, v63
	v_add_f32_e32 v149, v149, v56
	v_add_f32_e32 v150, v150, v57
	v_add_f32_e32 v151, v151, v58
	v_add_f32_e32 v152, v152, v59
	v_cvt_pk_bf16_f32 v54, v56, v57
	v_cvt_pk_bf16_f32 v55, v58, v59
	v_sub_f32_e32 v64, v64, v245
	v_sub_f32_e32 v65, v65, v245
	v_mfma_f32_16x16x32_bf16 v[80:83], v[20:23], v[52:55], v[80:83]
	v_sub_f32_e32 v66, v66, v245
	v_sub_f32_e32 v67, v67, v245
	v_exp_f32_e32 v64, v64
	v_mfma_f32_16x16x32_bf16 v[84:87], v[24:27], v[52:55], v[84:87]
	v_exp_f32_e32 v65, v65
	v_exp_f32_e32 v66, v66
	v_exp_f32_e32 v67, v67
	v_mfma_f32_16x16x32_bf16 v[88:91], v[28:31], v[52:55], v[88:91]
	v_add_f32_e32 v149, v149, v60
	v_add_f32_e32 v150, v150, v61
	v_add_f32_e32 v151, v151, v62
	v_mfma_f32_16x16x32_bf16 v[92:95], v[32:35], v[52:55], v[92:95]
	v_add_f32_e32 v152, v152, v63
	v_cvt_pk_bf16_f32 v60, v60, v61
	v_cvt_pk_bf16_f32 v61, v62, v63
	ds_read_b64 v[20:21], v227 offset:16384
	ds_read_b64 v[24:25], v227 offset:20480
	ds_read_b64 v[28:29], v227 offset:24576
	ds_read_b64 v[32:33], v227 offset:28672
	ds_read_b64 v[22:23], v228 offset:16384
	ds_read_b64 v[26:27], v228 offset:20480
	ds_read_b64 v[30:31], v228 offset:24576
	ds_read_b64 v[34:35], v228 offset:28672
	v_sub_f32_e32 v68, v68, v245
	v_sub_f32_e32 v69, v69, v245
	v_sub_f32_e32 v70, v70, v245
	v_sub_f32_e32 v71, v71, v245
	v_exp_f32_e32 v68, v68
	v_exp_f32_e32 v69, v69
	v_exp_f32_e32 v70, v70
	v_exp_f32_e32 v71, v71
	v_add_f32_e32 v149, v149, v64
	v_add_f32_e32 v150, v150, v65
	v_add_f32_e32 v151, v151, v66
	v_add_f32_e32 v152, v152, v67
	v_cvt_pk_bf16_f32 v62, v64, v65
	v_cvt_pk_bf16_f32 v63, v66, v67
	s_waitcnt lgkmcnt(8)
	v_sub_f32_e32 v72, v72, v245
	v_sub_f32_e32 v73, v73, v245
	v_mfma_f32_16x16x32_bf16 v[80:83], v[4:7], v[60:63], v[80:83]
	v_sub_f32_e32 v74, v74, v245
	v_sub_f32_e32 v75, v75, v245
	v_exp_f32_e32 v72, v72
	v_mfma_f32_16x16x32_bf16 v[84:87], v[8:11], v[60:63], v[84:87]
	v_exp_f32_e32 v73, v73
	v_exp_f32_e32 v74, v74
	v_exp_f32_e32 v75, v75
	v_mfma_f32_16x16x32_bf16 v[88:91], v[12:15], v[60:63], v[88:91]
	v_add_f32_e32 v149, v149, v68
	v_add_f32_e32 v150, v150, v69
	v_add_f32_e32 v151, v151, v70
	v_mfma_f32_16x16x32_bf16 v[92:95], v[16:19], v[60:63], v[92:95]
	v_add_f32_e32 v152, v152, v71
	v_cvt_pk_bf16_f32 v68, v68, v69
	v_cvt_pk_bf16_f32 v69, v70, v71
	ds_read_b64 v[4:5], v229 offset:16384
	ds_read_b64 v[8:9], v229 offset:20480
	ds_read_b64 v[12:13], v229 offset:24576
	ds_read_b64 v[16:17], v229 offset:28672
	v_mov_b32_e32 v6, 0
	v_mov_b32_e32 v7, 0
	v_mov_b32_e32 v10, 0
	v_mov_b32_e32 v11, 0
	v_mov_b32_e32 v14, 0
	v_mov_b32_e32 v15, 0
	v_mov_b32_e32 v18, 0
	v_mov_b32_e32 v19, 0
	v_sub_f32_e32 v76, v76, v245
	v_sub_f32_e32 v77, v77, v245
	v_sub_f32_e32 v78, v78, v245
	v_sub_f32_e32 v79, v79, v245
	v_exp_f32_e32 v76, v76
	v_exp_f32_e32 v77, v77
	v_exp_f32_e32 v78, v78
	v_exp_f32_e32 v79, v79
	v_add_f32_e32 v149, v149, v72
	v_add_f32_e32 v150, v150, v73
	v_add_f32_e32 v151, v151, v74
	v_add_f32_e32 v152, v152, v75
	v_cvt_pk_bf16_f32 v70, v72, v73
	v_cvt_pk_bf16_f32 v71, v74, v75
	s_waitcnt lgkmcnt(4)
	v_add_f32_e32 v149, v149, v76
	v_add_f32_e32 v150, v150, v77
	v_mfma_f32_16x16x32_bf16 v[80:83], v[20:23], v[68:71], v[80:83]
	v_add_f32_e32 v151, v151, v78
	v_add_f32_e32 v152, v152, v79
	v_mfma_f32_16x16x32_bf16 v[84:87], v[24:27], v[68:71], v[84:87]
	v_cvt_pk_bf16_f32 v76, v76, v77
	v_cvt_pk_bf16_f32 v77, v78, v79
	v_mfma_f32_16x16x32_bf16 v[88:91], v[28:31], v[68:71], v[88:91]
	v_mov_b32_e32 v78, 0
	v_mov_b32_e32 v79, 0
	v_mfma_f32_16x16x32_bf16 v[92:95], v[32:35], v[68:71], v[92:95]
	v_add_f32_e32 v149, v149, v150
	v_add_f32_e32 v151, v151, v152
	v_add_f32_e32 v246, v149, v151
	ds_bpermute_b32 v148, v239, v246
	s_waitcnt lgkmcnt(1)
	v_mfma_f32_16x16x32_bf16 v[80:83], v[4:7], v[76:79], v[80:83]
	v_mfma_f32_16x16x32_bf16 v[84:87], v[8:11], v[76:79], v[84:87]
	v_mfma_f32_16x16x32_bf16 v[88:91], v[12:15], v[76:79], v[88:91]
	v_mfma_f32_16x16x32_bf16 v[92:95], v[16:19], v[76:79], v[92:95]
	s_waitcnt lgkmcnt(0)
	v_add_f32_e32 v246, v246, v148
	ds_bpermute_b32 v148, v240, v246
	s_waitcnt lgkmcnt(0)
	v_add_f32_e32 v246, v246, v148
	v_rcp_f32_e32 v149, v246
	v_log_f32_e32 v150, v246
	s_nop 0
	v_add_f32_e32 v151, v245, v150
	v_mul_f32_e32 v151, 0x3f317218, v151
	v_mov_b32_e32 v140, v151
	v_mul_f32_e32 v80, v80, v149
	v_mul_f32_e32 v81, v81, v149
	v_mul_f32_e32 v82, v82, v149
	v_mul_f32_e32 v83, v83, v149
	v_mul_f32_e32 v84, v84, v149
	v_mul_f32_e32 v85, v85, v149
	v_mul_f32_e32 v86, v86, v149
	v_mul_f32_e32 v87, v87, v149
	v_mul_f32_e32 v88, v88, v149
	v_mul_f32_e32 v89, v89, v149
	v_mul_f32_e32 v90, v90, v149
	v_mul_f32_e32 v91, v91, v149
	v_mul_f32_e32 v92, v92, v149
	v_mul_f32_e32 v93, v93, v149
	v_mul_f32_e32 v94, v94, v149
	v_mul_f32_e32 v95, v95, v149
	v_cvt_pk_bf16_f32 v132, v80, v81
	v_cvt_pk_bf16_f32 v133, v82, v83
	v_cvt_pk_bf16_f32 v134, v84, v85
	v_cvt_pk_bf16_f32 v135, v86, v87
	v_cvt_pk_bf16_f32 v136, v88, v89
	v_cvt_pk_bf16_f32 v137, v90, v91
	v_cvt_pk_bf16_f32 v138, v92, v93
	v_cvt_pk_bf16_f32 v139, v94, v95
	s_mov_b64 s[26:27], s[86:87]
	s_mov_b64 s[28:29], s[88:89]
	s_mov_b64 s[86:87], s[12:13]
	s_mov_b64 s[88:89], s[14:15]
	s_mov_b32 s4, s83
	s_mov_b32 s5, s84
	s_waitcnt vmcnt(0)
	s_barrier
	ds_read_b128 v[4:7], v230 offset:32768
	ds_read_b128 v[8:11], v231 offset:32768
	ds_read_b128 v[12:15], v230 offset:34816
	ds_read_b128 v[16:19], v231 offset:34816
	ds_read_b128 v[20:23], v230 offset:36864
	ds_read_b128 v[24:27], v231 offset:36864
	ds_read_b128 v[28:31], v230 offset:38912
	ds_read_b128 v[32:35], v231 offset:38912
	ds_read_b128 v[36:39], v230 offset:40960
	ds_read_b128 v[40:43], v231 offset:40960
	global_store_dwordx2 v237, v[132:133], s[26:27]
	global_store_dwordx2 v237, v[134:135], s[26:27] offset:32
	global_store_dwordx2 v237, v[136:137], s[26:27] offset:64
	global_store_dwordx2 v237, v[138:139], s[26:27] offset:96
	s_mov_b64 s[90:91], exec
	s_mov_b64 exec, 0xffff
	global_store_dword v238, v140, s[28:29]
	s_mov_b64 exec, s[90:91]
	s_cmp_eq_u32 s7, 1
	s_cbranch_scc1 .Lat738_i3_nonext
	s_add_u32 s83, s4, 1
	s_mov_b32 s84, s5
	s_mul_i32 s74, s84, 4096
	s_lshl_b32 s75, s83, 7
	s_add_u32 s74, s74, s75
	s_lshl_b32 s75, s74, 7
	s_add_u32 s16, s60, s75
	s_addc_u32 s17, s61, 0
	s_lshl_b32 s75, s74, 1
	s_add_u32 s24, s64, s75
	s_addc_u32 s25, s65, 0
	s_add_u32 m0, s70, 0x0
	s_nop 0
	global_load_lds_dwordx4 v232, s[16:17]
	s_add_u32 m0, s70, 0x2000
	s_nop 0
	global_load_lds_dwordx4 v233, s[16:17]
	s_add_u32 m0, s70, 0x10000
	s_nop 0
	global_load_lds_dwordx4 v234, s[24:25]
	s_add_u32 m0, s70, 0x12000
	s_nop 0
	global_load_lds_dwordx4 v235, s[24:25]
	s_lshl_b32 s74, s83, 7
	s_add_u32 s74, s74, s84
	s_lshl_b32 s75, s74, 7
	s_add_u32 s10, s30, s75
	s_addc_u32 s11, s31, 0
	s_add_u32 s12, s34, s75
	s_addc_u32 s13, s35, 0
	s_lshl_b32 s75, s74, 2
	s_add_u32 s14, s58, s75
	s_addc_u32 s15, s59, 0
	global_load_dwordx4 v[96:99], v236, s[10:11]
	global_load_dwordx4 v[100:103], v236, s[10:11] offset:64
.Lat738_i3_nonext:
	s_waitcnt lgkmcnt(0)
	v_mfma_f32_16x16x32_bf16 v[44:47], v[4:7], v[104:107], 0
	v_mfma_f32_16x16x32_bf16 v[48:51], v[12:15], v[104:107], 0
	v_mfma_f32_16x16x32_bf16 v[52:55], v[20:23], v[104:107], 0
	v_mfma_f32_16x16x32_bf16 v[56:59], v[28:31], v[104:107], 0
	v_mfma_f32_16x16x32_bf16 v[60:63], v[36:39], v[104:107], 0
	v_mfma_f32_16x16x32_bf16 v[44:47], v[8:11], v[108:111], v[44:47]
	v_mfma_f32_16x16x32_bf16 v[48:51], v[16:19], v[108:111], v[48:51]
	v_mfma_f32_16x16x32_bf16 v[52:55], v[24:27], v[108:111], v[52:55]
	v_mfma_f32_16x16x32_bf16 v[56:59], v[32:35], v[108:111], v[56:59]
	v_mfma_f32_16x16x32_bf16 v[60:63], v[40:43], v[108:111], v[60:63]
	ds_read_b128 v[4:7], v230 offset:43008
	ds_read_b128 v[8:11], v231 offset:43008
	ds_read_b128 v[12:15], v230 offset:45056
	ds_read_b128 v[16:19], v231 offset:45056
	ds_read_b128 v[20:23], v230 offset:47104
	ds_read_b128 v[24:27], v231 offset:47104
	ds_read_b128 v[28:31], v230 offset:49152
	ds_read_b128 v[32:35], v231 offset:49152
	s_nop 1
	v_fma_f32 v44, v44, s79, v185
	v_fma_f32 v45, v45, s79, v186
	v_fma_f32 v46, v46, s79, v187
	v_fma_f32 v47, v47, s79, v188
	v_fma_f32 v48, v48, s79, v189
	v_fma_f32 v49, v49, s79, v190
	s_waitcnt lgkmcnt(0)
	v_mfma_f32_16x16x32_bf16 v[64:67], v[4:7], v[104:107], 0
	v_fma_f32 v50, v50, s79, v191
	v_fma_f32 v51, v51, s79, v192
	v_mfma_f32_16x16x32_bf16 v[68:71], v[12:15], v[104:107], 0
	v_fma_f32 v52, v52, s79, v193
	v_fma_f32 v53, v53, s79, v194
	v_mfma_f32_16x16x32_bf16 v[72:75], v[20:23], v[104:107], 0
	v_fma_f32 v54, v54, s79, v195
	v_fma_f32 v55, v55, s79, v196
	v_mfma_f32_16x16x32_bf16 v[76:79], v[28:31], v[104:107], 0
	v_fma_f32 v56, v56, s79, v197
	v_fma_f32 v57, v57, s79, v198
	v_mfma_f32_16x16x32_bf16 v[64:67], v[8:11], v[108:111], v[64:67]
	v_fma_f32 v58, v58, s79, v199
	v_fma_f32 v59, v59, s79, v200
	v_mfma_f32_16x16x32_bf16 v[68:71], v[16:19], v[108:111], v[68:71]
	v_fma_f32 v60, v60, s79, v201
	v_fma_f32 v61, v61, s79, v202
	v_mfma_f32_16x16x32_bf16 v[72:75], v[24:27], v[108:111], v[72:75]
	v_fma_f32 v62, v62, s79, v203
	v_fma_f32 v63, v63, s79, v204
	v_mfma_f32_16x16x32_bf16 v[76:79], v[32:35], v[108:111], v[76:79]
	ds_read_b64 v[4:5], v221 offset:32768
	ds_read_b64 v[8:9], v221 offset:36864
	ds_read_b64 v[12:13], v221 offset:40960
	ds_read_b64 v[16:17], v221 offset:45056
	ds_read_b64 v[6:7], v222 offset:32768
	ds_read_b64 v[10:11], v222 offset:36864
	ds_read_b64 v[14:15], v222 offset:40960
	ds_read_b64 v[18:19], v222 offset:45056
	s_nop 1
	v_fma_f32 v64, v64, s79, v205
	v_fma_f32 v65, v65, s79, v206
	v_fma_f32 v66, v66, s79, v207
	v_fma_f32 v67, v67, s79, v208
	v_fma_f32 v68, v68, s79, v209
	v_fma_f32 v69, v69, s79, v210
	v_fma_f32 v70, v70, s79, v211
	v_fma_f32 v71, v71, s79, v212
	v_fma_f32 v72, v72, s79, v213
	v_fma_f32 v73, v73, s79, v214
	v_fma_f32 v74, v74, s79, v215
	v_fma_f32 v75, v75, s79, v216
	v_fma_f32 v76, v76, s79, v217
	v_fma_f32 v77, v77, s79, v218
	v_fma_f32 v78, v78, s79, v219
	v_fma_f32 v79, v79, s79, v220
	ds_read_b64 v[20:21], v223 offset:32768
	ds_read_b64 v[24:25], v223 offset:36864
	ds_read_b64 v[28:29], v223 offset:40960
	ds_read_b64 v[32:33], v223 offset:45056
	ds_read_b64 v[22:23], v224 offset:32768
	ds_read_b64 v[26:27], v224 offset:36864
	ds_read_b64 v[30:31], v224 offset:40960
	ds_read_b64 v[34:35], v224 offset:45056
	s_cmp_lg_u32 s4, 0
	s_cbranch_scc1 .Lat738_i3_nomask
	s_cmp_le_u32 s6, 0
	s_cbranch_scc1 .Lat738_i3_nomask
	v_mov_b32_e32 v44, v244
	v_mov_b32_e32 v45, v244
	v_mov_b32_e32 v46, v244
	v_mov_b32_e32 v47, v244
	s_cmp_le_u32 s6, 1
	s_cbranch_scc1 .Lat738_i3_nomask
	v_mov_b32_e32 v48, v244
	v_mov_b32_e32 v49, v244
	v_mov_b32_e32 v50, v244
	v_mov_b32_e32 v51, v244
	s_cmp_le_u32 s6, 2
	s_cbranch_scc1 .Lat738_i3_nomask
	v_mov_b32_e32 v52, v244
	v_mov_b32_e32 v53, v244
	v_mov_b32_e32 v54, v244
	v_mov_b32_e32 v55, v244
	s_cmp_le_u32 s6, 3
	s_cbranch_scc1 .Lat738_i3_nomask
	v_mov_b32_e32 v56, v244
	v_mov_b32_e32 v57, v244
	v_mov_b32_e32 v58, v244
	v_mov_b32_e32 v59, v244
	s_cmp_le_u32 s6, 4
	s_cbranch_scc1 .Lat738_i3_nomask
	v_mov_b32_e32 v60, v244
	v_mov_b32_e32 v61, v244
	v_mov_b32_e32 v62, v244
	v_mov_b32_e32 v63, v244
	s_cmp_le_u32 s6, 5
	s_cbranch_scc1 .Lat738_i3_nomask
	v_mov_b32_e32 v64, v244
	v_mov_b32_e32 v65, v244
	v_mov_b32_e32 v66, v244
	v_mov_b32_e32 v67, v244
	s_cmp_le_u32 s6, 6
	s_cbranch_scc1 .Lat738_i3_nomask
	v_mov_b32_e32 v68, v244
	v_mov_b32_e32 v69, v244
	v_mov_b32_e32 v70, v244
	v_mov_b32_e32 v71, v244
	s_cmp_le_u32 s6, 7
	s_cbranch_scc1 .Lat738_i3_nomask
	v_mov_b32_e32 v72, v244
	v_mov_b32_e32 v73, v244
	v_mov_b32_e32 v74, v244
	v_mov_b32_e32 v75, v244
.Lat738_i3_nomask:
	v_max3_f32 v245, v44, v45, v46
	v_max3_f32 v245, v245, v47, v48
	v_max3_f32 v245, v245, v49, v50
	v_max3_f32 v245, v245, v51, v52
	v_max3_f32 v245, v245, v53, v54
	v_max3_f32 v245, v245, v55, v56
	v_max3_f32 v245, v245, v57, v58
	v_max3_f32 v245, v245, v59, v60
	v_max3_f32 v245, v245, v61, v62
	v_max3_f32 v245, v245, v63, v64
	v_max3_f32 v245, v245, v65, v66
	v_max3_f32 v245, v245, v67, v68
	v_max3_f32 v245, v245, v69, v70
	v_max3_f32 v245, v245, v71, v72
	v_max3_f32 v245, v245, v73, v74
	v_max3_f32 v245, v245, v75, v76
	v_max3_f32 v245, v245, v77, v78
	v_max_f32_e32 v245, v245, v79
	ds_bpermute_b32 v148, v239, v245
	s_waitcnt lgkmcnt(0)
	v_max_f32_e32 v245, v245, v148
	ds_bpermute_b32 v148, v240, v245
	s_waitcnt lgkmcnt(0)
	v_max_f32_e32 v245, v245, v148
	v_sub_f32_e32 v44, v44, v245
	v_sub_f32_e32 v45, v45, v245
	v_sub_f32_e32 v46, v46, v245
	v_sub_f32_e32 v47, v47, v245
	v_exp_f32_e32 v44, v44
	v_exp_f32_e32 v45, v45
	v_exp_f32_e32 v46, v46
	v_exp_f32_e32 v47, v47
	v_sub_f32_e32 v48, v48, v245
	v_sub_f32_e32 v49, v49, v245
	v_sub_f32_e32 v50, v50, v245
	v_sub_f32_e32 v51, v51, v245
	v_exp_f32_e32 v48, v48
	v_exp_f32_e32 v49, v49
	v_exp_f32_e32 v50, v50
	v_exp_f32_e32 v51, v51
	v_mov_b32_e32 v149, v44
	v_mov_b32_e32 v150, v45
	v_mov_b32_e32 v151, v46
	v_mov_b32_e32 v152, v47
	v_cvt_pk_bf16_f32 v44, v44, v45
	v_cvt_pk_bf16_f32 v45, v46, v47
	v_sub_f32_e32 v52, v52, v245
	v_sub_f32_e32 v53, v53, v245
	v_sub_f32_e32 v54, v54, v245
	v_sub_f32_e32 v55, v55, v245
	v_exp_f32_e32 v52, v52
	v_exp_f32_e32 v53, v53
	v_exp_f32_e32 v54, v54
	v_exp_f32_e32 v55, v55
	v_add_f32_e32 v149, v149, v48
	v_add_f32_e32 v150, v150, v49
	v_add_f32_e32 v151, v151, v50
	v_add_f32_e32 v152, v152, v51
	v_cvt_pk_bf16_f32 v46, v48, v49
	v_cvt_pk_bf16_f32 v47, v50, v51
	s_waitcnt lgkmcnt(0)
	v_sub_f32_e32 v56, v56, v245
	v_sub_f32_e32 v57, v57, v245
	v_mfma_f32_16x16x32_bf16 v[80:83], v[4:7], v[44:47], 0
	v_sub_f32_e32 v58, v58, v245
	v_sub_f32_e32 v59, v59, v245
	v_exp_f32_e32 v56, v56
	v_mfma_f32_16x16x32_bf16 v[84:87], v[8:11], v[44:47], 0
	v_exp_f32_e32 v57, v57
	v_exp_f32_e32 v58, v58
	v_exp_f32_e32 v59, v59
	v_mfma_f32_16x16x32_bf16 v[88:91], v[12:15], v[44:47], 0
	v_add_f32_e32 v149, v149, v52
	v_add_f32_e32 v150, v150, v53
	v_add_f32_e32 v151, v151, v54
	v_mfma_f32_16x16x32_bf16 v[92:95], v[16:19], v[44:47], 0
	v_add_f32_e32 v152, v152, v55
	v_cvt_pk_bf16_f32 v52, v52, v53
	v_cvt_pk_bf16_f32 v53, v54, v55
	ds_read_b64 v[4:5], v225 offset:32768
	ds_read_b64 v[8:9], v225 offset:36864
	ds_read_b64 v[12:13], v225 offset:40960
	ds_read_b64 v[16:17], v225 offset:45056
	ds_read_b64 v[6:7], v226 offset:32768
	ds_read_b64 v[10:11], v226 offset:36864
	ds_read_b64 v[14:15], v226 offset:40960
	ds_read_b64 v[18:19], v226 offset:45056
	v_sub_f32_e32 v60, v60, v245
	v_sub_f32_e32 v61, v61, v245
	v_sub_f32_e32 v62, v62, v245
	v_sub_f32_e32 v63, v63, v245
	v_exp_f32_e32 v60, v60
	v_exp_f32_e32 v61, v61
	v_exp_f32_e32 v62, v62
	v_exp_f32_e32 v63, v63
	v_add_f32_e32 v149, v149, v56
	v_add_f32_e32 v150, v150, v57
	v_add_f32_e32 v151, v151, v58
	v_add_f32_e32 v152, v152, v59
	v_cvt_pk_bf16_f32 v54, v56, v57
	v_cvt_pk_bf16_f32 v55, v58, v59
	v_sub_f32_e32 v64, v64, v245
	v_sub_f32_e32 v65, v65, v245
	v_mfma_f32_16x16x32_bf16 v[80:83], v[20:23], v[52:55], v[80:83]
	v_sub_f32_e32 v66, v66, v245
	v_sub_f32_e32 v67, v67, v245
	v_exp_f32_e32 v64, v64
	v_mfma_f32_16x16x32_bf16 v[84:87], v[24:27], v[52:55], v[84:87]
	v_exp_f32_e32 v65, v65
	v_exp_f32_e32 v66, v66
	v_exp_f32_e32 v67, v67
	v_mfma_f32_16x16x32_bf16 v[88:91], v[28:31], v[52:55], v[88:91]
	v_add_f32_e32 v149, v149, v60
	v_add_f32_e32 v150, v150, v61
	v_add_f32_e32 v151, v151, v62
	v_mfma_f32_16x16x32_bf16 v[92:95], v[32:35], v[52:55], v[92:95]
	v_add_f32_e32 v152, v152, v63
	v_cvt_pk_bf16_f32 v60, v60, v61
	v_cvt_pk_bf16_f32 v61, v62, v63
	ds_read_b64 v[20:21], v227 offset:32768
	ds_read_b64 v[24:25], v227 offset:36864
	ds_read_b64 v[28:29], v227 offset:40960
	ds_read_b64 v[32:33], v227 offset:45056
	ds_read_b64 v[22:23], v228 offset:32768
	ds_read_b64 v[26:27], v228 offset:36864
	ds_read_b64 v[30:31], v228 offset:40960
	ds_read_b64 v[34:35], v228 offset:45056
	v_sub_f32_e32 v68, v68, v245
	v_sub_f32_e32 v69, v69, v245
	v_sub_f32_e32 v70, v70, v245
	v_sub_f32_e32 v71, v71, v245
	v_exp_f32_e32 v68, v68
	v_exp_f32_e32 v69, v69
	v_exp_f32_e32 v70, v70
	v_exp_f32_e32 v71, v71
	v_add_f32_e32 v149, v149, v64
	v_add_f32_e32 v150, v150, v65
	v_add_f32_e32 v151, v151, v66
	v_add_f32_e32 v152, v152, v67
	v_cvt_pk_bf16_f32 v62, v64, v65
	v_cvt_pk_bf16_f32 v63, v66, v67
	s_waitcnt lgkmcnt(8)
	v_sub_f32_e32 v72, v72, v245
	v_sub_f32_e32 v73, v73, v245
	v_mfma_f32_16x16x32_bf16 v[80:83], v[4:7], v[60:63], v[80:83]
	v_sub_f32_e32 v74, v74, v245
	v_sub_f32_e32 v75, v75, v245
	v_exp_f32_e32 v72, v72
	v_mfma_f32_16x16x32_bf16 v[84:87], v[8:11], v[60:63], v[84:87]
	v_exp_f32_e32 v73, v73
	v_exp_f32_e32 v74, v74
	v_exp_f32_e32 v75, v75
	v_mfma_f32_16x16x32_bf16 v[88:91], v[12:15], v[60:63], v[88:91]
	v_add_f32_e32 v149, v149, v68
	v_add_f32_e32 v150, v150, v69
	v_add_f32_e32 v151, v151, v70
	v_mfma_f32_16x16x32_bf16 v[92:95], v[16:19], v[60:63], v[92:95]
	v_add_f32_e32 v152, v152, v71
	v_cvt_pk_bf16_f32 v68, v68, v69
	v_cvt_pk_bf16_f32 v69, v70, v71
	ds_read_b64 v[4:5], v229 offset:32768
	ds_read_b64 v[8:9], v229 offset:36864
	ds_read_b64 v[12:13], v229 offset:40960
	ds_read_b64 v[16:17], v229 offset:45056
	v_mov_b32_e32 v6, 0
	v_mov_b32_e32 v7, 0
	v_mov_b32_e32 v10, 0
	v_mov_b32_e32 v11, 0
	v_mov_b32_e32 v14, 0
	v_mov_b32_e32 v15, 0
	v_mov_b32_e32 v18, 0
	v_mov_b32_e32 v19, 0
	v_sub_f32_e32 v76, v76, v245
	v_sub_f32_e32 v77, v77, v245
	v_sub_f32_e32 v78, v78, v245
	v_sub_f32_e32 v79, v79, v245
	v_exp_f32_e32 v76, v76
	v_exp_f32_e32 v77, v77
	v_exp_f32_e32 v78, v78
	v_exp_f32_e32 v79, v79
	v_add_f32_e32 v149, v149, v72
	v_add_f32_e32 v150, v150, v73
	v_add_f32_e32 v151, v151, v74
	v_add_f32_e32 v152, v152, v75
	v_cvt_pk_bf16_f32 v70, v72, v73
	v_cvt_pk_bf16_f32 v71, v74, v75
	s_waitcnt lgkmcnt(4)
	v_add_f32_e32 v149, v149, v76
	v_add_f32_e32 v150, v150, v77
	v_mfma_f32_16x16x32_bf16 v[80:83], v[20:23], v[68:71], v[80:83]
	v_add_f32_e32 v151, v151, v78
	v_add_f32_e32 v152, v152, v79
	v_mfma_f32_16x16x32_bf16 v[84:87], v[24:27], v[68:71], v[84:87]
	v_cvt_pk_bf16_f32 v76, v76, v77
	v_cvt_pk_bf16_f32 v77, v78, v79
	v_mfma_f32_16x16x32_bf16 v[88:91], v[28:31], v[68:71], v[88:91]
	v_mov_b32_e32 v78, 0
	v_mov_b32_e32 v79, 0
	v_mfma_f32_16x16x32_bf16 v[92:95], v[32:35], v[68:71], v[92:95]
	v_add_f32_e32 v149, v149, v150
	v_add_f32_e32 v151, v151, v152
	v_add_f32_e32 v246, v149, v151
	ds_bpermute_b32 v148, v239, v246
	s_waitcnt lgkmcnt(1)
	v_mfma_f32_16x16x32_bf16 v[80:83], v[4:7], v[76:79], v[80:83]
	v_mfma_f32_16x16x32_bf16 v[84:87], v[8:11], v[76:79], v[84:87]
	v_mfma_f32_16x16x32_bf16 v[88:91], v[12:15], v[76:79], v[88:91]
	v_mfma_f32_16x16x32_bf16 v[92:95], v[16:19], v[76:79], v[92:95]
	s_waitcnt lgkmcnt(0)
	v_add_f32_e32 v246, v246, v148
	ds_bpermute_b32 v148, v240, v246
	s_waitcnt lgkmcnt(0)
	v_add_f32_e32 v246, v246, v148
	v_rcp_f32_e32 v149, v246
	v_log_f32_e32 v150, v246
	s_nop 0
	v_add_f32_e32 v151, v245, v150
	v_mul_f32_e32 v151, 0x3f317218, v151
	v_mov_b32_e32 v140, v151
	v_mul_f32_e32 v80, v80, v149
	v_mul_f32_e32 v81, v81, v149
	v_mul_f32_e32 v82, v82, v149
	v_mul_f32_e32 v83, v83, v149
	v_mul_f32_e32 v84, v84, v149
	v_mul_f32_e32 v85, v85, v149
	v_mul_f32_e32 v86, v86, v149
	v_mul_f32_e32 v87, v87, v149
	v_mul_f32_e32 v88, v88, v149
	v_mul_f32_e32 v89, v89, v149
	v_mul_f32_e32 v90, v90, v149
	v_mul_f32_e32 v91, v91, v149
	v_mul_f32_e32 v92, v92, v149
	v_mul_f32_e32 v93, v93, v149
	v_mul_f32_e32 v94, v94, v149
	v_mul_f32_e32 v95, v95, v149
	v_cvt_pk_bf16_f32 v132, v80, v81
	v_cvt_pk_bf16_f32 v133, v82, v83
	v_cvt_pk_bf16_f32 v134, v84, v85
	v_cvt_pk_bf16_f32 v135, v86, v87
	v_cvt_pk_bf16_f32 v136, v88, v89
	v_cvt_pk_bf16_f32 v137, v90, v91
	v_cvt_pk_bf16_f32 v138, v92, v93
	v_cvt_pk_bf16_f32 v139, v94, v95
	s_mov_b64 s[26:27], s[86:87]
	s_mov_b64 s[28:29], s[88:89]
	s_mov_b64 s[86:87], s[12:13]
	s_mov_b64 s[88:89], s[14:15]
	s_mov_b32 s4, s83
	s_mov_b32 s5, s84
	s_add_u32 s7, s7, 1
	s_cmp_lt_u32 s7, 2
	s_cbranch_scc1 .Lat738_loop
	s_setprio 0
	global_store_dwordx2 v237, v[132:133], s[26:27]
	global_store_dwordx2 v237, v[134:135], s[26:27] offset:32
	global_store_dwordx2 v237, v[136:137], s[26:27] offset:64
	global_store_dwordx2 v237, v[138:139], s[26:27] offset:96
	s_mov_b64 s[90:91], exec
	s_mov_b64 exec, 0xffff
	global_store_dword v238, v140, s[28:29]
	s_mov_b64 exec, s[90:91]
	s_mov_b64 s[0:1], s[42:43]
	v_writelane_b32 v253, s0, 4
	s_waitcnt vmcnt(0)
	v_readlane_b32 s34, v252, 27
	v_readlane_b32 s36, v252, 29
	v_writelane_b32 v253, s1, 5
	v_readlane_b32 s70, v252, 31
	v_readlane_b32 s56, v253, 19
	v_readlane_b32 s16, v253, 21
	v_readlane_b32 s74, v252, 33
	v_readlane_b32 s76, v252, 35
	v_readlane_b32 s78, v252, 37
	s_mov_b64 s[6:7], 0
	v_readlane_b32 s85, v253, 23
	v_readlane_b32 s92, v253, 24
	v_readlane_b32 s35, v252, 28
	v_readlane_b32 s57, v253, 20
	v_readlane_b32 s17, v253, 22
	v_readlane_b32 s37, v252, 30
	v_readlane_b32 s71, v252, 32
	v_readlane_b32 s75, v252, 34
	v_readlane_b32 s77, v252, 36
	v_readlane_b32 s79, v252, 38
	s_barrier
	v_readlane_b32 s93, v253, 25

.Lat768_i3_nomask:
	v_max3_f32 v245, v44, v45, v46
	v_max3_f32 v245, v245, v47, v48
	v_max3_f32 v245, v245, v49, v50
	v_max3_f32 v245, v245, v51, v52
	v_max3_f32 v245, v245, v53, v54
	v_max3_f32 v245, v245, v55, v56
	v_max3_f32 v245, v245, v57, v58
	v_max3_f32 v245, v245, v59, v60
	v_max3_f32 v245, v245, v61, v62
	v_max3_f32 v245, v245, v63, v64
	v_max3_f32 v245, v245, v65, v66
	v_max3_f32 v245, v245, v67, v68
	v_max3_f32 v245, v245, v69, v70
	v_max3_f32 v245, v245, v71, v72
	v_max3_f32 v245, v245, v73, v74
	v_max3_f32 v245, v245, v75, v76
	v_max3_f32 v245, v245, v77, v78
	v_max_f32_e32 v245, v245, v79
	ds_bpermute_b32 v148, v239, v245
	s_waitcnt lgkmcnt(0)
	v_max_f32_e32 v245, v245, v148
	ds_bpermute_b32 v148, v240, v245
	s_waitcnt lgkmcnt(0)
	v_max_f32_e32 v245, v245, v148
	v_sub_f32_e32 v44, v44, v245
	v_sub_f32_e32 v45, v45, v245
	v_sub_f32_e32 v46, v46, v245
	v_sub_f32_e32 v47, v47, v245
	v_exp_f32_e32 v44, v44
	v_exp_f32_e32 v45, v45
	v_exp_f32_e32 v46, v46
	v_exp_f32_e32 v47, v47
	v_sub_f32_e32 v48, v48, v245
	v_sub_f32_e32 v49, v49, v245
	v_sub_f32_e32 v50, v50, v245
	v_sub_f32_e32 v51, v51, v245
	v_exp_f32_e32 v48, v48
	v_exp_f32_e32 v49, v49
	v_exp_f32_e32 v50, v50
	v_exp_f32_e32 v51, v51
	v_mov_b32_e32 v149, v44
	v_mov_b32_e32 v150, v45
	v_mov_b32_e32 v151, v46
	v_mov_b32_e32 v152, v47
	v_cvt_pk_bf16_f32 v44, v44, v45
	v_cvt_pk_bf16_f32 v45, v46, v47
	v_sub_f32_e32 v52, v52, v245
	v_sub_f32_e32 v53, v53, v245
	v_sub_f32_e32 v54, v54, v245
	v_sub_f32_e32 v55, v55, v245
	v_exp_f32_e32 v52, v52
	v_exp_f32_e32 v53, v53
	v_exp_f32_e32 v54, v54
	v_exp_f32_e32 v55, v55
	v_add_f32_e32 v149, v149, v48
	v_add_f32_e32 v150, v150, v49
	v_add_f32_e32 v151, v151, v50
	v_add_f32_e32 v152, v152, v51
	v_cvt_pk_bf16_f32 v46, v48, v49
	v_cvt_pk_bf16_f32 v47, v50, v51
	s_waitcnt lgkmcnt(0)
	v_sub_f32_e32 v56, v56, v245
	v_sub_f32_e32 v57, v57, v245
	v_mfma_f32_16x16x32_bf16 v[80:83], v[4:7], v[44:47], 0
	v_sub_f32_e32 v58, v58, v245
	v_sub_f32_e32 v59, v59, v245
	v_exp_f32_e32 v56, v56
	v_mfma_f32_16x16x32_bf16 v[84:87], v[8:11], v[44:47], 0
	v_exp_f32_e32 v57, v57
	v_exp_f32_e32 v58, v58
	v_exp_f32_e32 v59, v59
	v_mfma_f32_16x16x32_bf16 v[88:91], v[12:15], v[44:47], 0
	v_add_f32_e32 v149, v149, v52
	v_add_f32_e32 v150, v150, v53
	v_add_f32_e32 v151, v151, v54
	v_mfma_f32_16x16x32_bf16 v[92:95], v[16:19], v[44:47], 0
	v_add_f32_e32 v152, v152, v55
	v_cvt_pk_bf16_f32 v52, v52, v53
	v_cvt_pk_bf16_f32 v53, v54, v55
	ds_read_b64 v[4:5], v225 offset:32768
	ds_read_b64 v[8:9], v225 offset:36864
	ds_read_b64 v[12:13], v225 offset:40960
	ds_read_b64 v[16:17], v225 offset:45056
	ds_read_b64 v[6:7], v226 offset:32768
	ds_read_b64 v[10:11], v226 offset:36864
	ds_read_b64 v[14:15], v226 offset:40960
	ds_read_b64 v[18:19], v226 offset:45056
	v_sub_f32_e32 v60, v60, v245
	v_sub_f32_e32 v61, v61, v245
	v_sub_f32_e32 v62, v62, v245
	v_sub_f32_e32 v63, v63, v245
	v_exp_f32_e32 v60, v60
	v_exp_f32_e32 v61, v61
	v_exp_f32_e32 v62, v62
	v_exp_f32_e32 v63, v63
	v_add_f32_e32 v149, v149, v56
	v_add_f32_e32 v150, v150, v57
	v_add_f32_e32 v151, v151, v58
	v_add_f32_e32 v152, v152, v59
	v_cvt_pk_bf16_f32 v54, v56, v57
	v_cvt_pk_bf16_f32 v55, v58, v59
	v_sub_f32_e32 v64, v64, v245
	v_sub_f32_e32 v65, v65, v245
	v_mfma_f32_16x16x32_bf16 v[80:83], v[20:23], v[52:55], v[80:83]
	v_sub_f32_e32 v66, v66, v245
	v_sub_f32_e32 v67, v67, v245
	v_exp_f32_e32 v64, v64
	v_mfma_f32_16x16x32_bf16 v[84:87], v[24:27], v[52:55], v[84:87]
	v_exp_f32_e32 v65, v65
	v_exp_f32_e32 v66, v66
	v_exp_f32_e32 v67, v67
	v_mfma_f32_16x16x32_bf16 v[88:91], v[28:31], v[52:55], v[88:91]
	v_add_f32_e32 v149, v149, v60
	v_add_f32_e32 v150, v150, v61
	v_add_f32_e32 v151, v151, v62
	v_mfma_f32_16x16x32_bf16 v[92:95], v[32:35], v[52:55], v[92:95]
	v_add_f32_e32 v152, v152, v63
	v_cvt_pk_bf16_f32 v60, v60, v61
	v_cvt_pk_bf16_f32 v61, v62, v63
	ds_read_b64 v[20:21], v227 offset:32768
	ds_read_b64 v[24:25], v227 offset:36864
	ds_read_b64 v[28:29], v227 offset:40960
	ds_read_b64 v[32:33], v227 offset:45056
	ds_read_b64 v[22:23], v228 offset:32768
	ds_read_b64 v[26:27], v228 offset:36864
	ds_read_b64 v[30:31], v228 offset:40960
	ds_read_b64 v[34:35], v228 offset:45056
	v_sub_f32_e32 v68, v68, v245
	v_sub_f32_e32 v69, v69, v245
	v_sub_f32_e32 v70, v70, v245
	v_sub_f32_e32 v71, v71, v245
	v_exp_f32_e32 v68, v68
	v_exp_f32_e32 v69, v69
	v_exp_f32_e32 v70, v70
	v_exp_f32_e32 v71, v71
	v_add_f32_e32 v149, v149, v64
	v_add_f32_e32 v150, v150, v65
	v_add_f32_e32 v151, v151, v66
	v_add_f32_e32 v152, v152, v67
	v_cvt_pk_bf16_f32 v62, v64, v65
	v_cvt_pk_bf16_f32 v63, v66, v67
	s_waitcnt lgkmcnt(8)
	v_sub_f32_e32 v72, v72, v245
	v_sub_f32_e32 v73, v73, v245
	v_mfma_f32_16x16x32_bf16 v[80:83], v[4:7], v[60:63], v[80:83]
	v_sub_f32_e32 v74, v74, v245
	v_sub_f32_e32 v75, v75, v245
	v_exp_f32_e32 v72, v72
	v_mfma_f32_16x16x32_bf16 v[84:87], v[8:11], v[60:63], v[84:87]
	v_exp_f32_e32 v73, v73
	v_exp_f32_e32 v74, v74
	v_exp_f32_e32 v75, v75
	v_mfma_f32_16x16x32_bf16 v[88:91], v[12:15], v[60:63], v[88:91]
	v_add_f32_e32 v149, v149, v68
	v_add_f32_e32 v150, v150, v69
	v_add_f32_e32 v151, v151, v70
	v_mfma_f32_16x16x32_bf16 v[92:95], v[16:19], v[60:63], v[92:95]
	v_add_f32_e32 v152, v152, v71
	v_cvt_pk_bf16_f32 v68, v68, v69
	v_cvt_pk_bf16_f32 v69, v70, v71
	ds_read_b64 v[4:5], v229 offset:32768
	ds_read_b64 v[8:9], v229 offset:36864
	ds_read_b64 v[12:13], v229 offset:40960
	ds_read_b64 v[16:17], v229 offset:45056
	v_mov_b32_e32 v6, 0
	v_mov_b32_e32 v7, 0
	v_mov_b32_e32 v10, 0
	v_mov_b32_e32 v11, 0
	v_mov_b32_e32 v14, 0
	v_mov_b32_e32 v15, 0
	v_mov_b32_e32 v18, 0
	v_mov_b32_e32 v19, 0
	v_sub_f32_e32 v76, v76, v245
	v_sub_f32_e32 v77, v77, v245
	v_sub_f32_e32 v78, v78, v245
	v_sub_f32_e32 v79, v79, v245
	v_exp_f32_e32 v76, v76
	v_exp_f32_e32 v77, v77
	v_exp_f32_e32 v78, v78
	v_exp_f32_e32 v79, v79
	v_add_f32_e32 v149, v149, v72
	v_add_f32_e32 v150, v150, v73
	v_add_f32_e32 v151, v151, v74
	v_add_f32_e32 v152, v152, v75
	v_cvt_pk_bf16_f32 v70, v72, v73
	v_cvt_pk_bf16_f32 v71, v74, v75
	s_waitcnt lgkmcnt(4)
	v_add_f32_e32 v149, v149, v76
	v_add_f32_e32 v150, v150, v77
	v_mfma_f32_16x16x32_bf16 v[80:83], v[20:23], v[68:71], v[80:83]
	v_add_f32_e32 v151, v151, v78
	v_add_f32_e32 v152, v152, v79
	v_mfma_f32_16x16x32_bf16 v[84:87], v[24:27], v[68:71], v[84:87]
	v_cvt_pk_bf16_f32 v76, v76, v77
	v_cvt_pk_bf16_f32 v77, v78, v79
	v_mfma_f32_16x16x32_bf16 v[88:91], v[28:31], v[68:71], v[88:91]
	v_mov_b32_e32 v78, 0
	v_mov_b32_e32 v79, 0
	v_mfma_f32_16x16x32_bf16 v[92:95], v[32:35], v[68:71], v[92:95]
	v_add_f32_e32 v149, v149, v150
	v_add_f32_e32 v151, v151, v152
	v_add_f32_e32 v246, v149, v151
	ds_bpermute_b32 v148, v239, v246
	s_waitcnt lgkmcnt(1)
	v_mfma_f32_16x16x32_bf16 v[80:83], v[4:7], v[76:79], v[80:83]
	v_mfma_f32_16x16x32_bf16 v[84:87], v[8:11], v[76:79], v[84:87]
	v_mfma_f32_16x16x32_bf16 v[88:91], v[12:15], v[76:79], v[88:91]
	v_mfma_f32_16x16x32_bf16 v[92:95], v[16:19], v[76:79], v[92:95]
	s_waitcnt lgkmcnt(0)
	v_add_f32_e32 v246, v246, v148
	ds_bpermute_b32 v148, v240, v246
	s_waitcnt lgkmcnt(0)
	v_add_f32_e32 v246, v246, v148
	v_rcp_f32_e32 v149, v246
	v_log_f32_e32 v150, v246
	s_nop 0
	v_add_f32_e32 v151, v245, v150
	v_mul_f32_e32 v151, 0x3f317218, v151
	v_mov_b32_e32 v140, v151
	v_mul_f32_e32 v80, v80, v149
	v_mul_f32_e32 v81, v81, v149
	v_mul_f32_e32 v82, v82, v149
	v_mul_f32_e32 v83, v83, v149
	v_mul_f32_e32 v84, v84, v149
	v_mul_f32_e32 v85, v85, v149
	v_mul_f32_e32 v86, v86, v149
	v_mul_f32_e32 v87, v87, v149
	v_mul_f32_e32 v88, v88, v149
	v_mul_f32_e32 v89, v89, v149
	v_mul_f32_e32 v90, v90, v149
	v_mul_f32_e32 v91, v91, v149
	v_mul_f32_e32 v92, v92, v149
	v_mul_f32_e32 v93, v93, v149
	v_mul_f32_e32 v94, v94, v149
	v_mul_f32_e32 v95, v95, v149
	v_cvt_pk_bf16_f32 v132, v80, v81
	v_cvt_pk_bf16_f32 v133, v82, v83
	v_cvt_pk_bf16_f32 v134, v84, v85
	v_cvt_pk_bf16_f32 v135, v86, v87
	v_cvt_pk_bf16_f32 v136, v88, v89
	v_cvt_pk_bf16_f32 v137, v90, v91
	v_cvt_pk_bf16_f32 v138, v92, v93
	v_cvt_pk_bf16_f32 v139, v94, v95
	s_mov_b64 s[26:27], s[86:87]
	s_mov_b64 s[28:29], s[88:89]
	s_mov_b64 s[86:87], s[12:13]
	s_mov_b64 s[88:89], s[14:15]
	s_mov_b32 s4, s83
	s_mov_b32 s5, s84
	s_add_u32 s7, s7, 1
	s_cmp_lt_u32 s7, 2
	s_cbranch_scc1 .Lat768_loop
	s_setprio 0
	global_store_dwordx2 v237, v[132:133], s[26:27]
	global_store_dwordx2 v237, v[134:135], s[26:27] offset:32
	global_store_dwordx2 v237, v[136:137], s[26:27] offset:64
	global_store_dwordx2 v237, v[138:139], s[26:27] offset:96
	s_mov_b64 s[90:91], exec
	s_mov_b64 exec, 0xffff
	global_store_dword v238, v140, s[28:29]
	s_mov_b64 exec, s[90:91]
	v_readlane_b32 s0, v253, 62
	v_readlane_b32 s1, v253, 63
	s_waitcnt vmcnt(0)
	v_readlane_b32 s34, v252, 27
	v_writelane_b32 v253, s0, 4
	v_readlane_b32 s36, v252, 29
	v_readlane_b32 s70, v252, 31
	v_writelane_b32 v253, s1, 5
	v_readlane_b32 s74, v252, 33
	v_readlane_b32 s56, v253, 19
	v_readlane_b32 s16, v253, 21
	v_readlane_b32 s76, v252, 35
	v_readlane_b32 s78, v252, 37
	s_barrier
	v_readlane_b32 s35, v252, 28
	v_readlane_b32 s57, v253, 20
	v_readlane_b32 s17, v253, 22
	v_readlane_b32 s37, v252, 30
	v_readlane_b32 s71, v252, 32
	v_readlane_b32 s75, v252, 34
	v_readlane_b32 s77, v252, 36
	v_readlane_b32 s79, v252, 38

.Lat844_i0_nopend:
	s_add_u32 s83, s4, 1
	s_mov_b32 s84, s5
	s_mul_i32 s74, s84, 1024
	s_lshl_b32 s75, s83, 7
	s_add_u32 s74, s74, s75
	s_lshl_b32 s75, s74, 7
	s_add_u32 s16, s60, s75
	s_addc_u32 s17, s61, 0
	s_lshl_b32 s75, s74, 1
	s_add_u32 s24, s64, s75
	s_addc_u32 s25, s65, 0
	s_add_u32 m0, s70, 0x4000
	s_nop 0
	global_load_lds_dwordx4 v232, s[16:17]
	s_add_u32 m0, s70, 0x6000
	s_nop 0
	global_load_lds_dwordx4 v233, s[16:17]
	s_add_u32 m0, s70, 0x14000
	s_nop 0
	global_load_lds_dwordx4 v234, s[24:25]
	s_add_u32 m0, s70, 0x16000
	s_nop 0
	global_load_lds_dwordx4 v235, s[24:25]
	s_lshl_b32 s74, s83, 9
	s_add_u32 s74, s74, s84
	s_lshl_b32 s75, s74, 7
	s_add_u32 s10, s30, s75
	s_addc_u32 s11, s31, 0
	s_add_u32 s12, s34, s75
	s_addc_u32 s13, s35, 0
	s_lshl_b32 s75, s74, 2
	s_add_u32 s14, s58, s75
	s_addc_u32 s15, s59, 0
	global_load_dwordx4 v[104:107], v236, s[10:11]
	global_load_dwordx4 v[108:111], v236, s[10:11] offset:64
	global_load_dwordx2 v[122:123], v237, s[12:13]
	global_load_dwordx2 v[124:125], v237, s[12:13] offset:32
	global_load_dwordx2 v[126:127], v237, s[12:13] offset:64
	global_load_dwordx2 v[128:129], v237, s[12:13] offset:96
	global_load_dword v121, v238, s[14:15]
	s_waitcnt lgkmcnt(0)
	v_mfma_f32_16x16x32_bf16 v[44:47], v[4:7], v[96:99], 0
	v_mfma_f32_16x16x32_bf16 v[48:51], v[12:15], v[96:99], 0
	v_mfma_f32_16x16x32_bf16 v[52:55], v[20:23], v[96:99], 0
	v_mfma_f32_16x16x32_bf16 v[56:59], v[28:31], v[96:99], 0
	v_mfma_f32_16x16x32_bf16 v[60:63], v[36:39], v[96:99], 0
	v_mfma_f32_16x16x32_bf16 v[44:47], v[8:11], v[100:103], v[44:47]
	v_mfma_f32_16x16x32_bf16 v[48:51], v[16:19], v[100:103], v[48:51]
	v_mfma_f32_16x16x32_bf16 v[52:55], v[24:27], v[100:103], v[52:55]
	v_mfma_f32_16x16x32_bf16 v[56:59], v[32:35], v[100:103], v[56:59]
	v_mfma_f32_16x16x32_bf16 v[60:63], v[40:43], v[100:103], v[60:63]
	s_cmp_gt_u32 s6, 5
	s_cselect_b32 s74, s77, s78
	v_add_u32_e32 v146, s74, v230
	v_xor_b32_e32 v147, 64, v146
	ds_read_b128 v[4:7], v146 offset:10240
	ds_read_b128 v[8:11], v147 offset:10240
	s_cmp_gt_u32 s6, 6
	s_cselect_b32 s74, s77, s78
	v_add_u32_e32 v146, s74, v230
	v_xor_b32_e32 v147, 64, v146
	ds_read_b128 v[12:15], v146 offset:12288
	ds_read_b128 v[16:19], v147 offset:12288
	s_cmp_gt_u32 s6, 7
	s_cselect_b32 s74, s77, s78
	v_add_u32_e32 v146, s74, v230
	v_xor_b32_e32 v147, 64, v146
	ds_read_b128 v[20:23], v146 offset:14336
	ds_read_b128 v[24:27], v147 offset:14336
	s_cmp_gt_u32 s6, 8
	s_cselect_b32 s74, s77, s78
	v_add_u32_e32 v146, s74, v230
	v_xor_b32_e32 v147, 64, v146
	ds_read_b128 v[28:31], v146 offset:16384
	ds_read_b128 v[32:35], v147 offset:16384
	s_nop 1
	v_fma_f32 v44, v44, s79, v185
	v_fma_f32 v45, v45, s79, v186
	v_fma_f32 v46, v46, s79, v187
	v_fma_f32 v47, v47, s79, v188
	v_fma_f32 v48, v48, s79, v189
	v_fma_f32 v49, v49, s79, v190
	s_waitcnt lgkmcnt(0)
	v_mfma_f32_16x16x32_bf16 v[64:67], v[4:7], v[96:99], 0
	v_fma_f32 v50, v50, s79, v191
	v_fma_f32 v51, v51, s79, v192
	v_mfma_f32_16x16x32_bf16 v[68:71], v[12:15], v[96:99], 0
	v_fma_f32 v52, v52, s79, v193
	v_fma_f32 v53, v53, s79, v194
	v_mfma_f32_16x16x32_bf16 v[72:75], v[20:23], v[96:99], 0
	v_fma_f32 v54, v54, s79, v195
	v_fma_f32 v55, v55, s79, v196
	v_mfma_f32_16x16x32_bf16 v[76:79], v[28:31], v[96:99], 0
	v_fma_f32 v56, v56, s79, v197
	v_fma_f32 v57, v57, s79, v198
	v_mfma_f32_16x16x32_bf16 v[64:67], v[8:11], v[100:103], v[64:67]
	v_fma_f32 v58, v58, s79, v199
	v_fma_f32 v59, v59, s79, v200
	v_mfma_f32_16x16x32_bf16 v[68:71], v[16:19], v[100:103], v[68:71]
	v_fma_f32 v60, v60, s79, v201
	v_fma_f32 v61, v61, s79, v202
	v_mfma_f32_16x16x32_bf16 v[72:75], v[24:27], v[100:103], v[72:75]
	v_fma_f32 v62, v62, s79, v203
	v_fma_f32 v63, v63, s79, v204
	v_mfma_f32_16x16x32_bf16 v[76:79], v[32:35], v[100:103], v[76:79]
	s_cmp_gt_u32 s6, 0
	s_cselect_b32 s74, 0, 0xffff0000
	v_add_u32_e32 v146, s74, v221
	ds_read_b64 v[4:5], v146 offset:49152
	ds_read_b64 v[8:9], v146 offset:53248
	ds_read_b64 v[12:13], v146 offset:57344
	ds_read_b64 v[16:17], v146 offset:61440
	s_cmp_gt_u32 s6, 1
	s_cselect_b32 s74, 0, 0xffff0000
	v_add_u32_e32 v146, s74, v222
	ds_read_b64 v[6:7], v146 offset:49152
	ds_read_b64 v[10:11], v146 offset:53248
	ds_read_b64 v[14:15], v146 offset:57344
	ds_read_b64 v[18:19], v146 offset:61440
	s_nop 1
	v_fma_f32 v64, v64, s79, v205
	v_fma_f32 v65, v65, s79, v206
	v_fma_f32 v66, v66, s79, v207
	v_fma_f32 v67, v67, s79, v208
	v_fma_f32 v68, v68, s79, v209
	v_fma_f32 v69, v69, s79, v210
	v_fma_f32 v70, v70, s79, v211
	v_fma_f32 v71, v71, s79, v212
	v_fma_f32 v72, v72, s79, v213
	v_fma_f32 v73, v73, s79, v214
	v_fma_f32 v74, v74, s79, v215
	v_fma_f32 v75, v75, s79, v216
	v_fma_f32 v76, v76, s79, v217
	v_fma_f32 v77, v77, s79, v218
	v_fma_f32 v78, v78, s79, v219
	v_fma_f32 v79, v79, s79, v220
	s_cmp_gt_u32 s6, 2
	s_cselect_b32 s74, 0, 0xffff0000
	v_add_u32_e32 v146, s74, v223
	ds_read_b64 v[20:21], v146 offset:49152
	ds_read_b64 v[24:25], v146 offset:53248
	ds_read_b64 v[28:29], v146 offset:57344
	ds_read_b64 v[32:33], v146 offset:61440
	s_cmp_gt_u32 s6, 3
	s_cselect_b32 s74, 0, 0xffff0000
	v_add_u32_e32 v146, s74, v224
	ds_read_b64 v[22:23], v146 offset:49152
	ds_read_b64 v[26:27], v146 offset:53248
	ds_read_b64 v[30:31], v146 offset:57344
	ds_read_b64 v[34:35], v146 offset:61440
	s_cmp_lg_u32 s4, 0
	s_cbranch_scc1 .Lat844_i0_nomask
	s_cmp_le_u32 s6, 0
	s_cbranch_scc1 .Lat844_i0_nomask
	v_mov_b32_e32 v44, v244
	v_mov_b32_e32 v45, v244
	v_mov_b32_e32 v46, v244
	v_mov_b32_e32 v47, v244
	s_cmp_le_u32 s6, 1
	s_cbranch_scc1 .Lat844_i0_nomask
	v_mov_b32_e32 v48, v244
	v_mov_b32_e32 v49, v244
	v_mov_b32_e32 v50, v244
	v_mov_b32_e32 v51, v244
	s_cmp_le_u32 s6, 2
	s_cbranch_scc1 .Lat844_i0_nomask
	v_mov_b32_e32 v52, v244
	v_mov_b32_e32 v53, v244
	v_mov_b32_e32 v54, v244
	v_mov_b32_e32 v55, v244
	s_cmp_le_u32 s6, 3
	s_cbranch_scc1 .Lat844_i0_nomask
	v_mov_b32_e32 v56, v244
	v_mov_b32_e32 v57, v244
	v_mov_b32_e32 v58, v244
	v_mov_b32_e32 v59, v244
	s_cmp_le_u32 s6, 4
	s_cbranch_scc1 .Lat844_i0_nomask
	v_mov_b32_e32 v60, v244
	v_mov_b32_e32 v61, v244
	v_mov_b32_e32 v62, v244
	v_mov_b32_e32 v63, v244
	s_cmp_le_u32 s6, 5
	s_cbranch_scc1 .Lat844_i0_nomask
	v_mov_b32_e32 v64, v244
	v_mov_b32_e32 v65, v244
	v_mov_b32_e32 v66, v244
	v_mov_b32_e32 v67, v244
	s_cmp_le_u32 s6, 6
	s_cbranch_scc1 .Lat844_i0_nomask
	v_mov_b32_e32 v68, v244
	v_mov_b32_e32 v69, v244
	v_mov_b32_e32 v70, v244
	v_mov_b32_e32 v71, v244
	s_cmp_le_u32 s6, 7
	s_cbranch_scc1 .Lat844_i0_nomask
	v_mov_b32_e32 v72, v244
	v_mov_b32_e32 v73, v244
	v_mov_b32_e32 v74, v244
	v_mov_b32_e32 v75, v244
.Lat844_i0_nomask:
	v_max3_f32 v245, v44, v45, v46
	v_max3_f32 v245, v245, v47, v48
	v_max3_f32 v245, v245, v49, v50
	v_max3_f32 v245, v245, v51, v52
	v_max3_f32 v245, v245, v53, v54
	v_max3_f32 v245, v245, v55, v56
	v_max3_f32 v245, v245, v57, v58
	v_max3_f32 v245, v245, v59, v60
	v_max3_f32 v245, v245, v61, v62
	v_max3_f32 v245, v245, v63, v64
	v_max3_f32 v245, v245, v65, v66
	v_max3_f32 v245, v245, v67, v68
	v_max3_f32 v245, v245, v69, v70
	v_max3_f32 v245, v245, v71, v72
	v_max3_f32 v245, v245, v73, v74
	v_max3_f32 v245, v245, v75, v76
	v_max3_f32 v245, v245, v77, v78
	v_max_f32_e32 v245, v245, v79
	ds_bpermute_b32 v148, v239, v245
	s_waitcnt lgkmcnt(0)
	v_max_f32_e32 v245, v245, v148
	ds_bpermute_b32 v148, v240, v245
	s_waitcnt lgkmcnt(0)
	v_max_f32_e32 v245, v245, v148
	v_sub_f32_e32 v44, v44, v245
	v_sub_f32_e32 v45, v45, v245
	v_sub_f32_e32 v46, v46, v245
	v_sub_f32_e32 v47, v47, v245
	v_exp_f32_e32 v44, v44
	v_exp_f32_e32 v45, v45
	v_exp_f32_e32 v46, v46
	v_exp_f32_e32 v47, v47
	v_sub_f32_e32 v48, v48, v245
	v_sub_f32_e32 v49, v49, v245
	v_sub_f32_e32 v50, v50, v245
	v_sub_f32_e32 v51, v51, v245
	v_exp_f32_e32 v48, v48
	v_exp_f32_e32 v49, v49
	v_exp_f32_e32 v50, v50
	v_exp_f32_e32 v51, v51
	v_mov_b32_e32 v149, v44
	v_mov_b32_e32 v150, v45
	v_mov_b32_e32 v151, v46
	v_mov_b32_e32 v152, v47
	v_cvt_pk_bf16_f32 v44, v44, v45
	v_cvt_pk_bf16_f32 v45, v46, v47
	v_sub_f32_e32 v52, v52, v245
	v_sub_f32_e32 v53, v53, v245
	v_sub_f32_e32 v54, v54, v245
	v_sub_f32_e32 v55, v55, v245
	v_exp_f32_e32 v52, v52
	v_exp_f32_e32 v53, v53
	v_exp_f32_e32 v54, v54
	v_exp_f32_e32 v55, v55
	v_add_f32_e32 v149, v149, v48
	v_add_f32_e32 v150, v150, v49
	v_add_f32_e32 v151, v151, v50
	v_add_f32_e32 v152, v152, v51
	v_cvt_pk_bf16_f32 v46, v48, v49
	v_cvt_pk_bf16_f32 v47, v50, v51
	s_waitcnt lgkmcnt(0)
	v_sub_f32_e32 v56, v56, v245
	v_sub_f32_e32 v57, v57, v245
	v_mfma_f32_16x16x32_bf16 v[80:83], v[4:7], v[44:47], 0
	v_sub_f32_e32 v58, v58, v245
	v_sub_f32_e32 v59, v59, v245
	v_exp_f32_e32 v56, v56
	v_mfma_f32_16x16x32_bf16 v[84:87], v[8:11], v[44:47], 0
	v_exp_f32_e32 v57, v57
	v_exp_f32_e32 v58, v58
	v_exp_f32_e32 v59, v59
	v_mfma_f32_16x16x32_bf16 v[88:91], v[12:15], v[44:47], 0
	v_add_f32_e32 v149, v149, v52
	v_add_f32_e32 v150, v150, v53
	v_add_f32_e32 v151, v151, v54
	v_mfma_f32_16x16x32_bf16 v[92:95], v[16:19], v[44:47], 0
	v_add_f32_e32 v152, v152, v55
	v_cvt_pk_bf16_f32 v52, v52, v53
	v_cvt_pk_bf16_f32 v53, v54, v55
	s_cmp_gt_u32 s6, 4
	s_cselect_b32 s74, 0, 0xffff0000
	v_add_u32_e32 v146, s74, v225
	ds_read_b64 v[4:5], v146 offset:49152
	ds_read_b64 v[8:9], v146 offset:53248
	ds_read_b64 v[12:13], v146 offset:57344
	ds_read_b64 v[16:17], v146 offset:61440
	s_cmp_gt_u32 s6, 5
	s_cselect_b32 s74, 0, 0xffff0000
	v_add_u32_e32 v146, s74, v226
	ds_read_b64 v[6:7], v146 offset:49152
	ds_read_b64 v[10:11], v146 offset:53248
	ds_read_b64 v[14:15], v146 offset:57344
	ds_read_b64 v[18:19], v146 offset:61440
	v_sub_f32_e32 v60, v60, v245
	v_sub_f32_e32 v61, v61, v245
	v_sub_f32_e32 v62, v62, v245
	v_sub_f32_e32 v63, v63, v245
	v_exp_f32_e32 v60, v60
	v_exp_f32_e32 v61, v61
	v_exp_f32_e32 v62, v62
	v_exp_f32_e32 v63, v63
	v_add_f32_e32 v149, v149, v56
	v_add_f32_e32 v150, v150, v57
	v_add_f32_e32 v151, v151, v58
	v_add_f32_e32 v152, v152, v59
	v_cvt_pk_bf16_f32 v54, v56, v57
	v_cvt_pk_bf16_f32 v55, v58, v59
	v_sub_f32_e32 v64, v64, v245
	v_sub_f32_e32 v65, v65, v245
	v_mfma_f32_16x16x32_bf16 v[80:83], v[20:23], v[52:55], v[80:83]
	v_sub_f32_e32 v66, v66, v245
	v_sub_f32_e32 v67, v67, v245
	v_exp_f32_e32 v64, v64
	v_mfma_f32_16x16x32_bf16 v[84:87], v[24:27], v[52:55], v[84:87]
	v_exp_f32_e32 v65, v65
	v_exp_f32_e32 v66, v66
	v_exp_f32_e32 v67, v67
	v_mfma_f32_16x16x32_bf16 v[88:91], v[28:31], v[52:55], v[88:91]
	v_add_f32_e32 v149, v149, v60
	v_add_f32_e32 v150, v150, v61
	v_add_f32_e32 v151, v151, v62
	v_mfma_f32_16x16x32_bf16 v[92:95], v[32:35], v[52:55], v[92:95]
	v_add_f32_e32 v152, v152, v63
	v_cvt_pk_bf16_f32 v60, v60, v61
	v_cvt_pk_bf16_f32 v61, v62, v63
	s_cmp_gt_u32 s6, 6
	s_cselect_b32 s74, 0, 0xffff0000
	v_add_u32_e32 v146, s74, v227
	ds_read_b64 v[20:21], v146 offset:49152
	ds_read_b64 v[24:25], v146 offset:53248
	ds_read_b64 v[28:29], v146 offset:57344
	ds_read_b64 v[32:33], v146 offset:61440
	s_cmp_gt_u32 s6, 7
	s_cselect_b32 s74, 0, 0xffff0000
	v_add_u32_e32 v146, s74, v228
	ds_read_b64 v[22:23], v146 offset:49152
	ds_read_b64 v[26:27], v146 offset:53248
	ds_read_b64 v[30:31], v146 offset:57344
	ds_read_b64 v[34:35], v146 offset:61440
	v_sub_f32_e32 v68, v68, v245
	v_sub_f32_e32 v69, v69, v245
	v_sub_f32_e32 v70, v70, v245
	v_sub_f32_e32 v71, v71, v245
	v_exp_f32_e32 v68, v68
	v_exp_f32_e32 v69, v69
	v_exp_f32_e32 v70, v70
	v_exp_f32_e32 v71, v71
	v_add_f32_e32 v149, v149, v64
	v_add_f32_e32 v150, v150, v65
	v_add_f32_e32 v151, v151, v66
	v_add_f32_e32 v152, v152, v67
	v_cvt_pk_bf16_f32 v62, v64, v65
	v_cvt_pk_bf16_f32 v63, v66, v67
	s_waitcnt lgkmcnt(8)
	v_sub_f32_e32 v72, v72, v245
	v_sub_f32_e32 v73, v73, v245
	v_mfma_f32_16x16x32_bf16 v[80:83], v[4:7], v[60:63], v[80:83]
	v_sub_f32_e32 v74, v74, v245
	v_sub_f32_e32 v75, v75, v245
	v_exp_f32_e32 v72, v72
	v_mfma_f32_16x16x32_bf16 v[84:87], v[8:11], v[60:63], v[84:87]
	v_exp_f32_e32 v73, v73
	v_exp_f32_e32 v74, v74
	v_exp_f32_e32 v75, v75
	v_mfma_f32_16x16x32_bf16 v[88:91], v[12:15], v[60:63], v[88:91]
	v_add_f32_e32 v149, v149, v68
	v_add_f32_e32 v150, v150, v69
	v_add_f32_e32 v151, v151, v70
	v_mfma_f32_16x16x32_bf16 v[92:95], v[16:19], v[60:63], v[92:95]
	v_add_f32_e32 v152, v152, v71
	v_cvt_pk_bf16_f32 v68, v68, v69
	v_cvt_pk_bf16_f32 v69, v70, v71
	s_cmp_gt_u32 s6, 8
	s_cselect_b32 s74, 0, 0xffff0000
	v_add_u32_e32 v146, s74, v229
	ds_read_b64 v[4:5], v146 offset:49152
	ds_read_b64 v[8:9], v146 offset:53248
	ds_read_b64 v[12:13], v146 offset:57344
	ds_read_b64 v[16:17], v146 offset:61440
	v_mov_b32_e32 v6, 0
	v_mov_b32_e32 v7, 0
	v_mov_b32_e32 v10, 0
	v_mov_b32_e32 v11, 0
	v_mov_b32_e32 v14, 0
	v_mov_b32_e32 v15, 0
	v_mov_b32_e32 v18, 0
	v_mov_b32_e32 v19, 0
	v_sub_f32_e32 v76, v76, v245
	v_sub_f32_e32 v77, v77, v245
	v_sub_f32_e32 v78, v78, v245
	v_sub_f32_e32 v79, v79, v245
	v_exp_f32_e32 v76, v76
	v_exp_f32_e32 v77, v77
	v_exp_f32_e32 v78, v78
	v_exp_f32_e32 v79, v79
	v_add_f32_e32 v149, v149, v72
	v_add_f32_e32 v150, v150, v73
	v_add_f32_e32 v151, v151, v74
	v_add_f32_e32 v152, v152, v75
	v_cvt_pk_bf16_f32 v70, v72, v73
	v_cvt_pk_bf16_f32 v71, v74, v75
	s_waitcnt lgkmcnt(4)
	v_add_f32_e32 v149, v149, v76
	v_add_f32_e32 v150, v150, v77
	v_mfma_f32_16x16x32_bf16 v[80:83], v[20:23], v[68:71], v[80:83]
	v_add_f32_e32 v151, v151, v78
	v_add_f32_e32 v152, v152, v79
	v_mfma_f32_16x16x32_bf16 v[84:87], v[24:27], v[68:71], v[84:87]
	v_cvt_pk_bf16_f32 v76, v76, v77
	v_cvt_pk_bf16_f32 v77, v78, v79
	v_mfma_f32_16x16x32_bf16 v[88:91], v[28:31], v[68:71], v[88:91]
	v_mov_b32_e32 v78, 0
	v_mov_b32_e32 v79, 0
	v_mfma_f32_16x16x32_bf16 v[92:95], v[32:35], v[68:71], v[92:95]
	v_add_f32_e32 v149, v149, v150
	v_add_f32_e32 v151, v151, v152
	v_add_f32_e32 v246, v149, v151
	ds_bpermute_b32 v148, v239, v246
	s_waitcnt lgkmcnt(1)
	v_mfma_f32_16x16x32_bf16 v[80:83], v[4:7], v[76:79], v[80:83]
	v_mfma_f32_16x16x32_bf16 v[84:87], v[8:11], v[76:79], v[84:87]
	v_mfma_f32_16x16x32_bf16 v[88:91], v[12:15], v[76:79], v[88:91]
	v_mfma_f32_16x16x32_bf16 v[92:95], v[16:19], v[76:79], v[92:95]
	s_waitcnt lgkmcnt(0)
	v_add_f32_e32 v246, v246, v148
	ds_bpermute_b32 v148, v240, v246
	s_waitcnt lgkmcnt(0)
	v_add_f32_e32 v246, v246, v148
	v_rcp_f32_e32 v149, v246
	v_log_f32_e32 v150, v246
	s_nop 0
	v_add_f32_e32 v151, v245, v150
	v_mul_f32_e32 v151, 0x3f317218, v151
	v_max_f32_e32 v152, v120, v151
	v_sub_f32_e32 v153, v120, v152
	v_sub_f32_e32 v154, v151, v152
	v_mul_f32_e32 v153, 0x3fb8aa3b, v153
	v_mul_f32_e32 v154, 0x3fb8aa3b, v154
	v_exp_f32_e32 v153, v153
	v_exp_f32_e32 v154, v154
	s_nop 0
	v_add_f32_e32 v155, v153, v154
	v_rcp_f32_e32 v146, v155
	v_log_f32_e32 v150, v155
	s_nop 0
	v_mul_f32_e32 v154, v154, v146
	v_mul_f32_e32 v146, v153, v146
	v_mul_f32_e32 v147, v149, v154
	v_mul_f32_e32 v150, 0x3f317218, v150
	v_add_f32_e32 v140, v152, v150
	v_mul_f32_e32 v80, v80, v147
	v_mul_f32_e32 v81, v81, v147
	v_mul_f32_e32 v82, v82, v147
	v_mul_f32_e32 v83, v83, v147
	v_mul_f32_e32 v84, v84, v147
	v_mul_f32_e32 v85, v85, v147
	v_mul_f32_e32 v86, v86, v147
	v_mul_f32_e32 v87, v87, v147
	v_mul_f32_e32 v88, v88, v147
	v_mul_f32_e32 v89, v89, v147
	v_mul_f32_e32 v90, v90, v147
	v_mul_f32_e32 v91, v91, v147
	v_mul_f32_e32 v92, v92, v147
	v_mul_f32_e32 v93, v93, v147
	v_mul_f32_e32 v94, v94, v147
	v_mul_f32_e32 v95, v95, v147
	v_lshlrev_b32_e32 v141, 16, v112
	v_and_b32_e32 v142, 0xffff0000, v112
	v_lshlrev_b32_e32 v143, 16, v113
	v_and_b32_e32 v144, 0xffff0000, v113
	v_fmac_f32_e32 v80, v146, v141
	v_fmac_f32_e32 v81, v146, v142
	v_fmac_f32_e32 v82, v146, v143
	v_fmac_f32_e32 v83, v146, v144
	v_cvt_pk_bf16_f32 v132, v80, v81
	v_cvt_pk_bf16_f32 v133, v82, v83
	v_lshlrev_b32_e32 v141, 16, v114
	v_and_b32_e32 v142, 0xffff0000, v114
	v_lshlrev_b32_e32 v143, 16, v115
	v_and_b32_e32 v144, 0xffff0000, v115
	v_fmac_f32_e32 v84, v146, v141
	v_fmac_f32_e32 v85, v146, v142
	v_fmac_f32_e32 v86, v146, v143
	v_fmac_f32_e32 v87, v146, v144
	v_cvt_pk_bf16_f32 v134, v84, v85
	v_cvt_pk_bf16_f32 v135, v86, v87
	v_lshlrev_b32_e32 v141, 16, v116
	v_and_b32_e32 v142, 0xffff0000, v116
	v_lshlrev_b32_e32 v143, 16, v117
	v_and_b32_e32 v144, 0xffff0000, v117
	v_fmac_f32_e32 v88, v146, v141
	v_fmac_f32_e32 v89, v146, v142
	v_fmac_f32_e32 v90, v146, v143
	v_fmac_f32_e32 v91, v146, v144
	v_cvt_pk_bf16_f32 v136, v88, v89
	v_cvt_pk_bf16_f32 v137, v90, v91
	v_lshlrev_b32_e32 v141, 16, v118
	v_and_b32_e32 v142, 0xffff0000, v118
	v_lshlrev_b32_e32 v143, 16, v119
	v_and_b32_e32 v144, 0xffff0000, v119
	v_fmac_f32_e32 v92, v146, v141
	v_fmac_f32_e32 v93, v146, v142
	v_fmac_f32_e32 v94, v146, v143
	v_fmac_f32_e32 v95, v146, v144
	v_cvt_pk_bf16_f32 v138, v92, v93
	v_cvt_pk_bf16_f32 v139, v94, v95
	s_mov_b64 s[26:27], s[86:87]
	s_mov_b64 s[28:29], s[88:89]
	s_mov_b64 s[86:87], s[12:13]
	s_mov_b64 s[88:89], s[14:15]
	s_mov_b32 s4, s83
	s_mov_b32 s5, s84
	s_waitcnt vmcnt(0)
	s_barrier
	ds_read_b128 v[4:7], v230 offset:0
	ds_read_b128 v[8:11], v231 offset:0
	ds_read_b128 v[12:15], v230 offset:2048
	ds_read_b128 v[16:19], v231 offset:2048
	ds_read_b128 v[20:23], v230 offset:4096
	ds_read_b128 v[24:27], v231 offset:4096
	ds_read_b128 v[28:31], v230 offset:6144
	ds_read_b128 v[32:35], v231 offset:6144
	ds_read_b128 v[36:39], v230 offset:8192
	ds_read_b128 v[40:43], v231 offset:8192
	global_store_dwordx2 v237, v[132:133], s[26:27]
	global_store_dwordx2 v237, v[134:135], s[26:27] offset:32
	global_store_dwordx2 v237, v[136:137], s[26:27] offset:64
	global_store_dwordx2 v237, v[138:139], s[26:27] offset:96
	s_mov_b64 s[90:91], exec
	s_mov_b64 exec, 0xffff
	global_store_dword v238, v140, s[28:29]
	s_mov_b64 exec, s[90:91]
	s_add_u32 s83, s4, 1
	s_mov_b32 s84, s5
	s_mul_i32 s74, s84, 1024
	s_lshl_b32 s75, s83, 7
	s_add_u32 s74, s74, s75
	s_lshl_b32 s75, s74, 7
	s_add_u32 s16, s60, s75
	s_addc_u32 s17, s61, 0
	s_lshl_b32 s75, s74, 1
	s_add_u32 s24, s64, s75
	s_addc_u32 s25, s65, 0
	s_add_u32 m0, s70, 0x8000
	s_nop 0
	global_load_lds_dwordx4 v232, s[16:17]
	s_add_u32 m0, s70, 0xa000
	s_nop 0
	global_load_lds_dwordx4 v233, s[16:17]
	s_add_u32 m0, s70, 0x18000
	s_nop 0
	global_load_lds_dwordx4 v234, s[24:25]
	s_add_u32 m0, s70, 0x1a000
	s_nop 0
	global_load_lds_dwordx4 v235, s[24:25]
	s_lshl_b32 s74, s83, 9
	s_add_u32 s74, s74, s84
	s_lshl_b32 s75, s74, 7
	s_add_u32 s10, s30, s75
	s_addc_u32 s11, s31, 0
	s_add_u32 s12, s34, s75
	s_addc_u32 s13, s35, 0
	s_lshl_b32 s75, s74, 2
	s_add_u32 s14, s58, s75
	s_addc_u32 s15, s59, 0
	global_load_dwordx4 v[96:99], v236, s[10:11]
	global_load_dwordx4 v[100:103], v236, s[10:11] offset:64
	global_load_dwordx2 v[112:113], v237, s[12:13]
	global_load_dwordx2 v[114:115], v237, s[12:13] offset:32
	global_load_dwordx2 v[116:117], v237, s[12:13] offset:64
	global_load_dwordx2 v[118:119], v237, s[12:13] offset:96
	global_load_dword v120, v238, s[14:15]
	s_waitcnt lgkmcnt(0)
	v_mfma_f32_16x16x32_bf16 v[44:47], v[4:7], v[104:107], 0
	v_mfma_f32_16x16x32_bf16 v[48:51], v[12:15], v[104:107], 0
	v_mfma_f32_16x16x32_bf16 v[52:55], v[20:23], v[104:107], 0
	v_mfma_f32_16x16x32_bf16 v[56:59], v[28:31], v[104:107], 0
	v_mfma_f32_16x16x32_bf16 v[60:63], v[36:39], v[104:107], 0
	v_mfma_f32_16x16x32_bf16 v[44:47], v[8:11], v[108:111], v[44:47]
	v_mfma_f32_16x16x32_bf16 v[48:51], v[16:19], v[108:111], v[48:51]
	v_mfma_f32_16x16x32_bf16 v[52:55], v[24:27], v[108:111], v[52:55]
	v_mfma_f32_16x16x32_bf16 v[56:59], v[32:35], v[108:111], v[56:59]
	v_mfma_f32_16x16x32_bf16 v[60:63], v[40:43], v[108:111], v[60:63]
	ds_read_b128 v[4:7], v230 offset:10240
	ds_read_b128 v[8:11], v231 offset:10240
	ds_read_b128 v[12:15], v230 offset:12288
	ds_read_b128 v[16:19], v231 offset:12288
	ds_read_b128 v[20:23], v230 offset:14336
	ds_read_b128 v[24:27], v231 offset:14336
	ds_read_b128 v[28:31], v230 offset:16384
	ds_read_b128 v[32:35], v231 offset:16384
	s_nop 1
	v_fma_f32 v44, v44, s79, v185
	v_fma_f32 v45, v45, s79, v186
	v_fma_f32 v46, v46, s79, v187
	v_fma_f32 v47, v47, s79, v188
	v_fma_f32 v48, v48, s79, v189
	v_fma_f32 v49, v49, s79, v190
	s_waitcnt lgkmcnt(0)
	v_mfma_f32_16x16x32_bf16 v[64:67], v[4:7], v[104:107], 0
	v_fma_f32 v50, v50, s79, v191
	v_fma_f32 v51, v51, s79, v192
	v_mfma_f32_16x16x32_bf16 v[68:71], v[12:15], v[104:107], 0
	v_fma_f32 v52, v52, s79, v193
	v_fma_f32 v53, v53, s79, v194
	v_mfma_f32_16x16x32_bf16 v[72:75], v[20:23], v[104:107], 0
	v_fma_f32 v54, v54, s79, v195
	v_fma_f32 v55, v55, s79, v196
	v_mfma_f32_16x16x32_bf16 v[76:79], v[28:31], v[104:107], 0
	v_fma_f32 v56, v56, s79, v197
	v_fma_f32 v57, v57, s79, v198
	v_mfma_f32_16x16x32_bf16 v[64:67], v[8:11], v[108:111], v[64:67]
	v_fma_f32 v58, v58, s79, v199
	v_fma_f32 v59, v59, s79, v200
	v_mfma_f32_16x16x32_bf16 v[68:71], v[16:19], v[108:111], v[68:71]
	v_fma_f32 v60, v60, s79, v201
	v_fma_f32 v61, v61, s79, v202
	v_mfma_f32_16x16x32_bf16 v[72:75], v[24:27], v[108:111], v[72:75]
	v_fma_f32 v62, v62, s79, v203
	v_fma_f32 v63, v63, s79, v204
	v_mfma_f32_16x16x32_bf16 v[76:79], v[32:35], v[108:111], v[76:79]
	ds_read_b64 v[4:5], v221 offset:0
	ds_read_b64 v[8:9], v221 offset:4096
	ds_read_b64 v[12:13], v221 offset:8192
	ds_read_b64 v[16:17], v221 offset:12288
	ds_read_b64 v[6:7], v222 offset:0
	ds_read_b64 v[10:11], v222 offset:4096
	ds_read_b64 v[14:15], v222 offset:8192
	ds_read_b64 v[18:19], v222 offset:12288
	s_nop 1
	v_fma_f32 v64, v64, s79, v205
	v_fma_f32 v65, v65, s79, v206
	v_fma_f32 v66, v66, s79, v207
	v_fma_f32 v67, v67, s79, v208
	v_fma_f32 v68, v68, s79, v209
	v_fma_f32 v69, v69, s79, v210
	v_fma_f32 v70, v70, s79, v211
	v_fma_f32 v71, v71, s79, v212
	v_fma_f32 v72, v72, s79, v213
	v_fma_f32 v73, v73, s79, v214
	v_fma_f32 v74, v74, s79, v215
	v_fma_f32 v75, v75, s79, v216
	v_fma_f32 v76, v76, s79, v217
	v_fma_f32 v77, v77, s79, v218
	v_fma_f32 v78, v78, s79, v219
	v_fma_f32 v79, v79, s79, v220
	ds_read_b64 v[20:21], v223 offset:0
	ds_read_b64 v[24:25], v223 offset:4096
	ds_read_b64 v[28:29], v223 offset:8192
	ds_read_b64 v[32:33], v223 offset:12288
	ds_read_b64 v[22:23], v224 offset:0
	ds_read_b64 v[26:27], v224 offset:4096
	ds_read_b64 v[30:31], v224 offset:8192
	ds_read_b64 v[34:35], v224 offset:12288
	s_cmp_lg_u32 s4, 0
	s_cbranch_scc1 .Lat844_i1_nomask
	s_cmp_le_u32 s6, 0
	s_cbranch_scc1 .Lat844_i1_nomask
	v_mov_b32_e32 v44, v244
	v_mov_b32_e32 v45, v244
	v_mov_b32_e32 v46, v244
	v_mov_b32_e32 v47, v244
	s_cmp_le_u32 s6, 1
	s_cbranch_scc1 .Lat844_i1_nomask
	v_mov_b32_e32 v48, v244
	v_mov_b32_e32 v49, v244
	v_mov_b32_e32 v50, v244
	v_mov_b32_e32 v51, v244
	s_cmp_le_u32 s6, 2
	s_cbranch_scc1 .Lat844_i1_nomask
	v_mov_b32_e32 v52, v244
	v_mov_b32_e32 v53, v244
	v_mov_b32_e32 v54, v244
	v_mov_b32_e32 v55, v244
	s_cmp_le_u32 s6, 3
	s_cbranch_scc1 .Lat844_i1_nomask
	v_mov_b32_e32 v56, v244
	v_mov_b32_e32 v57, v244
	v_mov_b32_e32 v58, v244
	v_mov_b32_e32 v59, v244
	s_cmp_le_u32 s6, 4
	s_cbranch_scc1 .Lat844_i1_nomask
	v_mov_b32_e32 v60, v244
	v_mov_b32_e32 v61, v244
	v_mov_b32_e32 v62, v244
	v_mov_b32_e32 v63, v244
	s_cmp_le_u32 s6, 5
	s_cbranch_scc1 .Lat844_i1_nomask
	v_mov_b32_e32 v64, v244
	v_mov_b32_e32 v65, v244
	v_mov_b32_e32 v66, v244
	v_mov_b32_e32 v67, v244
	s_cmp_le_u32 s6, 6
	s_cbranch_scc1 .Lat844_i1_nomask
	v_mov_b32_e32 v68, v244
	v_mov_b32_e32 v69, v244
	v_mov_b32_e32 v70, v244
	v_mov_b32_e32 v71, v244
	s_cmp_le_u32 s6, 7
	s_cbranch_scc1 .Lat844_i1_nomask
	v_mov_b32_e32 v72, v244
	v_mov_b32_e32 v73, v244
	v_mov_b32_e32 v74, v244
	v_mov_b32_e32 v75, v244
.Lat844_i1_nomask:
	v_max3_f32 v245, v44, v45, v46
	v_max3_f32 v245, v245, v47, v48
	v_max3_f32 v245, v245, v49, v50
	v_max3_f32 v245, v245, v51, v52
	v_max3_f32 v245, v245, v53, v54
	v_max3_f32 v245, v245, v55, v56
	v_max3_f32 v245, v245, v57, v58
	v_max3_f32 v245, v245, v59, v60
	v_max3_f32 v245, v245, v61, v62
	v_max3_f32 v245, v245, v63, v64
	v_max3_f32 v245, v245, v65, v66
	v_max3_f32 v245, v245, v67, v68
	v_max3_f32 v245, v245, v69, v70
	v_max3_f32 v245, v245, v71, v72
	v_max3_f32 v245, v245, v73, v74
	v_max3_f32 v245, v245, v75, v76
	v_max3_f32 v245, v245, v77, v78
	v_max_f32_e32 v245, v245, v79
	ds_bpermute_b32 v148, v239, v245
	s_waitcnt lgkmcnt(0)
	v_max_f32_e32 v245, v245, v148
	ds_bpermute_b32 v148, v240, v245
	s_waitcnt lgkmcnt(0)
	v_max_f32_e32 v245, v245, v148
	v_sub_f32_e32 v44, v44, v245
	v_sub_f32_e32 v45, v45, v245
	v_sub_f32_e32 v46, v46, v245
	v_sub_f32_e32 v47, v47, v245
	v_exp_f32_e32 v44, v44
	v_exp_f32_e32 v45, v45
	v_exp_f32_e32 v46, v46
	v_exp_f32_e32 v47, v47
	v_sub_f32_e32 v48, v48, v245
	v_sub_f32_e32 v49, v49, v245
	v_sub_f32_e32 v50, v50, v245
	v_sub_f32_e32 v51, v51, v245
	v_exp_f32_e32 v48, v48
	v_exp_f32_e32 v49, v49
	v_exp_f32_e32 v50, v50
	v_exp_f32_e32 v51, v51
	v_mov_b32_e32 v149, v44
	v_mov_b32_e32 v150, v45
	v_mov_b32_e32 v151, v46
	v_mov_b32_e32 v152, v47
	v_cvt_pk_bf16_f32 v44, v44, v45
	v_cvt_pk_bf16_f32 v45, v46, v47
	v_sub_f32_e32 v52, v52, v245
	v_sub_f32_e32 v53, v53, v245
	v_sub_f32_e32 v54, v54, v245
	v_sub_f32_e32 v55, v55, v245
	v_exp_f32_e32 v52, v52
	v_exp_f32_e32 v53, v53
	v_exp_f32_e32 v54, v54
	v_exp_f32_e32 v55, v55
	v_add_f32_e32 v149, v149, v48
	v_add_f32_e32 v150, v150, v49
	v_add_f32_e32 v151, v151, v50
	v_add_f32_e32 v152, v152, v51
	v_cvt_pk_bf16_f32 v46, v48, v49
	v_cvt_pk_bf16_f32 v47, v50, v51
	s_waitcnt lgkmcnt(0)
	v_sub_f32_e32 v56, v56, v245
	v_sub_f32_e32 v57, v57, v245
	v_mfma_f32_16x16x32_bf16 v[80:83], v[4:7], v[44:47], 0
	v_sub_f32_e32 v58, v58, v245
	v_sub_f32_e32 v59, v59, v245
	v_exp_f32_e32 v56, v56
	v_mfma_f32_16x16x32_bf16 v[84:87], v[8:11], v[44:47], 0
	v_exp_f32_e32 v57, v57
	v_exp_f32_e32 v58, v58
	v_exp_f32_e32 v59, v59
	v_mfma_f32_16x16x32_bf16 v[88:91], v[12:15], v[44:47], 0
	v_add_f32_e32 v149, v149, v52
	v_add_f32_e32 v150, v150, v53
	v_add_f32_e32 v151, v151, v54
	v_mfma_f32_16x16x32_bf16 v[92:95], v[16:19], v[44:47], 0
	v_add_f32_e32 v152, v152, v55
	v_cvt_pk_bf16_f32 v52, v52, v53
	v_cvt_pk_bf16_f32 v53, v54, v55
	ds_read_b64 v[4:5], v225 offset:0
	ds_read_b64 v[8:9], v225 offset:4096
	ds_read_b64 v[12:13], v225 offset:8192
	ds_read_b64 v[16:17], v225 offset:12288
	ds_read_b64 v[6:7], v226 offset:0
	ds_read_b64 v[10:11], v226 offset:4096
	ds_read_b64 v[14:15], v226 offset:8192
	ds_read_b64 v[18:19], v226 offset:12288
	v_sub_f32_e32 v60, v60, v245
	v_sub_f32_e32 v61, v61, v245
	v_sub_f32_e32 v62, v62, v245
	v_sub_f32_e32 v63, v63, v245
	v_exp_f32_e32 v60, v60
	v_exp_f32_e32 v61, v61
	v_exp_f32_e32 v62, v62
	v_exp_f32_e32 v63, v63
	v_add_f32_e32 v149, v149, v56
	v_add_f32_e32 v150, v150, v57
	v_add_f32_e32 v151, v151, v58
	v_add_f32_e32 v152, v152, v59
	v_cvt_pk_bf16_f32 v54, v56, v57
	v_cvt_pk_bf16_f32 v55, v58, v59
	v_sub_f32_e32 v64, v64, v245
	v_sub_f32_e32 v65, v65, v245
	v_mfma_f32_16x16x32_bf16 v[80:83], v[20:23], v[52:55], v[80:83]
	v_sub_f32_e32 v66, v66, v245
	v_sub_f32_e32 v67, v67, v245
	v_exp_f32_e32 v64, v64
	v_mfma_f32_16x16x32_bf16 v[84:87], v[24:27], v[52:55], v[84:87]
	v_exp_f32_e32 v65, v65
	v_exp_f32_e32 v66, v66
	v_exp_f32_e32 v67, v67
	v_mfma_f32_16x16x32_bf16 v[88:91], v[28:31], v[52:55], v[88:91]
	v_add_f32_e32 v149, v149, v60
	v_add_f32_e32 v150, v150, v61
	v_add_f32_e32 v151, v151, v62
	v_mfma_f32_16x16x32_bf16 v[92:95], v[32:35], v[52:55], v[92:95]
	v_add_f32_e32 v152, v152, v63
	v_cvt_pk_bf16_f32 v60, v60, v61
	v_cvt_pk_bf16_f32 v61, v62, v63
	ds_read_b64 v[20:21], v227 offset:0
	ds_read_b64 v[24:25], v227 offset:4096
	ds_read_b64 v[28:29], v227 offset:8192
	ds_read_b64 v[32:33], v227 offset:12288
	ds_read_b64 v[22:23], v228 offset:0
	ds_read_b64 v[26:27], v228 offset:4096
	ds_read_b64 v[30:31], v228 offset:8192
	ds_read_b64 v[34:35], v228 offset:12288
	v_sub_f32_e32 v68, v68, v245
	v_sub_f32_e32 v69, v69, v245
	v_sub_f32_e32 v70, v70, v245
	v_sub_f32_e32 v71, v71, v245
	v_exp_f32_e32 v68, v68
	v_exp_f32_e32 v69, v69
	v_exp_f32_e32 v70, v70
	v_exp_f32_e32 v71, v71
	v_add_f32_e32 v149, v149, v64
	v_add_f32_e32 v150, v150, v65
	v_add_f32_e32 v151, v151, v66
	v_add_f32_e32 v152, v152, v67
	v_cvt_pk_bf16_f32 v62, v64, v65
	v_cvt_pk_bf16_f32 v63, v66, v67
	s_waitcnt lgkmcnt(8)
	v_sub_f32_e32 v72, v72, v245
	v_sub_f32_e32 v73, v73, v245
	v_mfma_f32_16x16x32_bf16 v[80:83], v[4:7], v[60:63], v[80:83]
	v_sub_f32_e32 v74, v74, v245
	v_sub_f32_e32 v75, v75, v245
	v_exp_f32_e32 v72, v72
	v_mfma_f32_16x16x32_bf16 v[84:87], v[8:11], v[60:63], v[84:87]
	v_exp_f32_e32 v73, v73
	v_exp_f32_e32 v74, v74
	v_exp_f32_e32 v75, v75
	v_mfma_f32_16x16x32_bf16 v[88:91], v[12:15], v[60:63], v[88:91]
	v_add_f32_e32 v149, v149, v68
	v_add_f32_e32 v150, v150, v69
	v_add_f32_e32 v151, v151, v70
	v_mfma_f32_16x16x32_bf16 v[92:95], v[16:19], v[60:63], v[92:95]
	v_add_f32_e32 v152, v152, v71
	v_cvt_pk_bf16_f32 v68, v68, v69
	v_cvt_pk_bf16_f32 v69, v70, v71
	ds_read_b64 v[4:5], v229 offset:0
	ds_read_b64 v[8:9], v229 offset:4096
	ds_read_b64 v[12:13], v229 offset:8192
	ds_read_b64 v[16:17], v229 offset:12288
	v_mov_b32_e32 v6, 0
	v_mov_b32_e32 v7, 0
	v_mov_b32_e32 v10, 0
	v_mov_b32_e32 v11, 0
	v_mov_b32_e32 v14, 0
	v_mov_b32_e32 v15, 0
	v_mov_b32_e32 v18, 0
	v_mov_b32_e32 v19, 0
	v_sub_f32_e32 v76, v76, v245
	v_sub_f32_e32 v77, v77, v245
	v_sub_f32_e32 v78, v78, v245
	v_sub_f32_e32 v79, v79, v245
	v_exp_f32_e32 v76, v76
	v_exp_f32_e32 v77, v77
	v_exp_f32_e32 v78, v78
	v_exp_f32_e32 v79, v79
	v_add_f32_e32 v149, v149, v72
	v_add_f32_e32 v150, v150, v73
	v_add_f32_e32 v151, v151, v74
	v_add_f32_e32 v152, v152, v75
	v_cvt_pk_bf16_f32 v70, v72, v73
	v_cvt_pk_bf16_f32 v71, v74, v75
	s_waitcnt lgkmcnt(4)
	v_add_f32_e32 v149, v149, v76
	v_add_f32_e32 v150, v150, v77
	v_mfma_f32_16x16x32_bf16 v[80:83], v[20:23], v[68:71], v[80:83]
	v_add_f32_e32 v151, v151, v78
	v_add_f32_e32 v152, v152, v79
	v_mfma_f32_16x16x32_bf16 v[84:87], v[24:27], v[68:71], v[84:87]
	v_cvt_pk_bf16_f32 v76, v76, v77
	v_cvt_pk_bf16_f32 v77, v78, v79
	v_mfma_f32_16x16x32_bf16 v[88:91], v[28:31], v[68:71], v[88:91]
	v_mov_b32_e32 v78, 0
	v_mov_b32_e32 v79, 0
	v_mfma_f32_16x16x32_bf16 v[92:95], v[32:35], v[68:71], v[92:95]
	v_add_f32_e32 v149, v149, v150
	v_add_f32_e32 v151, v151, v152
	v_add_f32_e32 v246, v149, v151
	ds_bpermute_b32 v148, v239, v246
	s_waitcnt lgkmcnt(1)
	v_mfma_f32_16x16x32_bf16 v[80:83], v[4:7], v[76:79], v[80:83]
	v_mfma_f32_16x16x32_bf16 v[84:87], v[8:11], v[76:79], v[84:87]
	v_mfma_f32_16x16x32_bf16 v[88:91], v[12:15], v[76:79], v[88:91]
	v_mfma_f32_16x16x32_bf16 v[92:95], v[16:19], v[76:79], v[92:95]
	s_waitcnt lgkmcnt(0)
	v_add_f32_e32 v246, v246, v148
	ds_bpermute_b32 v148, v240, v246
	s_waitcnt lgkmcnt(0)
	v_add_f32_e32 v246, v246, v148
	v_rcp_f32_e32 v149, v246
	v_log_f32_e32 v150, v246
	s_nop 0
	v_add_f32_e32 v151, v245, v150
	v_mul_f32_e32 v151, 0x3f317218, v151
	v_max_f32_e32 v152, v121, v151
	v_sub_f32_e32 v153, v121, v152
	v_sub_f32_e32 v154, v151, v152
	v_mul_f32_e32 v153, 0x3fb8aa3b, v153
	v_mul_f32_e32 v154, 0x3fb8aa3b, v154
	v_exp_f32_e32 v153, v153
	v_exp_f32_e32 v154, v154
	s_nop 0
	v_add_f32_e32 v155, v153, v154
	v_rcp_f32_e32 v146, v155
	v_log_f32_e32 v150, v155
	s_nop 0
	v_mul_f32_e32 v154, v154, v146
	v_mul_f32_e32 v146, v153, v146
	v_mul_f32_e32 v147, v149, v154
	v_mul_f32_e32 v150, 0x3f317218, v150
	v_add_f32_e32 v140, v152, v150
	v_mul_f32_e32 v80, v80, v147
	v_mul_f32_e32 v81, v81, v147
	v_mul_f32_e32 v82, v82, v147
	v_mul_f32_e32 v83, v83, v147
	v_mul_f32_e32 v84, v84, v147
	v_mul_f32_e32 v85, v85, v147
	v_mul_f32_e32 v86, v86, v147
	v_mul_f32_e32 v87, v87, v147
	v_mul_f32_e32 v88, v88, v147
	v_mul_f32_e32 v89, v89, v147
	v_mul_f32_e32 v90, v90, v147
	v_mul_f32_e32 v91, v91, v147
	v_mul_f32_e32 v92, v92, v147
	v_mul_f32_e32 v93, v93, v147
	v_mul_f32_e32 v94, v94, v147
	v_mul_f32_e32 v95, v95, v147
	v_lshlrev_b32_e32 v141, 16, v122
	v_and_b32_e32 v142, 0xffff0000, v122
	v_lshlrev_b32_e32 v143, 16, v123
	v_and_b32_e32 v144, 0xffff0000, v123
	v_fmac_f32_e32 v80, v146, v141
	v_fmac_f32_e32 v81, v146, v142
	v_fmac_f32_e32 v82, v146, v143
	v_fmac_f32_e32 v83, v146, v144
	v_cvt_pk_bf16_f32 v132, v80, v81
	v_cvt_pk_bf16_f32 v133, v82, v83
	v_lshlrev_b32_e32 v141, 16, v124
	v_and_b32_e32 v142, 0xffff0000, v124
	v_lshlrev_b32_e32 v143, 16, v125
	v_and_b32_e32 v144, 0xffff0000, v125
	v_fmac_f32_e32 v84, v146, v141
	v_fmac_f32_e32 v85, v146, v142
	v_fmac_f32_e32 v86, v146, v143
	v_fmac_f32_e32 v87, v146, v144
	v_cvt_pk_bf16_f32 v134, v84, v85
	v_cvt_pk_bf16_f32 v135, v86, v87
	v_lshlrev_b32_e32 v141, 16, v126
	v_and_b32_e32 v142, 0xffff0000, v126
	v_lshlrev_b32_e32 v143, 16, v127
	v_and_b32_e32 v144, 0xffff0000, v127
	v_fmac_f32_e32 v88, v146, v141
	v_fmac_f32_e32 v89, v146, v142
	v_fmac_f32_e32 v90, v146, v143
	v_fmac_f32_e32 v91, v146, v144
	v_cvt_pk_bf16_f32 v136, v88, v89
	v_cvt_pk_bf16_f32 v137, v90, v91
	v_lshlrev_b32_e32 v141, 16, v128
	v_and_b32_e32 v142, 0xffff0000, v128
	v_lshlrev_b32_e32 v143, 16, v129
	v_and_b32_e32 v144, 0xffff0000, v129
	v_fmac_f32_e32 v92, v146, v141
	v_fmac_f32_e32 v93, v146, v142
	v_fmac_f32_e32 v94, v146, v143
	v_fmac_f32_e32 v95, v146, v144
	v_cvt_pk_bf16_f32 v138, v92, v93
	v_cvt_pk_bf16_f32 v139, v94, v95
	s_mov_b64 s[26:27], s[86:87]
	s_mov_b64 s[28:29], s[88:89]
	s_mov_b64 s[86:87], s[12:13]
	s_mov_b64 s[88:89], s[14:15]
	s_mov_b32 s4, s83
	s_mov_b32 s5, s84
	s_waitcnt vmcnt(0)
	s_barrier
	ds_read_b128 v[4:7], v230 offset:16384
	ds_read_b128 v[8:11], v231 offset:16384
	ds_read_b128 v[12:15], v230 offset:18432
	ds_read_b128 v[16:19], v231 offset:18432
	ds_read_b128 v[20:23], v230 offset:20480
	ds_read_b128 v[24:27], v231 offset:20480
	ds_read_b128 v[28:31], v230 offset:22528
	ds_read_b128 v[32:35], v231 offset:22528
	ds_read_b128 v[36:39], v230 offset:24576
	ds_read_b128 v[40:43], v231 offset:24576
	global_store_dwordx2 v237, v[132:133], s[26:27]
	global_store_dwordx2 v237, v[134:135], s[26:27] offset:32
	global_store_dwordx2 v237, v[136:137], s[26:27] offset:64
	global_store_dwordx2 v237, v[138:139], s[26:27] offset:96
	s_mov_b64 s[90:91], exec
	s_mov_b64 exec, 0xffff
	global_store_dword v238, v140, s[28:29]
	s_mov_b64 exec, s[90:91]
	s_add_u32 s83, s4, 1
	s_mov_b32 s84, s5
	s_mul_i32 s74, s84, 1024
	s_lshl_b32 s75, s83, 7
	s_add_u32 s74, s74, s75
	s_lshl_b32 s75, s74, 7
	s_add_u32 s16, s60, s75
	s_addc_u32 s17, s61, 0
	s_lshl_b32 s75, s74, 1
	s_add_u32 s24, s64, s75
	s_addc_u32 s25, s65, 0
	s_add_u32 m0, s70, 0xc000
	s_nop 0
	global_load_lds_dwordx4 v232, s[16:17]
	s_add_u32 m0, s70, 0xe000
	s_nop 0
	global_load_lds_dwordx4 v233, s[16:17]
	s_add_u32 m0, s70, 0x1c000
	s_nop 0
	global_load_lds_dwordx4 v234, s[24:25]
	s_add_u32 m0, s70, 0x1e000
	s_nop 0
	global_load_lds_dwordx4 v235, s[24:25]
	s_lshl_b32 s74, s83, 9
	s_add_u32 s74, s74, s84
	s_lshl_b32 s75, s74, 7
	s_add_u32 s10, s30, s75
	s_addc_u32 s11, s31, 0
	s_add_u32 s12, s34, s75
	s_addc_u32 s13, s35, 0
	s_lshl_b32 s75, s74, 2
	s_add_u32 s14, s58, s75
	s_addc_u32 s15, s59, 0
	global_load_dwordx4 v[104:107], v236, s[10:11]
	global_load_dwordx4 v[108:111], v236, s[10:11] offset:64
	global_load_dwordx2 v[122:123], v237, s[12:13]
	global_load_dwordx2 v[124:125], v237, s[12:13] offset:32
	global_load_dwordx2 v[126:127], v237, s[12:13] offset:64
	global_load_dwordx2 v[128:129], v237, s[12:13] offset:96
	global_load_dword v121, v238, s[14:15]
	s_waitcnt lgkmcnt(0)
	v_mfma_f32_16x16x32_bf16 v[44:47], v[4:7], v[96:99], 0
	v_mfma_f32_16x16x32_bf16 v[48:51], v[12:15], v[96:99], 0
	v_mfma_f32_16x16x32_bf16 v[52:55], v[20:23], v[96:99], 0
	v_mfma_f32_16x16x32_bf16 v[56:59], v[28:31], v[96:99], 0
	v_mfma_f32_16x16x32_bf16 v[60:63], v[36:39], v[96:99], 0
	v_mfma_f32_16x16x32_bf16 v[44:47], v[8:11], v[100:103], v[44:47]
	v_mfma_f32_16x16x32_bf16 v[48:51], v[16:19], v[100:103], v[48:51]
	v_mfma_f32_16x16x32_bf16 v[52:55], v[24:27], v[100:103], v[52:55]
	v_mfma_f32_16x16x32_bf16 v[56:59], v[32:35], v[100:103], v[56:59]
	v_mfma_f32_16x16x32_bf16 v[60:63], v[40:43], v[100:103], v[60:63]
	ds_read_b128 v[4:7], v230 offset:26624
	ds_read_b128 v[8:11], v231 offset:26624
	ds_read_b128 v[12:15], v230 offset:28672
	ds_read_b128 v[16:19], v231 offset:28672
	ds_read_b128 v[20:23], v230 offset:30720
	ds_read_b128 v[24:27], v231 offset:30720
	ds_read_b128 v[28:31], v230 offset:32768
	ds_read_b128 v[32:35], v231 offset:32768
	s_nop 1
	v_fma_f32 v44, v44, s79, v185
	v_fma_f32 v45, v45, s79, v186
	v_fma_f32 v46, v46, s79, v187
	v_fma_f32 v47, v47, s79, v188
	v_fma_f32 v48, v48, s79, v189
	v_fma_f32 v49, v49, s79, v190
	s_waitcnt lgkmcnt(0)
	v_mfma_f32_16x16x32_bf16 v[64:67], v[4:7], v[96:99], 0
	v_fma_f32 v50, v50, s79, v191
	v_fma_f32 v51, v51, s79, v192
	v_mfma_f32_16x16x32_bf16 v[68:71], v[12:15], v[96:99], 0
	v_fma_f32 v52, v52, s79, v193
	v_fma_f32 v53, v53, s79, v194
	v_mfma_f32_16x16x32_bf16 v[72:75], v[20:23], v[96:99], 0
	v_fma_f32 v54, v54, s79, v195
	v_fma_f32 v55, v55, s79, v196
	v_mfma_f32_16x16x32_bf16 v[76:79], v[28:31], v[96:99], 0
	v_fma_f32 v56, v56, s79, v197
	v_fma_f32 v57, v57, s79, v198
	v_mfma_f32_16x16x32_bf16 v[64:67], v[8:11], v[100:103], v[64:67]
	v_fma_f32 v58, v58, s79, v199
	v_fma_f32 v59, v59, s79, v200
	v_mfma_f32_16x16x32_bf16 v[68:71], v[16:19], v[100:103], v[68:71]
	v_fma_f32 v60, v60, s79, v201
	v_fma_f32 v61, v61, s79, v202
	v_mfma_f32_16x16x32_bf16 v[72:75], v[24:27], v[100:103], v[72:75]
	v_fma_f32 v62, v62, s79, v203
	v_fma_f32 v63, v63, s79, v204
	v_mfma_f32_16x16x32_bf16 v[76:79], v[32:35], v[100:103], v[76:79]
	ds_read_b64 v[4:5], v221 offset:16384
	ds_read_b64 v[8:9], v221 offset:20480
	ds_read_b64 v[12:13], v221 offset:24576
	ds_read_b64 v[16:17], v221 offset:28672
	ds_read_b64 v[6:7], v222 offset:16384
	ds_read_b64 v[10:11], v222 offset:20480
	ds_read_b64 v[14:15], v222 offset:24576
	ds_read_b64 v[18:19], v222 offset:28672
	s_nop 1
	v_fma_f32 v64, v64, s79, v205
	v_fma_f32 v65, v65, s79, v206
	v_fma_f32 v66, v66, s79, v207
	v_fma_f32 v67, v67, s79, v208
	v_fma_f32 v68, v68, s79, v209
	v_fma_f32 v69, v69, s79, v210
	v_fma_f32 v70, v70, s79, v211
	v_fma_f32 v71, v71, s79, v212
	v_fma_f32 v72, v72, s79, v213
	v_fma_f32 v73, v73, s79, v214
	v_fma_f32 v74, v74, s79, v215
	v_fma_f32 v75, v75, s79, v216
	v_fma_f32 v76, v76, s79, v217
	v_fma_f32 v77, v77, s79, v218
	v_fma_f32 v78, v78, s79, v219
	v_fma_f32 v79, v79, s79, v220
	ds_read_b64 v[20:21], v223 offset:16384
	ds_read_b64 v[24:25], v223 offset:20480
	ds_read_b64 v[28:29], v223 offset:24576
	ds_read_b64 v[32:33], v223 offset:28672
	ds_read_b64 v[22:23], v224 offset:16384
	ds_read_b64 v[26:27], v224 offset:20480
	ds_read_b64 v[30:31], v224 offset:24576
	ds_read_b64 v[34:35], v224 offset:28672
	s_cmp_lg_u32 s4, 0
	s_cbranch_scc1 .Lat844_i2_nomask
	s_cmp_le_u32 s6, 0
	s_cbranch_scc1 .Lat844_i2_nomask
	v_mov_b32_e32 v44, v244
	v_mov_b32_e32 v45, v244
	v_mov_b32_e32 v46, v244
	v_mov_b32_e32 v47, v244
	s_cmp_le_u32 s6, 1
	s_cbranch_scc1 .Lat844_i2_nomask
	v_mov_b32_e32 v48, v244
	v_mov_b32_e32 v49, v244
	v_mov_b32_e32 v50, v244
	v_mov_b32_e32 v51, v244
	s_cmp_le_u32 s6, 2
	s_cbranch_scc1 .Lat844_i2_nomask
	v_mov_b32_e32 v52, v244
	v_mov_b32_e32 v53, v244
	v_mov_b32_e32 v54, v244
	v_mov_b32_e32 v55, v244
	s_cmp_le_u32 s6, 3
	s_cbranch_scc1 .Lat844_i2_nomask
	v_mov_b32_e32 v56, v244
	v_mov_b32_e32 v57, v244
	v_mov_b32_e32 v58, v244
	v_mov_b32_e32 v59, v244
	s_cmp_le_u32 s6, 4
	s_cbranch_scc1 .Lat844_i2_nomask
	v_mov_b32_e32 v60, v244
	v_mov_b32_e32 v61, v244
	v_mov_b32_e32 v62, v244
	v_mov_b32_e32 v63, v244
	s_cmp_le_u32 s6, 5
	s_cbranch_scc1 .Lat844_i2_nomask
	v_mov_b32_e32 v64, v244
	v_mov_b32_e32 v65, v244
	v_mov_b32_e32 v66, v244
	v_mov_b32_e32 v67, v244
	s_cmp_le_u32 s6, 6
	s_cbranch_scc1 .Lat844_i2_nomask
	v_mov_b32_e32 v68, v244
	v_mov_b32_e32 v69, v244
	v_mov_b32_e32 v70, v244
	v_mov_b32_e32 v71, v244
	s_cmp_le_u32 s6, 7
	s_cbranch_scc1 .Lat844_i2_nomask
	v_mov_b32_e32 v72, v244
	v_mov_b32_e32 v73, v244
	v_mov_b32_e32 v74, v244
	v_mov_b32_e32 v75, v244
.Lat844_i2_nomask:
	v_max3_f32 v245, v44, v45, v46
	v_max3_f32 v245, v245, v47, v48
	v_max3_f32 v245, v245, v49, v50
	v_max3_f32 v245, v245, v51, v52
	v_max3_f32 v245, v245, v53, v54
	v_max3_f32 v245, v245, v55, v56
	v_max3_f32 v245, v245, v57, v58
	v_max3_f32 v245, v245, v59, v60
	v_max3_f32 v245, v245, v61, v62
	v_max3_f32 v245, v245, v63, v64
	v_max3_f32 v245, v245, v65, v66
	v_max3_f32 v245, v245, v67, v68
	v_max3_f32 v245, v245, v69, v70
	v_max3_f32 v245, v245, v71, v72
	v_max3_f32 v245, v245, v73, v74
	v_max3_f32 v245, v245, v75, v76
	v_max3_f32 v245, v245, v77, v78
	v_max_f32_e32 v245, v245, v79
	ds_bpermute_b32 v148, v239, v245
	s_waitcnt lgkmcnt(0)
	v_max_f32_e32 v245, v245, v148
	ds_bpermute_b32 v148, v240, v245
	s_waitcnt lgkmcnt(0)
	v_max_f32_e32 v245, v245, v148
	v_sub_f32_e32 v44, v44, v245
	v_sub_f32_e32 v45, v45, v245
	v_sub_f32_e32 v46, v46, v245
	v_sub_f32_e32 v47, v47, v245
	v_exp_f32_e32 v44, v44
	v_exp_f32_e32 v45, v45
	v_exp_f32_e32 v46, v46
	v_exp_f32_e32 v47, v47
	v_sub_f32_e32 v48, v48, v245
	v_sub_f32_e32 v49, v49, v245
	v_sub_f32_e32 v50, v50, v245
	v_sub_f32_e32 v51, v51, v245
	v_exp_f32_e32 v48, v48
	v_exp_f32_e32 v49, v49
	v_exp_f32_e32 v50, v50
	v_exp_f32_e32 v51, v51
	v_mov_b32_e32 v149, v44
	v_mov_b32_e32 v150, v45
	v_mov_b32_e32 v151, v46
	v_mov_b32_e32 v152, v47
	v_cvt_pk_bf16_f32 v44, v44, v45
	v_cvt_pk_bf16_f32 v45, v46, v47
	v_sub_f32_e32 v52, v52, v245
	v_sub_f32_e32 v53, v53, v245
	v_sub_f32_e32 v54, v54, v245
	v_sub_f32_e32 v55, v55, v245
	v_exp_f32_e32 v52, v52
	v_exp_f32_e32 v53, v53
	v_exp_f32_e32 v54, v54
	v_exp_f32_e32 v55, v55
	v_add_f32_e32 v149, v149, v48
	v_add_f32_e32 v150, v150, v49
	v_add_f32_e32 v151, v151, v50
	v_add_f32_e32 v152, v152, v51
	v_cvt_pk_bf16_f32 v46, v48, v49
	v_cvt_pk_bf16_f32 v47, v50, v51
	s_waitcnt lgkmcnt(0)
	v_sub_f32_e32 v56, v56, v245
	v_sub_f32_e32 v57, v57, v245
	v_mfma_f32_16x16x32_bf16 v[80:83], v[4:7], v[44:47], 0
	v_sub_f32_e32 v58, v58, v245
	v_sub_f32_e32 v59, v59, v245
	v_exp_f32_e32 v56, v56
	v_mfma_f32_16x16x32_bf16 v[84:87], v[8:11], v[44:47], 0
	v_exp_f32_e32 v57, v57
	v_exp_f32_e32 v58, v58
	v_exp_f32_e32 v59, v59
	v_mfma_f32_16x16x32_bf16 v[88:91], v[12:15], v[44:47], 0
	v_add_f32_e32 v149, v149, v52
	v_add_f32_e32 v150, v150, v53
	v_add_f32_e32 v151, v151, v54
	v_mfma_f32_16x16x32_bf16 v[92:95], v[16:19], v[44:47], 0
	v_add_f32_e32 v152, v152, v55
	v_cvt_pk_bf16_f32 v52, v52, v53
	v_cvt_pk_bf16_f32 v53, v54, v55
	ds_read_b64 v[4:5], v225 offset:16384
	ds_read_b64 v[8:9], v225 offset:20480
	ds_read_b64 v[12:13], v225 offset:24576
	ds_read_b64 v[16:17], v225 offset:28672
	ds_read_b64 v[6:7], v226 offset:16384
	ds_read_b64 v[10:11], v226 offset:20480
	ds_read_b64 v[14:15], v226 offset:24576
	ds_read_b64 v[18:19], v226 offset:28672
	v_sub_f32_e32 v60, v60, v245
	v_sub_f32_e32 v61, v61, v245
	v_sub_f32_e32 v62, v62, v245
	v_sub_f32_e32 v63, v63, v245
	v_exp_f32_e32 v60, v60
	v_exp_f32_e32 v61, v61
	v_exp_f32_e32 v62, v62
	v_exp_f32_e32 v63, v63
	v_add_f32_e32 v149, v149, v56
	v_add_f32_e32 v150, v150, v57
	v_add_f32_e32 v151, v151, v58
	v_add_f32_e32 v152, v152, v59
	v_cvt_pk_bf16_f32 v54, v56, v57
	v_cvt_pk_bf16_f32 v55, v58, v59
	v_sub_f32_e32 v64, v64, v245
	v_sub_f32_e32 v65, v65, v245
	v_mfma_f32_16x16x32_bf16 v[80:83], v[20:23], v[52:55], v[80:83]
	v_sub_f32_e32 v66, v66, v245
	v_sub_f32_e32 v67, v67, v245
	v_exp_f32_e32 v64, v64
	v_mfma_f32_16x16x32_bf16 v[84:87], v[24:27], v[52:55], v[84:87]
	v_exp_f32_e32 v65, v65
	v_exp_f32_e32 v66, v66
	v_exp_f32_e32 v67, v67
	v_mfma_f32_16x16x32_bf16 v[88:91], v[28:31], v[52:55], v[88:91]
	v_add_f32_e32 v149, v149, v60
	v_add_f32_e32 v150, v150, v61
	v_add_f32_e32 v151, v151, v62
	v_mfma_f32_16x16x32_bf16 v[92:95], v[32:35], v[52:55], v[92:95]
	v_add_f32_e32 v152, v152, v63
	v_cvt_pk_bf16_f32 v60, v60, v61
	v_cvt_pk_bf16_f32 v61, v62, v63
	ds_read_b64 v[20:21], v227 offset:16384
	ds_read_b64 v[24:25], v227 offset:20480
	ds_read_b64 v[28:29], v227 offset:24576
	ds_read_b64 v[32:33], v227 offset:28672
	ds_read_b64 v[22:23], v228 offset:16384
	ds_read_b64 v[26:27], v228 offset:20480
	ds_read_b64 v[30:31], v228 offset:24576
	ds_read_b64 v[34:35], v228 offset:28672
	v_sub_f32_e32 v68, v68, v245
	v_sub_f32_e32 v69, v69, v245
	v_sub_f32_e32 v70, v70, v245
	v_sub_f32_e32 v71, v71, v245
	v_exp_f32_e32 v68, v68
	v_exp_f32_e32 v69, v69
	v_exp_f32_e32 v70, v70
	v_exp_f32_e32 v71, v71
	v_add_f32_e32 v149, v149, v64
	v_add_f32_e32 v150, v150, v65
	v_add_f32_e32 v151, v151, v66
	v_add_f32_e32 v152, v152, v67
	v_cvt_pk_bf16_f32 v62, v64, v65
	v_cvt_pk_bf16_f32 v63, v66, v67
	s_waitcnt lgkmcnt(8)
	v_sub_f32_e32 v72, v72, v245
	v_sub_f32_e32 v73, v73, v245
	v_mfma_f32_16x16x32_bf16 v[80:83], v[4:7], v[60:63], v[80:83]
	v_sub_f32_e32 v74, v74, v245
	v_sub_f32_e32 v75, v75, v245
	v_exp_f32_e32 v72, v72
	v_mfma_f32_16x16x32_bf16 v[84:87], v[8:11], v[60:63], v[84:87]
	v_exp_f32_e32 v73, v73
	v_exp_f32_e32 v74, v74
	v_exp_f32_e32 v75, v75
	v_mfma_f32_16x16x32_bf16 v[88:91], v[12:15], v[60:63], v[88:91]
	v_add_f32_e32 v149, v149, v68
	v_add_f32_e32 v150, v150, v69
	v_add_f32_e32 v151, v151, v70
	v_mfma_f32_16x16x32_bf16 v[92:95], v[16:19], v[60:63], v[92:95]
	v_add_f32_e32 v152, v152, v71
	v_cvt_pk_bf16_f32 v68, v68, v69
	v_cvt_pk_bf16_f32 v69, v70, v71
	ds_read_b64 v[4:5], v229 offset:16384
	ds_read_b64 v[8:9], v229 offset:20480
	ds_read_b64 v[12:13], v229 offset:24576
	ds_read_b64 v[16:17], v229 offset:28672
	v_mov_b32_e32 v6, 0
	v_mov_b32_e32 v7, 0
	v_mov_b32_e32 v10, 0
	v_mov_b32_e32 v11, 0
	v_mov_b32_e32 v14, 0
	v_mov_b32_e32 v15, 0
	v_mov_b32_e32 v18, 0
	v_mov_b32_e32 v19, 0
	v_sub_f32_e32 v76, v76, v245
	v_sub_f32_e32 v77, v77, v245
	v_sub_f32_e32 v78, v78, v245
	v_sub_f32_e32 v79, v79, v245
	v_exp_f32_e32 v76, v76
	v_exp_f32_e32 v77, v77
	v_exp_f32_e32 v78, v78
	v_exp_f32_e32 v79, v79
	v_add_f32_e32 v149, v149, v72
	v_add_f32_e32 v150, v150, v73
	v_add_f32_e32 v151, v151, v74
	v_add_f32_e32 v152, v152, v75
	v_cvt_pk_bf16_f32 v70, v72, v73
	v_cvt_pk_bf16_f32 v71, v74, v75
	s_waitcnt lgkmcnt(4)
	v_add_f32_e32 v149, v149, v76
	v_add_f32_e32 v150, v150, v77
	v_mfma_f32_16x16x32_bf16 v[80:83], v[20:23], v[68:71], v[80:83]
	v_add_f32_e32 v151, v151, v78
	v_add_f32_e32 v152, v152, v79
	v_mfma_f32_16x16x32_bf16 v[84:87], v[24:27], v[68:71], v[84:87]
	v_cvt_pk_bf16_f32 v76, v76, v77
	v_cvt_pk_bf16_f32 v77, v78, v79
	v_mfma_f32_16x16x32_bf16 v[88:91], v[28:31], v[68:71], v[88:91]
	v_mov_b32_e32 v78, 0
	v_mov_b32_e32 v79, 0
	v_mfma_f32_16x16x32_bf16 v[92:95], v[32:35], v[68:71], v[92:95]
	v_add_f32_e32 v149, v149, v150
	v_add_f32_e32 v151, v151, v152
	v_add_f32_e32 v246, v149, v151
	ds_bpermute_b32 v148, v239, v246
	s_waitcnt lgkmcnt(1)
	v_mfma_f32_16x16x32_bf16 v[80:83], v[4:7], v[76:79], v[80:83]
	v_mfma_f32_16x16x32_bf16 v[84:87], v[8:11], v[76:79], v[84:87]
	v_mfma_f32_16x16x32_bf16 v[88:91], v[12:15], v[76:79], v[88:91]
	v_mfma_f32_16x16x32_bf16 v[92:95], v[16:19], v[76:79], v[92:95]
	s_waitcnt lgkmcnt(0)
	v_add_f32_e32 v246, v246, v148
	ds_bpermute_b32 v148, v240, v246
	s_waitcnt lgkmcnt(0)
	v_add_f32_e32 v246, v246, v148
	v_rcp_f32_e32 v149, v246
	v_log_f32_e32 v150, v246
	s_nop 0
	v_add_f32_e32 v151, v245, v150
	v_mul_f32_e32 v151, 0x3f317218, v151
	v_max_f32_e32 v152, v120, v151
	v_sub_f32_e32 v153, v120, v152
	v_sub_f32_e32 v154, v151, v152
	v_mul_f32_e32 v153, 0x3fb8aa3b, v153
	v_mul_f32_e32 v154, 0x3fb8aa3b, v154
	v_exp_f32_e32 v153, v153
	v_exp_f32_e32 v154, v154
	s_nop 0
	v_add_f32_e32 v155, v153, v154
	v_rcp_f32_e32 v146, v155
	v_log_f32_e32 v150, v155
	s_nop 0
	v_mul_f32_e32 v154, v154, v146
	v_mul_f32_e32 v146, v153, v146
	v_mul_f32_e32 v147, v149, v154
	v_mul_f32_e32 v150, 0x3f317218, v150
	v_add_f32_e32 v140, v152, v150
	v_mul_f32_e32 v80, v80, v147
	v_mul_f32_e32 v81, v81, v147
	v_mul_f32_e32 v82, v82, v147
	v_mul_f32_e32 v83, v83, v147
	v_mul_f32_e32 v84, v84, v147
	v_mul_f32_e32 v85, v85, v147
	v_mul_f32_e32 v86, v86, v147
	v_mul_f32_e32 v87, v87, v147
	v_mul_f32_e32 v88, v88, v147
	v_mul_f32_e32 v89, v89, v147
	v_mul_f32_e32 v90, v90, v147
	v_mul_f32_e32 v91, v91, v147
	v_mul_f32_e32 v92, v92, v147
	v_mul_f32_e32 v93, v93, v147
	v_mul_f32_e32 v94, v94, v147
	v_mul_f32_e32 v95, v95, v147
	v_lshlrev_b32_e32 v141, 16, v112
	v_and_b32_e32 v142, 0xffff0000, v112
	v_lshlrev_b32_e32 v143, 16, v113
	v_and_b32_e32 v144, 0xffff0000, v113
	v_fmac_f32_e32 v80, v146, v141
	v_fmac_f32_e32 v81, v146, v142
	v_fmac_f32_e32 v82, v146, v143
	v_fmac_f32_e32 v83, v146, v144
	v_cvt_pk_bf16_f32 v132, v80, v81
	v_cvt_pk_bf16_f32 v133, v82, v83
	v_lshlrev_b32_e32 v141, 16, v114
	v_and_b32_e32 v142, 0xffff0000, v114
	v_lshlrev_b32_e32 v143, 16, v115
	v_and_b32_e32 v144, 0xffff0000, v115
	v_fmac_f32_e32 v84, v146, v141
	v_fmac_f32_e32 v85, v146, v142
	v_fmac_f32_e32 v86, v146, v143
	v_fmac_f32_e32 v87, v146, v144
	v_cvt_pk_bf16_f32 v134, v84, v85
	v_cvt_pk_bf16_f32 v135, v86, v87
	v_lshlrev_b32_e32 v141, 16, v116
	v_and_b32_e32 v142, 0xffff0000, v116
	v_lshlrev_b32_e32 v143, 16, v117
	v_and_b32_e32 v144, 0xffff0000, v117
	v_fmac_f32_e32 v88, v146, v141
	v_fmac_f32_e32 v89, v146, v142
	v_fmac_f32_e32 v90, v146, v143
	v_fmac_f32_e32 v91, v146, v144
	v_cvt_pk_bf16_f32 v136, v88, v89
	v_cvt_pk_bf16_f32 v137, v90, v91
	v_lshlrev_b32_e32 v141, 16, v118
	v_and_b32_e32 v142, 0xffff0000, v118
	v_lshlrev_b32_e32 v143, 16, v119
	v_and_b32_e32 v144, 0xffff0000, v119
	v_fmac_f32_e32 v92, v146, v141
	v_fmac_f32_e32 v93, v146, v142
	v_fmac_f32_e32 v94, v146, v143
	v_fmac_f32_e32 v95, v146, v144
	v_cvt_pk_bf16_f32 v138, v92, v93
	v_cvt_pk_bf16_f32 v139, v94, v95
	s_mov_b64 s[26:27], s[86:87]
	s_mov_b64 s[28:29], s[88:89]
	s_mov_b64 s[86:87], s[12:13]
	s_mov_b64 s[88:89], s[14:15]
	s_mov_b32 s4, s83
	s_mov_b32 s5, s84
	s_waitcnt vmcnt(0)
	s_barrier
	ds_read_b128 v[4:7], v230 offset:32768
	ds_read_b128 v[8:11], v231 offset:32768
	ds_read_b128 v[12:15], v230 offset:34816
	ds_read_b128 v[16:19], v231 offset:34816
	ds_read_b128 v[20:23], v230 offset:36864
	ds_read_b128 v[24:27], v231 offset:36864
	ds_read_b128 v[28:31], v230 offset:38912
	ds_read_b128 v[32:35], v231 offset:38912
	ds_read_b128 v[36:39], v230 offset:40960
	ds_read_b128 v[40:43], v231 offset:40960
	global_store_dwordx2 v237, v[132:133], s[26:27]
	global_store_dwordx2 v237, v[134:135], s[26:27] offset:32
	global_store_dwordx2 v237, v[136:137], s[26:27] offset:64
	global_store_dwordx2 v237, v[138:139], s[26:27] offset:96
	s_mov_b64 s[90:91], exec
	s_mov_b64 exec, 0xffff
	global_store_dword v238, v140, s[28:29]
	s_mov_b64 exec, s[90:91]
	s_cmp_eq_u32 s7, 1
	s_cbranch_scc1 .Lat844_i3_nonext
	s_add_u32 s83, s4, 1
	s_mov_b32 s84, s5
	s_mul_i32 s74, s84, 1024
	s_lshl_b32 s75, s83, 7
	s_add_u32 s74, s74, s75
	s_lshl_b32 s75, s74, 7
	s_add_u32 s16, s60, s75
	s_addc_u32 s17, s61, 0
	s_lshl_b32 s75, s74, 1
	s_add_u32 s24, s64, s75
	s_addc_u32 s25, s65, 0
	s_add_u32 m0, s70, 0x0
	s_nop 0
	global_load_lds_dwordx4 v232, s[16:17]
	s_add_u32 m0, s70, 0x2000
	s_nop 0
	global_load_lds_dwordx4 v233, s[16:17]
	s_add_u32 m0, s70, 0x10000
	s_nop 0
	global_load_lds_dwordx4 v234, s[24:25]
	s_add_u32 m0, s70, 0x12000
	s_nop 0
	global_load_lds_dwordx4 v235, s[24:25]
	s_lshl_b32 s74, s83, 9
	s_add_u32 s74, s74, s84
	s_lshl_b32 s75, s74, 7
	s_add_u32 s10, s30, s75
	s_addc_u32 s11, s31, 0
	s_add_u32 s12, s34, s75
	s_addc_u32 s13, s35, 0
	s_lshl_b32 s75, s74, 2
	s_add_u32 s14, s58, s75
	s_addc_u32 s15, s59, 0
	global_load_dwordx4 v[96:99], v236, s[10:11]
	global_load_dwordx4 v[100:103], v236, s[10:11] offset:64
	global_load_dwordx2 v[112:113], v237, s[12:13]
	global_load_dwordx2 v[114:115], v237, s[12:13] offset:32
	global_load_dwordx2 v[116:117], v237, s[12:13] offset:64
	global_load_dwordx2 v[118:119], v237, s[12:13] offset:96
	global_load_dword v120, v238, s[14:15]

.Lat844_i3_nomask:
	v_max3_f32 v245, v44, v45, v46
	v_max3_f32 v245, v245, v47, v48
	v_max3_f32 v245, v245, v49, v50
	v_max3_f32 v245, v245, v51, v52
	v_max3_f32 v245, v245, v53, v54
	v_max3_f32 v245, v245, v55, v56
	v_max3_f32 v245, v245, v57, v58
	v_max3_f32 v245, v245, v59, v60
	v_max3_f32 v245, v245, v61, v62
	v_max3_f32 v245, v245, v63, v64
	v_max3_f32 v245, v245, v65, v66
	v_max3_f32 v245, v245, v67, v68
	v_max3_f32 v245, v245, v69, v70
	v_max3_f32 v245, v245, v71, v72
	v_max3_f32 v245, v245, v73, v74
	v_max3_f32 v245, v245, v75, v76
	v_max3_f32 v245, v245, v77, v78
	v_max_f32_e32 v245, v245, v79
	ds_bpermute_b32 v148, v239, v245
	s_waitcnt lgkmcnt(0)
	v_max_f32_e32 v245, v245, v148
	ds_bpermute_b32 v148, v240, v245
	s_waitcnt lgkmcnt(0)
	v_max_f32_e32 v245, v245, v148
	v_sub_f32_e32 v44, v44, v245
	v_sub_f32_e32 v45, v45, v245
	v_sub_f32_e32 v46, v46, v245
	v_sub_f32_e32 v47, v47, v245
	v_exp_f32_e32 v44, v44
	v_exp_f32_e32 v45, v45
	v_exp_f32_e32 v46, v46
	v_exp_f32_e32 v47, v47
	v_sub_f32_e32 v48, v48, v245
	v_sub_f32_e32 v49, v49, v245
	v_sub_f32_e32 v50, v50, v245
	v_sub_f32_e32 v51, v51, v245
	v_exp_f32_e32 v48, v48
	v_exp_f32_e32 v49, v49
	v_exp_f32_e32 v50, v50
	v_exp_f32_e32 v51, v51
	v_mov_b32_e32 v149, v44
	v_mov_b32_e32 v150, v45
	v_mov_b32_e32 v151, v46
	v_mov_b32_e32 v152, v47
	v_cvt_pk_bf16_f32 v44, v44, v45
	v_cvt_pk_bf16_f32 v45, v46, v47
	v_sub_f32_e32 v52, v52, v245
	v_sub_f32_e32 v53, v53, v245
	v_sub_f32_e32 v54, v54, v245
	v_sub_f32_e32 v55, v55, v245
	v_exp_f32_e32 v52, v52
	v_exp_f32_e32 v53, v53
	v_exp_f32_e32 v54, v54
	v_exp_f32_e32 v55, v55
	v_add_f32_e32 v149, v149, v48
	v_add_f32_e32 v150, v150, v49
	v_add_f32_e32 v151, v151, v50
	v_add_f32_e32 v152, v152, v51
	v_cvt_pk_bf16_f32 v46, v48, v49
	v_cvt_pk_bf16_f32 v47, v50, v51
	s_waitcnt lgkmcnt(0)
	v_sub_f32_e32 v56, v56, v245
	v_sub_f32_e32 v57, v57, v245
	v_mfma_f32_16x16x32_bf16 v[80:83], v[4:7], v[44:47], 0
	v_sub_f32_e32 v58, v58, v245
	v_sub_f32_e32 v59, v59, v245
	v_exp_f32_e32 v56, v56
	v_mfma_f32_16x16x32_bf16 v[84:87], v[8:11], v[44:47], 0
	v_exp_f32_e32 v57, v57
	v_exp_f32_e32 v58, v58
	v_exp_f32_e32 v59, v59
	v_mfma_f32_16x16x32_bf16 v[88:91], v[12:15], v[44:47], 0
	v_add_f32_e32 v149, v149, v52
	v_add_f32_e32 v150, v150, v53
	v_add_f32_e32 v151, v151, v54
	v_mfma_f32_16x16x32_bf16 v[92:95], v[16:19], v[44:47], 0
	v_add_f32_e32 v152, v152, v55
	v_cvt_pk_bf16_f32 v52, v52, v53
	v_cvt_pk_bf16_f32 v53, v54, v55
	ds_read_b64 v[4:5], v225 offset:32768
	ds_read_b64 v[8:9], v225 offset:36864
	ds_read_b64 v[12:13], v225 offset:40960
	ds_read_b64 v[16:17], v225 offset:45056
	ds_read_b64 v[6:7], v226 offset:32768
	ds_read_b64 v[10:11], v226 offset:36864
	ds_read_b64 v[14:15], v226 offset:40960
	ds_read_b64 v[18:19], v226 offset:45056
	v_sub_f32_e32 v60, v60, v245
	v_sub_f32_e32 v61, v61, v245
	v_sub_f32_e32 v62, v62, v245
	v_sub_f32_e32 v63, v63, v245
	v_exp_f32_e32 v60, v60
	v_exp_f32_e32 v61, v61
	v_exp_f32_e32 v62, v62
	v_exp_f32_e32 v63, v63
	v_add_f32_e32 v149, v149, v56
	v_add_f32_e32 v150, v150, v57
	v_add_f32_e32 v151, v151, v58
	v_add_f32_e32 v152, v152, v59
	v_cvt_pk_bf16_f32 v54, v56, v57
	v_cvt_pk_bf16_f32 v55, v58, v59
	v_sub_f32_e32 v64, v64, v245
	v_sub_f32_e32 v65, v65, v245
	v_mfma_f32_16x16x32_bf16 v[80:83], v[20:23], v[52:55], v[80:83]
	v_sub_f32_e32 v66, v66, v245
	v_sub_f32_e32 v67, v67, v245
	v_exp_f32_e32 v64, v64
	v_mfma_f32_16x16x32_bf16 v[84:87], v[24:27], v[52:55], v[84:87]
	v_exp_f32_e32 v65, v65
	v_exp_f32_e32 v66, v66
	v_exp_f32_e32 v67, v67
	v_mfma_f32_16x16x32_bf16 v[88:91], v[28:31], v[52:55], v[88:91]
	v_add_f32_e32 v149, v149, v60
	v_add_f32_e32 v150, v150, v61
	v_add_f32_e32 v151, v151, v62
	v_mfma_f32_16x16x32_bf16 v[92:95], v[32:35], v[52:55], v[92:95]
	v_add_f32_e32 v152, v152, v63
	v_cvt_pk_bf16_f32 v60, v60, v61
	v_cvt_pk_bf16_f32 v61, v62, v63
	ds_read_b64 v[20:21], v227 offset:32768
	ds_read_b64 v[24:25], v227 offset:36864
	ds_read_b64 v[28:29], v227 offset:40960
	ds_read_b64 v[32:33], v227 offset:45056
	ds_read_b64 v[22:23], v228 offset:32768
	ds_read_b64 v[26:27], v228 offset:36864
	ds_read_b64 v[30:31], v228 offset:40960
	ds_read_b64 v[34:35], v228 offset:45056
	v_sub_f32_e32 v68, v68, v245
	v_sub_f32_e32 v69, v69, v245
	v_sub_f32_e32 v70, v70, v245
	v_sub_f32_e32 v71, v71, v245
	v_exp_f32_e32 v68, v68
	v_exp_f32_e32 v69, v69
	v_exp_f32_e32 v70, v70
	v_exp_f32_e32 v71, v71
	v_add_f32_e32 v149, v149, v64
	v_add_f32_e32 v150, v150, v65
	v_add_f32_e32 v151, v151, v66
	v_add_f32_e32 v152, v152, v67
	v_cvt_pk_bf16_f32 v62, v64, v65
	v_cvt_pk_bf16_f32 v63, v66, v67
	s_waitcnt lgkmcnt(8)
	v_sub_f32_e32 v72, v72, v245
	v_sub_f32_e32 v73, v73, v245
	v_mfma_f32_16x16x32_bf16 v[80:83], v[4:7], v[60:63], v[80:83]
	v_sub_f32_e32 v74, v74, v245
	v_sub_f32_e32 v75, v75, v245
	v_exp_f32_e32 v72, v72
	v_mfma_f32_16x16x32_bf16 v[84:87], v[8:11], v[60:63], v[84:87]
	v_exp_f32_e32 v73, v73
	v_exp_f32_e32 v74, v74
	v_exp_f32_e32 v75, v75
	v_mfma_f32_16x16x32_bf16 v[88:91], v[12:15], v[60:63], v[88:91]
	v_add_f32_e32 v149, v149, v68
	v_add_f32_e32 v150, v150, v69
	v_add_f32_e32 v151, v151, v70
	v_mfma_f32_16x16x32_bf16 v[92:95], v[16:19], v[60:63], v[92:95]
	v_add_f32_e32 v152, v152, v71
	v_cvt_pk_bf16_f32 v68, v68, v69
	v_cvt_pk_bf16_f32 v69, v70, v71
	ds_read_b64 v[4:5], v229 offset:32768
	ds_read_b64 v[8:9], v229 offset:36864
	ds_read_b64 v[12:13], v229 offset:40960
	ds_read_b64 v[16:17], v229 offset:45056
	v_mov_b32_e32 v6, 0
	v_mov_b32_e32 v7, 0
	v_mov_b32_e32 v10, 0
	v_mov_b32_e32 v11, 0
	v_mov_b32_e32 v14, 0
	v_mov_b32_e32 v15, 0
	v_mov_b32_e32 v18, 0
	v_mov_b32_e32 v19, 0
	v_sub_f32_e32 v76, v76, v245
	v_sub_f32_e32 v77, v77, v245
	v_sub_f32_e32 v78, v78, v245
	v_sub_f32_e32 v79, v79, v245
	v_exp_f32_e32 v76, v76
	v_exp_f32_e32 v77, v77
	v_exp_f32_e32 v78, v78
	v_exp_f32_e32 v79, v79
	v_add_f32_e32 v149, v149, v72
	v_add_f32_e32 v150, v150, v73
	v_add_f32_e32 v151, v151, v74
	v_add_f32_e32 v152, v152, v75
	v_cvt_pk_bf16_f32 v70, v72, v73
	v_cvt_pk_bf16_f32 v71, v74, v75
	s_waitcnt lgkmcnt(4)
	v_add_f32_e32 v149, v149, v76
	v_add_f32_e32 v150, v150, v77
	v_mfma_f32_16x16x32_bf16 v[80:83], v[20:23], v[68:71], v[80:83]
	v_add_f32_e32 v151, v151, v78
	v_add_f32_e32 v152, v152, v79
	v_mfma_f32_16x16x32_bf16 v[84:87], v[24:27], v[68:71], v[84:87]
	v_cvt_pk_bf16_f32 v76, v76, v77
	v_cvt_pk_bf16_f32 v77, v78, v79
	v_mfma_f32_16x16x32_bf16 v[88:91], v[28:31], v[68:71], v[88:91]
	v_mov_b32_e32 v78, 0
	v_mov_b32_e32 v79, 0
	v_mfma_f32_16x16x32_bf16 v[92:95], v[32:35], v[68:71], v[92:95]
	v_add_f32_e32 v149, v149, v150
	v_add_f32_e32 v151, v151, v152
	v_add_f32_e32 v246, v149, v151
	ds_bpermute_b32 v148, v239, v246
	s_waitcnt lgkmcnt(1)
	v_mfma_f32_16x16x32_bf16 v[80:83], v[4:7], v[76:79], v[80:83]
	v_mfma_f32_16x16x32_bf16 v[84:87], v[8:11], v[76:79], v[84:87]
	v_mfma_f32_16x16x32_bf16 v[88:91], v[12:15], v[76:79], v[88:91]
	v_mfma_f32_16x16x32_bf16 v[92:95], v[16:19], v[76:79], v[92:95]
	s_waitcnt lgkmcnt(0)
	v_add_f32_e32 v246, v246, v148
	ds_bpermute_b32 v148, v240, v246
	s_waitcnt lgkmcnt(0)
	v_add_f32_e32 v246, v246, v148
	v_rcp_f32_e32 v149, v246
	v_log_f32_e32 v150, v246
	s_nop 0
	v_add_f32_e32 v151, v245, v150
	v_mul_f32_e32 v151, 0x3f317218, v151
	v_max_f32_e32 v152, v121, v151
	v_sub_f32_e32 v153, v121, v152
	v_sub_f32_e32 v154, v151, v152
	v_mul_f32_e32 v153, 0x3fb8aa3b, v153
	v_mul_f32_e32 v154, 0x3fb8aa3b, v154
	v_exp_f32_e32 v153, v153
	v_exp_f32_e32 v154, v154
	s_nop 0
	v_add_f32_e32 v155, v153, v154
	v_rcp_f32_e32 v146, v155
	v_log_f32_e32 v150, v155
	s_nop 0
	v_mul_f32_e32 v154, v154, v146
	v_mul_f32_e32 v146, v153, v146
	v_mul_f32_e32 v147, v149, v154
	v_mul_f32_e32 v150, 0x3f317218, v150
	v_add_f32_e32 v140, v152, v150
	v_mul_f32_e32 v80, v80, v147
	v_mul_f32_e32 v81, v81, v147
	v_mul_f32_e32 v82, v82, v147
	v_mul_f32_e32 v83, v83, v147
	v_mul_f32_e32 v84, v84, v147
	v_mul_f32_e32 v85, v85, v147
	v_mul_f32_e32 v86, v86, v147
	v_mul_f32_e32 v87, v87, v147
	v_mul_f32_e32 v88, v88, v147
	v_mul_f32_e32 v89, v89, v147
	v_mul_f32_e32 v90, v90, v147
	v_mul_f32_e32 v91, v91, v147
	v_mul_f32_e32 v92, v92, v147
	v_mul_f32_e32 v93, v93, v147
	v_mul_f32_e32 v94, v94, v147
	v_mul_f32_e32 v95, v95, v147
	v_lshlrev_b32_e32 v141, 16, v122
	v_and_b32_e32 v142, 0xffff0000, v122
	v_lshlrev_b32_e32 v143, 16, v123
	v_and_b32_e32 v144, 0xffff0000, v123
	v_fmac_f32_e32 v80, v146, v141
	v_fmac_f32_e32 v81, v146, v142
	v_fmac_f32_e32 v82, v146, v143
	v_fmac_f32_e32 v83, v146, v144
	v_cvt_pk_bf16_f32 v132, v80, v81
	v_cvt_pk_bf16_f32 v133, v82, v83
	v_lshlrev_b32_e32 v141, 16, v124
	v_and_b32_e32 v142, 0xffff0000, v124
	v_lshlrev_b32_e32 v143, 16, v125
	v_and_b32_e32 v144, 0xffff0000, v125
	v_fmac_f32_e32 v84, v146, v141
	v_fmac_f32_e32 v85, v146, v142
	v_fmac_f32_e32 v86, v146, v143
	v_fmac_f32_e32 v87, v146, v144
	v_cvt_pk_bf16_f32 v134, v84, v85
	v_cvt_pk_bf16_f32 v135, v86, v87
	v_lshlrev_b32_e32 v141, 16, v126
	v_and_b32_e32 v142, 0xffff0000, v126
	v_lshlrev_b32_e32 v143, 16, v127
	v_and_b32_e32 v144, 0xffff0000, v127
	v_fmac_f32_e32 v88, v146, v141
	v_fmac_f32_e32 v89, v146, v142
	v_fmac_f32_e32 v90, v146, v143
	v_fmac_f32_e32 v91, v146, v144
	v_cvt_pk_bf16_f32 v136, v88, v89
	v_cvt_pk_bf16_f32 v137, v90, v91
	v_lshlrev_b32_e32 v141, 16, v128
	v_and_b32_e32 v142, 0xffff0000, v128
	v_lshlrev_b32_e32 v143, 16, v129
	v_and_b32_e32 v144, 0xffff0000, v129
	v_fmac_f32_e32 v92, v146, v141
	v_fmac_f32_e32 v93, v146, v142
	v_fmac_f32_e32 v94, v146, v143
	v_fmac_f32_e32 v95, v146, v144
	v_cvt_pk_bf16_f32 v138, v92, v93
	v_cvt_pk_bf16_f32 v139, v94, v95
	s_mov_b64 s[26:27], s[86:87]
	s_mov_b64 s[28:29], s[88:89]
	s_mov_b64 s[86:87], s[12:13]
	s_mov_b64 s[88:89], s[14:15]
	s_mov_b32 s4, s83
	s_mov_b32 s5, s84
	s_add_u32 s7, s7, 1
	s_cmp_lt_u32 s7, 2
	s_cbranch_scc1 .Lat844_loop
	s_setprio 0
	global_store_dwordx2 v237, v[132:133], s[26:27]
	global_store_dwordx2 v237, v[134:135], s[26:27] offset:32
	global_store_dwordx2 v237, v[136:137], s[26:27] offset:64
	global_store_dwordx2 v237, v[138:139], s[26:27] offset:96
	s_mov_b64 s[90:91], exec
	s_mov_b64 exec, 0xffff
	global_store_dword v238, v140, s[28:29]
	s_mov_b64 exec, s[90:91]
	s_mov_b32 s67, 0x10000
	s_mov_b32 s68, 0x14000
	v_mov_b32_e32 v183, v239
	v_mov_b32_e32 v184, v240
	s_waitcnt vmcnt(0)
	s_barrier
	s_waitcnt vmcnt(0)
	s_barrier
	s_mov_b64 s[4:5], exec
	v_readlane_b32 s0, v252, 2
	v_readlane_b32 s30, v253, 24
	v_readlane_b32 s1, v252, 3
	v_readlane_b32 s31, v253, 25
	v_readlane_b32 s34, v253, 15
	v_readlane_b32 s36, v252, 27
	v_readlane_b32 s8, v253, 19
	v_readlane_b32 s10, v253, 21
	v_readlane_b32 s38, v252, 29
	v_readlane_b32 s60, v252, 31
	v_readlane_b32 s64, v252, 33
	v_readlane_b32 s70, v252, 35
	v_readlane_b32 s74, v252, 37
	s_and_b64 s[0:1], s[4:5], s[0:1]
	v_readlane_b32 s28, v253, 23
	v_readlane_b32 s35, v253, 16
	v_readlane_b32 s29, v252, 26
	v_readlane_b32 s31, v253, 18
	v_readlane_b32 s37, v252, 28
	v_readlane_b32 s9, v253, 20
	v_readlane_b32 s11, v253, 22
	v_readlane_b32 s39, v252, 30
	v_readlane_b32 s61, v252, 32
	v_readlane_b32 s65, v252, 34
	v_readlane_b32 s71, v252, 36
	v_readlane_b32 s75, v252, 38
	v_readlane_b32 s63, v253, 17
	s_mov_b64 exec, s[0:1]
	s_cbranch_execz .LBB0_916
	v_mov_b32_e32 v0, 0x20000
	ds_read_b64 v[0:1], v0
	s_getreg_b32 s44, hwreg(HW_REG_XCC_ID, 0, 4)
	s_lshl_b32 s44, s44, 7
	s_add_u32 s44, s44, 0xdc03600
	v_mov_b32_e32 v2, s44
	v_mov_b32_e32 v4, 1
	s_waitcnt vmcnt(0) lgkmcnt(0)
	global_atomic_add v5, v2, v4, s[42:43] sc0
	buffer_inv sc1
	s_add_u32 s100, s100, 1
	v_readfirstlane_b32 s46, v0
	v_readfirstlane_b32 s47, v1
	v_mov_b32_e32 v2, 0xdc03e00
	s_nop 3
	s_mul_i32 s48, s46, s100
	s_mul_i32 s49, s47, s100
	s_waitcnt vmcnt(1)
	v_readfirstlane_b32 s50, v5
	s_nop 3
	s_add_u32 s50, s50, 1
	s_cmp_lg_u32 s50, s48
	s_cbranch_scc1 .Lxb7_poll
	buffer_wbl2 sc1
	s_waitcnt vmcnt(0)
	global_atomic_add v2, v4, s[42:43]

.Lat991_i0_nopend:
	s_add_u32 s84, s5, s4
	s_xor_b32 s83, s4, 1
	s_mul_i32 s74, s84, 256
	s_lshl_b32 s75, s83, 7
	s_add_u32 s74, s74, s75
	s_lshl_b32 s75, s74, 7
	s_add_u32 s16, s60, s75
	s_addc_u32 s17, s61, 0
	s_lshl_b32 s75, s74, 1
	s_add_u32 s24, s64, s75
	s_addc_u32 s25, s65, 0
	s_add_u32 m0, s70, 0x4000
	s_nop 0
	global_load_lds_dwordx4 v232, s[16:17]
	s_add_u32 m0, s70, 0x6000
	s_nop 0
	global_load_lds_dwordx4 v233, s[16:17]
	s_add_u32 m0, s70, 0x14000
	s_nop 0
	global_load_lds_dwordx4 v234, s[24:25]
	s_add_u32 m0, s70, 0x16000
	s_nop 0
	global_load_lds_dwordx4 v235, s[24:25]
	s_lshl_b32 s74, s83, 11
	s_add_u32 s74, s74, s84
	s_lshl_b32 s75, s74, 7
	s_add_u32 s10, s30, s75
	s_addc_u32 s11, s31, 0
	s_add_u32 s12, s34, s75
	s_addc_u32 s13, s35, 0
	s_lshl_b32 s75, s74, 2
	s_add_u32 s14, s58, s75
	s_addc_u32 s15, s59, 0
	global_load_dwordx4 v[104:107], v236, s[10:11]
	global_load_dwordx4 v[108:111], v236, s[10:11] offset:64
	global_load_dwordx2 v[122:123], v237, s[12:13]
	global_load_dwordx2 v[124:125], v237, s[12:13] offset:32
	global_load_dwordx2 v[126:127], v237, s[12:13] offset:64
	global_load_dwordx2 v[128:129], v237, s[12:13] offset:96
	global_load_dword v121, v238, s[14:15]
	s_waitcnt lgkmcnt(0)
	v_mfma_f32_16x16x32_bf16 v[44:47], v[4:7], v[96:99], 0
	v_mfma_f32_16x16x32_bf16 v[48:51], v[12:15], v[96:99], 0
	v_mfma_f32_16x16x32_bf16 v[52:55], v[20:23], v[96:99], 0
	v_mfma_f32_16x16x32_bf16 v[56:59], v[28:31], v[96:99], 0
	v_mfma_f32_16x16x32_bf16 v[60:63], v[36:39], v[96:99], 0
	v_mfma_f32_16x16x32_bf16 v[44:47], v[8:11], v[100:103], v[44:47]
	v_mfma_f32_16x16x32_bf16 v[48:51], v[16:19], v[100:103], v[48:51]
	v_mfma_f32_16x16x32_bf16 v[52:55], v[24:27], v[100:103], v[52:55]
	v_mfma_f32_16x16x32_bf16 v[56:59], v[32:35], v[100:103], v[56:59]
	v_mfma_f32_16x16x32_bf16 v[60:63], v[40:43], v[100:103], v[60:63]
	s_cmp_gt_u32 s6, 5
	s_cselect_b32 s74, s77, s78
	v_add_u32_e32 v146, s74, v230
	v_xor_b32_e32 v147, 64, v146
	ds_read_b128 v[4:7], v146 offset:10240
	ds_read_b128 v[8:11], v147 offset:10240
	s_cmp_gt_u32 s6, 6
	s_cselect_b32 s74, s77, s78
	v_add_u32_e32 v146, s74, v230
	v_xor_b32_e32 v147, 64, v146
	ds_read_b128 v[12:15], v146 offset:12288
	ds_read_b128 v[16:19], v147 offset:12288
	s_cmp_gt_u32 s6, 7
	s_cselect_b32 s74, s77, s78
	v_add_u32_e32 v146, s74, v230
	v_xor_b32_e32 v147, 64, v146
	ds_read_b128 v[20:23], v146 offset:14336
	ds_read_b128 v[24:27], v147 offset:14336
	s_cmp_gt_u32 s6, 8
	s_cselect_b32 s74, s77, s78
	v_add_u32_e32 v146, s74, v230
	v_xor_b32_e32 v147, 64, v146
	ds_read_b128 v[28:31], v146 offset:16384
	ds_read_b128 v[32:35], v147 offset:16384
	s_nop 1
	v_fma_f32 v44, v44, s79, v185
	v_fma_f32 v45, v45, s79, v186
	v_fma_f32 v46, v46, s79, v187
	v_fma_f32 v47, v47, s79, v188
	v_fma_f32 v48, v48, s79, v189
	v_fma_f32 v49, v49, s79, v190
	s_waitcnt lgkmcnt(0)
	v_mfma_f32_16x16x32_bf16 v[64:67], v[4:7], v[96:99], 0
	v_fma_f32 v50, v50, s79, v191
	v_fma_f32 v51, v51, s79, v192
	v_mfma_f32_16x16x32_bf16 v[68:71], v[12:15], v[96:99], 0
	v_fma_f32 v52, v52, s79, v193
	v_fma_f32 v53, v53, s79, v194
	v_mfma_f32_16x16x32_bf16 v[72:75], v[20:23], v[96:99], 0
	v_fma_f32 v54, v54, s79, v195
	v_fma_f32 v55, v55, s79, v196
	v_mfma_f32_16x16x32_bf16 v[76:79], v[28:31], v[96:99], 0
	v_fma_f32 v56, v56, s79, v197
	v_fma_f32 v57, v57, s79, v198
	v_mfma_f32_16x16x32_bf16 v[64:67], v[8:11], v[100:103], v[64:67]
	v_fma_f32 v58, v58, s79, v199
	v_fma_f32 v59, v59, s79, v200
	v_mfma_f32_16x16x32_bf16 v[68:71], v[16:19], v[100:103], v[68:71]
	v_fma_f32 v60, v60, s79, v201
	v_fma_f32 v61, v61, s79, v202
	v_mfma_f32_16x16x32_bf16 v[72:75], v[24:27], v[100:103], v[72:75]
	v_fma_f32 v62, v62, s79, v203
	v_fma_f32 v63, v63, s79, v204
	v_mfma_f32_16x16x32_bf16 v[76:79], v[32:35], v[100:103], v[76:79]
	s_cmp_gt_u32 s6, 0
	s_cselect_b32 s74, 0, 0xffff0000
	v_add_u32_e32 v146, s74, v221
	ds_read_b64 v[4:5], v146 offset:49152
	ds_read_b64 v[8:9], v146 offset:53248
	ds_read_b64 v[12:13], v146 offset:57344
	ds_read_b64 v[16:17], v146 offset:61440
	s_cmp_gt_u32 s6, 1
	s_cselect_b32 s74, 0, 0xffff0000
	v_add_u32_e32 v146, s74, v222
	ds_read_b64 v[6:7], v146 offset:49152
	ds_read_b64 v[10:11], v146 offset:53248
	ds_read_b64 v[14:15], v146 offset:57344
	ds_read_b64 v[18:19], v146 offset:61440
	s_nop 1
	v_fma_f32 v64, v64, s79, v205
	v_fma_f32 v65, v65, s79, v206
	v_fma_f32 v66, v66, s79, v207
	v_fma_f32 v67, v67, s79, v208
	v_fma_f32 v68, v68, s79, v209
	v_fma_f32 v69, v69, s79, v210
	v_fma_f32 v70, v70, s79, v211
	v_fma_f32 v71, v71, s79, v212
	v_fma_f32 v72, v72, s79, v213
	v_fma_f32 v73, v73, s79, v214
	v_fma_f32 v74, v74, s79, v215
	v_fma_f32 v75, v75, s79, v216
	v_fma_f32 v76, v76, s79, v217
	v_fma_f32 v77, v77, s79, v218
	v_fma_f32 v78, v78, s79, v219
	v_fma_f32 v79, v79, s79, v220
	s_cmp_gt_u32 s6, 2
	s_cselect_b32 s74, 0, 0xffff0000
	v_add_u32_e32 v146, s74, v223
	ds_read_b64 v[20:21], v146 offset:49152
	ds_read_b64 v[24:25], v146 offset:53248
	ds_read_b64 v[28:29], v146 offset:57344
	ds_read_b64 v[32:33], v146 offset:61440
	s_cmp_gt_u32 s6, 3
	s_cselect_b32 s74, 0, 0xffff0000
	v_add_u32_e32 v146, s74, v224
	ds_read_b64 v[22:23], v146 offset:49152
	ds_read_b64 v[26:27], v146 offset:53248
	ds_read_b64 v[30:31], v146 offset:57344
	ds_read_b64 v[34:35], v146 offset:61440
	s_cmp_lg_u32 s4, 0
	s_cbranch_scc1 .Lat991_i0_nomask
	s_cmp_le_u32 s6, 0
	s_cbranch_scc1 .Lat991_i0_nomask
	v_mov_b32_e32 v44, v244
	v_mov_b32_e32 v45, v244
	v_mov_b32_e32 v46, v244
	v_mov_b32_e32 v47, v244
	s_cmp_le_u32 s6, 1
	s_cbranch_scc1 .Lat991_i0_nomask
	v_mov_b32_e32 v48, v244
	v_mov_b32_e32 v49, v244
	v_mov_b32_e32 v50, v244
	v_mov_b32_e32 v51, v244
	s_cmp_le_u32 s6, 2
	s_cbranch_scc1 .Lat991_i0_nomask
	v_mov_b32_e32 v52, v244
	v_mov_b32_e32 v53, v244
	v_mov_b32_e32 v54, v244
	v_mov_b32_e32 v55, v244
	s_cmp_le_u32 s6, 3
	s_cbranch_scc1 .Lat991_i0_nomask
	v_mov_b32_e32 v56, v244
	v_mov_b32_e32 v57, v244
	v_mov_b32_e32 v58, v244
	v_mov_b32_e32 v59, v244
	s_cmp_le_u32 s6, 4
	s_cbranch_scc1 .Lat991_i0_nomask
	v_mov_b32_e32 v60, v244
	v_mov_b32_e32 v61, v244
	v_mov_b32_e32 v62, v244
	v_mov_b32_e32 v63, v244
	s_cmp_le_u32 s6, 5
	s_cbranch_scc1 .Lat991_i0_nomask
	v_mov_b32_e32 v64, v244
	v_mov_b32_e32 v65, v244
	v_mov_b32_e32 v66, v244
	v_mov_b32_e32 v67, v244
	s_cmp_le_u32 s6, 6
	s_cbranch_scc1 .Lat991_i0_nomask
	v_mov_b32_e32 v68, v244
	v_mov_b32_e32 v69, v244
	v_mov_b32_e32 v70, v244
	v_mov_b32_e32 v71, v244
	s_cmp_le_u32 s6, 7
	s_cbranch_scc1 .Lat991_i0_nomask
	v_mov_b32_e32 v72, v244
	v_mov_b32_e32 v73, v244
	v_mov_b32_e32 v74, v244
	v_mov_b32_e32 v75, v244
.Lat991_i0_nomask:
	v_max3_f32 v245, v44, v45, v46
	v_max3_f32 v245, v245, v47, v48
	v_max3_f32 v245, v245, v49, v50
	v_max3_f32 v245, v245, v51, v52
	v_max3_f32 v245, v245, v53, v54
	v_max3_f32 v245, v245, v55, v56
	v_max3_f32 v245, v245, v57, v58
	v_max3_f32 v245, v245, v59, v60
	v_max3_f32 v245, v245, v61, v62
	v_max3_f32 v245, v245, v63, v64
	v_max3_f32 v245, v245, v65, v66
	v_max3_f32 v245, v245, v67, v68
	v_max3_f32 v245, v245, v69, v70
	v_max3_f32 v245, v245, v71, v72
	v_max3_f32 v245, v245, v73, v74
	v_max3_f32 v245, v245, v75, v76
	v_max3_f32 v245, v245, v77, v78
	v_max_f32_e32 v245, v245, v79
	ds_bpermute_b32 v148, v239, v245
	s_waitcnt lgkmcnt(0)
	v_max_f32_e32 v245, v245, v148
	ds_bpermute_b32 v148, v240, v245
	s_waitcnt lgkmcnt(0)
	v_max_f32_e32 v245, v245, v148
	v_sub_f32_e32 v44, v44, v245
	v_sub_f32_e32 v45, v45, v245
	v_sub_f32_e32 v46, v46, v245
	v_sub_f32_e32 v47, v47, v245
	v_exp_f32_e32 v44, v44
	v_exp_f32_e32 v45, v45
	v_exp_f32_e32 v46, v46
	v_exp_f32_e32 v47, v47
	v_sub_f32_e32 v48, v48, v245
	v_sub_f32_e32 v49, v49, v245
	v_sub_f32_e32 v50, v50, v245
	v_sub_f32_e32 v51, v51, v245
	v_exp_f32_e32 v48, v48
	v_exp_f32_e32 v49, v49
	v_exp_f32_e32 v50, v50
	v_exp_f32_e32 v51, v51
	v_mov_b32_e32 v149, v44
	v_mov_b32_e32 v150, v45
	v_mov_b32_e32 v151, v46
	v_mov_b32_e32 v152, v47
	v_cvt_pk_bf16_f32 v44, v44, v45
	v_cvt_pk_bf16_f32 v45, v46, v47
	v_sub_f32_e32 v52, v52, v245
	v_sub_f32_e32 v53, v53, v245
	v_sub_f32_e32 v54, v54, v245
	v_sub_f32_e32 v55, v55, v245
	v_exp_f32_e32 v52, v52
	v_exp_f32_e32 v53, v53
	v_exp_f32_e32 v54, v54
	v_exp_f32_e32 v55, v55
	v_add_f32_e32 v149, v149, v48
	v_add_f32_e32 v150, v150, v49
	v_add_f32_e32 v151, v151, v50
	v_add_f32_e32 v152, v152, v51
	v_cvt_pk_bf16_f32 v46, v48, v49
	v_cvt_pk_bf16_f32 v47, v50, v51
	s_waitcnt lgkmcnt(0)
	v_sub_f32_e32 v56, v56, v245
	v_sub_f32_e32 v57, v57, v245
	v_mfma_f32_16x16x32_bf16 v[80:83], v[4:7], v[44:47], 0
	v_sub_f32_e32 v58, v58, v245
	v_sub_f32_e32 v59, v59, v245
	v_exp_f32_e32 v56, v56
	v_mfma_f32_16x16x32_bf16 v[84:87], v[8:11], v[44:47], 0
	v_exp_f32_e32 v57, v57
	v_exp_f32_e32 v58, v58
	v_exp_f32_e32 v59, v59
	v_mfma_f32_16x16x32_bf16 v[88:91], v[12:15], v[44:47], 0
	v_add_f32_e32 v149, v149, v52
	v_add_f32_e32 v150, v150, v53
	v_add_f32_e32 v151, v151, v54
	v_mfma_f32_16x16x32_bf16 v[92:95], v[16:19], v[44:47], 0
	v_add_f32_e32 v152, v152, v55
	v_cvt_pk_bf16_f32 v52, v52, v53
	v_cvt_pk_bf16_f32 v53, v54, v55
	s_cmp_gt_u32 s6, 4
	s_cselect_b32 s74, 0, 0xffff0000
	v_add_u32_e32 v146, s74, v225
	ds_read_b64 v[4:5], v146 offset:49152
	ds_read_b64 v[8:9], v146 offset:53248
	ds_read_b64 v[12:13], v146 offset:57344
	ds_read_b64 v[16:17], v146 offset:61440
	s_cmp_gt_u32 s6, 5
	s_cselect_b32 s74, 0, 0xffff0000
	v_add_u32_e32 v146, s74, v226
	ds_read_b64 v[6:7], v146 offset:49152
	ds_read_b64 v[10:11], v146 offset:53248
	ds_read_b64 v[14:15], v146 offset:57344
	ds_read_b64 v[18:19], v146 offset:61440
	v_sub_f32_e32 v60, v60, v245
	v_sub_f32_e32 v61, v61, v245
	v_sub_f32_e32 v62, v62, v245
	v_sub_f32_e32 v63, v63, v245
	v_exp_f32_e32 v60, v60
	v_exp_f32_e32 v61, v61
	v_exp_f32_e32 v62, v62
	v_exp_f32_e32 v63, v63
	v_add_f32_e32 v149, v149, v56
	v_add_f32_e32 v150, v150, v57
	v_add_f32_e32 v151, v151, v58
	v_add_f32_e32 v152, v152, v59
	v_cvt_pk_bf16_f32 v54, v56, v57
	v_cvt_pk_bf16_f32 v55, v58, v59
	v_sub_f32_e32 v64, v64, v245
	v_sub_f32_e32 v65, v65, v245
	v_mfma_f32_16x16x32_bf16 v[80:83], v[20:23], v[52:55], v[80:83]
	v_sub_f32_e32 v66, v66, v245
	v_sub_f32_e32 v67, v67, v245
	v_exp_f32_e32 v64, v64
	v_mfma_f32_16x16x32_bf16 v[84:87], v[24:27], v[52:55], v[84:87]
	v_exp_f32_e32 v65, v65
	v_exp_f32_e32 v66, v66
	v_exp_f32_e32 v67, v67
	v_mfma_f32_16x16x32_bf16 v[88:91], v[28:31], v[52:55], v[88:91]
	v_add_f32_e32 v149, v149, v60
	v_add_f32_e32 v150, v150, v61
	v_add_f32_e32 v151, v151, v62
	v_mfma_f32_16x16x32_bf16 v[92:95], v[32:35], v[52:55], v[92:95]
	v_add_f32_e32 v152, v152, v63
	v_cvt_pk_bf16_f32 v60, v60, v61
	v_cvt_pk_bf16_f32 v61, v62, v63
	s_cmp_gt_u32 s6, 6
	s_cselect_b32 s74, 0, 0xffff0000
	v_add_u32_e32 v146, s74, v227
	ds_read_b64 v[20:21], v146 offset:49152
	ds_read_b64 v[24:25], v146 offset:53248
	ds_read_b64 v[28:29], v146 offset:57344
	ds_read_b64 v[32:33], v146 offset:61440
	s_cmp_gt_u32 s6, 7
	s_cselect_b32 s74, 0, 0xffff0000
	v_add_u32_e32 v146, s74, v228
	ds_read_b64 v[22:23], v146 offset:49152
	ds_read_b64 v[26:27], v146 offset:53248
	ds_read_b64 v[30:31], v146 offset:57344
	ds_read_b64 v[34:35], v146 offset:61440
	v_sub_f32_e32 v68, v68, v245
	v_sub_f32_e32 v69, v69, v245
	v_sub_f32_e32 v70, v70, v245
	v_sub_f32_e32 v71, v71, v245
	v_exp_f32_e32 v68, v68
	v_exp_f32_e32 v69, v69
	v_exp_f32_e32 v70, v70
	v_exp_f32_e32 v71, v71
	v_add_f32_e32 v149, v149, v64
	v_add_f32_e32 v150, v150, v65
	v_add_f32_e32 v151, v151, v66
	v_add_f32_e32 v152, v152, v67
	v_cvt_pk_bf16_f32 v62, v64, v65
	v_cvt_pk_bf16_f32 v63, v66, v67
	s_waitcnt lgkmcnt(8)
	v_sub_f32_e32 v72, v72, v245
	v_sub_f32_e32 v73, v73, v245
	v_mfma_f32_16x16x32_bf16 v[80:83], v[4:7], v[60:63], v[80:83]
	v_sub_f32_e32 v74, v74, v245
	v_sub_f32_e32 v75, v75, v245
	v_exp_f32_e32 v72, v72
	v_mfma_f32_16x16x32_bf16 v[84:87], v[8:11], v[60:63], v[84:87]
	v_exp_f32_e32 v73, v73
	v_exp_f32_e32 v74, v74
	v_exp_f32_e32 v75, v75
	v_mfma_f32_16x16x32_bf16 v[88:91], v[12:15], v[60:63], v[88:91]
	v_add_f32_e32 v149, v149, v68
	v_add_f32_e32 v150, v150, v69
	v_add_f32_e32 v151, v151, v70
	v_mfma_f32_16x16x32_bf16 v[92:95], v[16:19], v[60:63], v[92:95]
	v_add_f32_e32 v152, v152, v71
	v_cvt_pk_bf16_f32 v68, v68, v69
	v_cvt_pk_bf16_f32 v69, v70, v71
	s_cmp_gt_u32 s6, 8
	s_cselect_b32 s74, 0, 0xffff0000
	v_add_u32_e32 v146, s74, v229
	ds_read_b64 v[4:5], v146 offset:49152
	ds_read_b64 v[8:9], v146 offset:53248
	ds_read_b64 v[12:13], v146 offset:57344
	ds_read_b64 v[16:17], v146 offset:61440
	v_mov_b32_e32 v6, 0
	v_mov_b32_e32 v7, 0
	v_mov_b32_e32 v10, 0
	v_mov_b32_e32 v11, 0
	v_mov_b32_e32 v14, 0
	v_mov_b32_e32 v15, 0
	v_mov_b32_e32 v18, 0
	v_mov_b32_e32 v19, 0
	v_sub_f32_e32 v76, v76, v245
	v_sub_f32_e32 v77, v77, v245
	v_sub_f32_e32 v78, v78, v245
	v_sub_f32_e32 v79, v79, v245
	v_exp_f32_e32 v76, v76
	v_exp_f32_e32 v77, v77
	v_exp_f32_e32 v78, v78
	v_exp_f32_e32 v79, v79
	v_add_f32_e32 v149, v149, v72
	v_add_f32_e32 v150, v150, v73
	v_add_f32_e32 v151, v151, v74
	v_add_f32_e32 v152, v152, v75
	v_cvt_pk_bf16_f32 v70, v72, v73
	v_cvt_pk_bf16_f32 v71, v74, v75
	s_waitcnt lgkmcnt(4)
	v_add_f32_e32 v149, v149, v76
	v_add_f32_e32 v150, v150, v77
	v_mfma_f32_16x16x32_bf16 v[80:83], v[20:23], v[68:71], v[80:83]
	v_add_f32_e32 v151, v151, v78
	v_add_f32_e32 v152, v152, v79
	v_mfma_f32_16x16x32_bf16 v[84:87], v[24:27], v[68:71], v[84:87]
	v_cvt_pk_bf16_f32 v76, v76, v77
	v_cvt_pk_bf16_f32 v77, v78, v79
	v_mfma_f32_16x16x32_bf16 v[88:91], v[28:31], v[68:71], v[88:91]
	v_mov_b32_e32 v78, 0
	v_mov_b32_e32 v79, 0
	v_mfma_f32_16x16x32_bf16 v[92:95], v[32:35], v[68:71], v[92:95]
	v_add_f32_e32 v149, v149, v150
	v_add_f32_e32 v151, v151, v152
	v_add_f32_e32 v246, v149, v151
	ds_bpermute_b32 v148, v239, v246
	s_waitcnt lgkmcnt(1)
	v_mfma_f32_16x16x32_bf16 v[80:83], v[4:7], v[76:79], v[80:83]
	v_mfma_f32_16x16x32_bf16 v[84:87], v[8:11], v[76:79], v[84:87]
	v_mfma_f32_16x16x32_bf16 v[88:91], v[12:15], v[76:79], v[88:91]
	v_mfma_f32_16x16x32_bf16 v[92:95], v[16:19], v[76:79], v[92:95]
	s_waitcnt lgkmcnt(0)
	v_add_f32_e32 v246, v246, v148
	ds_bpermute_b32 v148, v240, v246
	s_waitcnt lgkmcnt(0)
	v_add_f32_e32 v246, v246, v148
	v_rcp_f32_e32 v149, v246
	v_log_f32_e32 v150, v246
	s_nop 0
	v_add_f32_e32 v151, v245, v150
	v_mul_f32_e32 v151, 0x3f317218, v151
	v_max_f32_e32 v152, v120, v151
	v_sub_f32_e32 v153, v120, v152
	v_sub_f32_e32 v154, v151, v152
	v_mul_f32_e32 v153, 0x3fb8aa3b, v153
	v_mul_f32_e32 v154, 0x3fb8aa3b, v154
	v_exp_f32_e32 v153, v153
	v_exp_f32_e32 v154, v154
	s_nop 0
	v_add_f32_e32 v155, v153, v154
	v_rcp_f32_e32 v146, v155
	v_log_f32_e32 v150, v155
	s_nop 0
	v_mul_f32_e32 v154, v154, v146
	v_mul_f32_e32 v146, v153, v146
	v_mul_f32_e32 v147, v149, v154
	v_mul_f32_e32 v150, 0x3f317218, v150
	v_add_f32_e32 v140, v152, v150
	v_mul_f32_e32 v80, v80, v147
	v_mul_f32_e32 v81, v81, v147
	v_mul_f32_e32 v82, v82, v147
	v_mul_f32_e32 v83, v83, v147
	v_mul_f32_e32 v84, v84, v147
	v_mul_f32_e32 v85, v85, v147
	v_mul_f32_e32 v86, v86, v147
	v_mul_f32_e32 v87, v87, v147
	v_mul_f32_e32 v88, v88, v147
	v_mul_f32_e32 v89, v89, v147
	v_mul_f32_e32 v90, v90, v147
	v_mul_f32_e32 v91, v91, v147
	v_mul_f32_e32 v92, v92, v147
	v_mul_f32_e32 v93, v93, v147
	v_mul_f32_e32 v94, v94, v147
	v_mul_f32_e32 v95, v95, v147
	v_lshlrev_b32_e32 v141, 16, v112
	v_and_b32_e32 v142, 0xffff0000, v112
	v_lshlrev_b32_e32 v143, 16, v113
	v_and_b32_e32 v144, 0xffff0000, v113
	v_fmac_f32_e32 v80, v146, v141
	v_fmac_f32_e32 v81, v146, v142
	v_fmac_f32_e32 v82, v146, v143
	v_fmac_f32_e32 v83, v146, v144
	v_cvt_pk_bf16_f32 v132, v80, v81
	v_cvt_pk_bf16_f32 v133, v82, v83
	v_lshlrev_b32_e32 v141, 16, v114
	v_and_b32_e32 v142, 0xffff0000, v114
	v_lshlrev_b32_e32 v143, 16, v115
	v_and_b32_e32 v144, 0xffff0000, v115
	v_fmac_f32_e32 v84, v146, v141
	v_fmac_f32_e32 v85, v146, v142
	v_fmac_f32_e32 v86, v146, v143
	v_fmac_f32_e32 v87, v146, v144
	v_cvt_pk_bf16_f32 v134, v84, v85
	v_cvt_pk_bf16_f32 v135, v86, v87
	v_lshlrev_b32_e32 v141, 16, v116
	v_and_b32_e32 v142, 0xffff0000, v116
	v_lshlrev_b32_e32 v143, 16, v117
	v_and_b32_e32 v144, 0xffff0000, v117
	v_fmac_f32_e32 v88, v146, v141
	v_fmac_f32_e32 v89, v146, v142
	v_fmac_f32_e32 v90, v146, v143
	v_fmac_f32_e32 v91, v146, v144
	v_cvt_pk_bf16_f32 v136, v88, v89
	v_cvt_pk_bf16_f32 v137, v90, v91
	v_lshlrev_b32_e32 v141, 16, v118
	v_and_b32_e32 v142, 0xffff0000, v118
	v_lshlrev_b32_e32 v143, 16, v119
	v_and_b32_e32 v144, 0xffff0000, v119
	v_fmac_f32_e32 v92, v146, v141
	v_fmac_f32_e32 v93, v146, v142
	v_fmac_f32_e32 v94, v146, v143
	v_fmac_f32_e32 v95, v146, v144
	v_cvt_pk_bf16_f32 v138, v92, v93
	v_cvt_pk_bf16_f32 v139, v94, v95
	s_mov_b64 s[26:27], s[86:87]
	s_mov_b64 s[28:29], s[88:89]
	s_mov_b64 s[86:87], s[12:13]
	s_mov_b64 s[88:89], s[14:15]
	s_mov_b32 s4, s83
	s_mov_b32 s5, s84
	s_waitcnt vmcnt(0)
	s_barrier
	ds_read_b128 v[4:7], v230 offset:0
	ds_read_b128 v[8:11], v231 offset:0
	ds_read_b128 v[12:15], v230 offset:2048
	ds_read_b128 v[16:19], v231 offset:2048
	ds_read_b128 v[20:23], v230 offset:4096
	ds_read_b128 v[24:27], v231 offset:4096
	ds_read_b128 v[28:31], v230 offset:6144
	ds_read_b128 v[32:35], v231 offset:6144
	ds_read_b128 v[36:39], v230 offset:8192
	ds_read_b128 v[40:43], v231 offset:8192
	global_store_dwordx2 v237, v[132:133], s[26:27]
	global_store_dwordx2 v237, v[134:135], s[26:27] offset:32
	global_store_dwordx2 v237, v[136:137], s[26:27] offset:64
	global_store_dwordx2 v237, v[138:139], s[26:27] offset:96
	s_mov_b64 s[90:91], exec
	s_mov_b64 exec, 0xffff
	global_store_dword v238, v140, s[28:29]
	s_mov_b64 exec, s[90:91]
	s_add_u32 s84, s5, s4
	s_xor_b32 s83, s4, 1
	s_mul_i32 s74, s84, 256
	s_lshl_b32 s75, s83, 7
	s_add_u32 s74, s74, s75
	s_lshl_b32 s75, s74, 7
	s_add_u32 s16, s60, s75
	s_addc_u32 s17, s61, 0
	s_lshl_b32 s75, s74, 1
	s_add_u32 s24, s64, s75
	s_addc_u32 s25, s65, 0
	s_add_u32 m0, s70, 0x8000
	s_nop 0
	global_load_lds_dwordx4 v232, s[16:17]
	s_add_u32 m0, s70, 0xa000
	s_nop 0
	global_load_lds_dwordx4 v233, s[16:17]
	s_add_u32 m0, s70, 0x18000
	s_nop 0
	global_load_lds_dwordx4 v234, s[24:25]
	s_add_u32 m0, s70, 0x1a000
	s_nop 0
	global_load_lds_dwordx4 v235, s[24:25]
	s_lshl_b32 s74, s83, 11
	s_add_u32 s74, s74, s84
	s_lshl_b32 s75, s74, 7
	s_add_u32 s10, s30, s75
	s_addc_u32 s11, s31, 0
	s_add_u32 s12, s34, s75
	s_addc_u32 s13, s35, 0
	s_lshl_b32 s75, s74, 2
	s_add_u32 s14, s58, s75
	s_addc_u32 s15, s59, 0
	global_load_dwordx4 v[96:99], v236, s[10:11]
	global_load_dwordx4 v[100:103], v236, s[10:11] offset:64
	global_load_dwordx2 v[112:113], v237, s[12:13]
	global_load_dwordx2 v[114:115], v237, s[12:13] offset:32
	global_load_dwordx2 v[116:117], v237, s[12:13] offset:64
	global_load_dwordx2 v[118:119], v237, s[12:13] offset:96
	global_load_dword v120, v238, s[14:15]
	s_waitcnt lgkmcnt(0)
	v_mfma_f32_16x16x32_bf16 v[44:47], v[4:7], v[104:107], 0
	v_mfma_f32_16x16x32_bf16 v[48:51], v[12:15], v[104:107], 0
	v_mfma_f32_16x16x32_bf16 v[52:55], v[20:23], v[104:107], 0
	v_mfma_f32_16x16x32_bf16 v[56:59], v[28:31], v[104:107], 0
	v_mfma_f32_16x16x32_bf16 v[60:63], v[36:39], v[104:107], 0
	v_mfma_f32_16x16x32_bf16 v[44:47], v[8:11], v[108:111], v[44:47]
	v_mfma_f32_16x16x32_bf16 v[48:51], v[16:19], v[108:111], v[48:51]
	v_mfma_f32_16x16x32_bf16 v[52:55], v[24:27], v[108:111], v[52:55]
	v_mfma_f32_16x16x32_bf16 v[56:59], v[32:35], v[108:111], v[56:59]
	v_mfma_f32_16x16x32_bf16 v[60:63], v[40:43], v[108:111], v[60:63]
	ds_read_b128 v[4:7], v230 offset:10240
	ds_read_b128 v[8:11], v231 offset:10240
	ds_read_b128 v[12:15], v230 offset:12288
	ds_read_b128 v[16:19], v231 offset:12288
	ds_read_b128 v[20:23], v230 offset:14336
	ds_read_b128 v[24:27], v231 offset:14336
	ds_read_b128 v[28:31], v230 offset:16384
	ds_read_b128 v[32:35], v231 offset:16384
	s_nop 1
	v_fma_f32 v44, v44, s79, v185
	v_fma_f32 v45, v45, s79, v186
	v_fma_f32 v46, v46, s79, v187
	v_fma_f32 v47, v47, s79, v188
	v_fma_f32 v48, v48, s79, v189
	v_fma_f32 v49, v49, s79, v190
	s_waitcnt lgkmcnt(0)
	v_mfma_f32_16x16x32_bf16 v[64:67], v[4:7], v[104:107], 0
	v_fma_f32 v50, v50, s79, v191
	v_fma_f32 v51, v51, s79, v192
	v_mfma_f32_16x16x32_bf16 v[68:71], v[12:15], v[104:107], 0
	v_fma_f32 v52, v52, s79, v193
	v_fma_f32 v53, v53, s79, v194
	v_mfma_f32_16x16x32_bf16 v[72:75], v[20:23], v[104:107], 0
	v_fma_f32 v54, v54, s79, v195
	v_fma_f32 v55, v55, s79, v196
	v_mfma_f32_16x16x32_bf16 v[76:79], v[28:31], v[104:107], 0
	v_fma_f32 v56, v56, s79, v197
	v_fma_f32 v57, v57, s79, v198
	v_mfma_f32_16x16x32_bf16 v[64:67], v[8:11], v[108:111], v[64:67]
	v_fma_f32 v58, v58, s79, v199
	v_fma_f32 v59, v59, s79, v200
	v_mfma_f32_16x16x32_bf16 v[68:71], v[16:19], v[108:111], v[68:71]
	v_fma_f32 v60, v60, s79, v201
	v_fma_f32 v61, v61, s79, v202
	v_mfma_f32_16x16x32_bf16 v[72:75], v[24:27], v[108:111], v[72:75]
	v_fma_f32 v62, v62, s79, v203
	v_fma_f32 v63, v63, s79, v204
	v_mfma_f32_16x16x32_bf16 v[76:79], v[32:35], v[108:111], v[76:79]
	ds_read_b64 v[4:5], v221 offset:0
	ds_read_b64 v[8:9], v221 offset:4096
	ds_read_b64 v[12:13], v221 offset:8192
	ds_read_b64 v[16:17], v221 offset:12288
	ds_read_b64 v[6:7], v222 offset:0
	ds_read_b64 v[10:11], v222 offset:4096
	ds_read_b64 v[14:15], v222 offset:8192
	ds_read_b64 v[18:19], v222 offset:12288
	s_nop 1
	v_fma_f32 v64, v64, s79, v205
	v_fma_f32 v65, v65, s79, v206
	v_fma_f32 v66, v66, s79, v207
	v_fma_f32 v67, v67, s79, v208
	v_fma_f32 v68, v68, s79, v209
	v_fma_f32 v69, v69, s79, v210
	v_fma_f32 v70, v70, s79, v211
	v_fma_f32 v71, v71, s79, v212
	v_fma_f32 v72, v72, s79, v213
	v_fma_f32 v73, v73, s79, v214
	v_fma_f32 v74, v74, s79, v215
	v_fma_f32 v75, v75, s79, v216
	v_fma_f32 v76, v76, s79, v217
	v_fma_f32 v77, v77, s79, v218
	v_fma_f32 v78, v78, s79, v219
	v_fma_f32 v79, v79, s79, v220
	ds_read_b64 v[20:21], v223 offset:0
	ds_read_b64 v[24:25], v223 offset:4096
	ds_read_b64 v[28:29], v223 offset:8192
	ds_read_b64 v[32:33], v223 offset:12288
	ds_read_b64 v[22:23], v224 offset:0
	ds_read_b64 v[26:27], v224 offset:4096
	ds_read_b64 v[30:31], v224 offset:8192
	ds_read_b64 v[34:35], v224 offset:12288
	s_cmp_lg_u32 s4, 0
	s_cbranch_scc1 .Lat991_i1_nomask
	s_cmp_le_u32 s6, 0
	s_cbranch_scc1 .Lat991_i1_nomask
	v_mov_b32_e32 v44, v244
	v_mov_b32_e32 v45, v244
	v_mov_b32_e32 v46, v244
	v_mov_b32_e32 v47, v244
	s_cmp_le_u32 s6, 1
	s_cbranch_scc1 .Lat991_i1_nomask
	v_mov_b32_e32 v48, v244
	v_mov_b32_e32 v49, v244
	v_mov_b32_e32 v50, v244
	v_mov_b32_e32 v51, v244
	s_cmp_le_u32 s6, 2
	s_cbranch_scc1 .Lat991_i1_nomask
	v_mov_b32_e32 v52, v244
	v_mov_b32_e32 v53, v244
	v_mov_b32_e32 v54, v244
	v_mov_b32_e32 v55, v244
	s_cmp_le_u32 s6, 3
	s_cbranch_scc1 .Lat991_i1_nomask
	v_mov_b32_e32 v56, v244
	v_mov_b32_e32 v57, v244
	v_mov_b32_e32 v58, v244
	v_mov_b32_e32 v59, v244
	s_cmp_le_u32 s6, 4
	s_cbranch_scc1 .Lat991_i1_nomask
	v_mov_b32_e32 v60, v244
	v_mov_b32_e32 v61, v244
	v_mov_b32_e32 v62, v244
	v_mov_b32_e32 v63, v244
	s_cmp_le_u32 s6, 5
	s_cbranch_scc1 .Lat991_i1_nomask
	v_mov_b32_e32 v64, v244
	v_mov_b32_e32 v65, v244
	v_mov_b32_e32 v66, v244
	v_mov_b32_e32 v67, v244
	s_cmp_le_u32 s6, 6
	s_cbranch_scc1 .Lat991_i1_nomask
	v_mov_b32_e32 v68, v244
	v_mov_b32_e32 v69, v244
	v_mov_b32_e32 v70, v244
	v_mov_b32_e32 v71, v244
	s_cmp_le_u32 s6, 7
	s_cbranch_scc1 .Lat991_i1_nomask
	v_mov_b32_e32 v72, v244
	v_mov_b32_e32 v73, v244
	v_mov_b32_e32 v74, v244
	v_mov_b32_e32 v75, v244
.Lat991_i1_nomask:
	v_max3_f32 v245, v44, v45, v46
	v_max3_f32 v245, v245, v47, v48
	v_max3_f32 v245, v245, v49, v50
	v_max3_f32 v245, v245, v51, v52
	v_max3_f32 v245, v245, v53, v54
	v_max3_f32 v245, v245, v55, v56
	v_max3_f32 v245, v245, v57, v58
	v_max3_f32 v245, v245, v59, v60
	v_max3_f32 v245, v245, v61, v62
	v_max3_f32 v245, v245, v63, v64
	v_max3_f32 v245, v245, v65, v66
	v_max3_f32 v245, v245, v67, v68
	v_max3_f32 v245, v245, v69, v70
	v_max3_f32 v245, v245, v71, v72
	v_max3_f32 v245, v245, v73, v74
	v_max3_f32 v245, v245, v75, v76
	v_max3_f32 v245, v245, v77, v78
	v_max_f32_e32 v245, v245, v79
	ds_bpermute_b32 v148, v239, v245
	s_waitcnt lgkmcnt(0)
	v_max_f32_e32 v245, v245, v148
	ds_bpermute_b32 v148, v240, v245
	s_waitcnt lgkmcnt(0)
	v_max_f32_e32 v245, v245, v148
	v_sub_f32_e32 v44, v44, v245
	v_sub_f32_e32 v45, v45, v245
	v_sub_f32_e32 v46, v46, v245
	v_sub_f32_e32 v47, v47, v245
	v_exp_f32_e32 v44, v44
	v_exp_f32_e32 v45, v45
	v_exp_f32_e32 v46, v46
	v_exp_f32_e32 v47, v47
	v_sub_f32_e32 v48, v48, v245
	v_sub_f32_e32 v49, v49, v245
	v_sub_f32_e32 v50, v50, v245
	v_sub_f32_e32 v51, v51, v245
	v_exp_f32_e32 v48, v48
	v_exp_f32_e32 v49, v49
	v_exp_f32_e32 v50, v50
	v_exp_f32_e32 v51, v51
	v_mov_b32_e32 v149, v44
	v_mov_b32_e32 v150, v45
	v_mov_b32_e32 v151, v46
	v_mov_b32_e32 v152, v47
	v_cvt_pk_bf16_f32 v44, v44, v45
	v_cvt_pk_bf16_f32 v45, v46, v47
	v_sub_f32_e32 v52, v52, v245
	v_sub_f32_e32 v53, v53, v245
	v_sub_f32_e32 v54, v54, v245
	v_sub_f32_e32 v55, v55, v245
	v_exp_f32_e32 v52, v52
	v_exp_f32_e32 v53, v53
	v_exp_f32_e32 v54, v54
	v_exp_f32_e32 v55, v55
	v_add_f32_e32 v149, v149, v48
	v_add_f32_e32 v150, v150, v49
	v_add_f32_e32 v151, v151, v50
	v_add_f32_e32 v152, v152, v51
	v_cvt_pk_bf16_f32 v46, v48, v49
	v_cvt_pk_bf16_f32 v47, v50, v51
	s_waitcnt lgkmcnt(0)
	v_sub_f32_e32 v56, v56, v245
	v_sub_f32_e32 v57, v57, v245
	v_mfma_f32_16x16x32_bf16 v[80:83], v[4:7], v[44:47], 0
	v_sub_f32_e32 v58, v58, v245
	v_sub_f32_e32 v59, v59, v245
	v_exp_f32_e32 v56, v56
	v_mfma_f32_16x16x32_bf16 v[84:87], v[8:11], v[44:47], 0
	v_exp_f32_e32 v57, v57
	v_exp_f32_e32 v58, v58
	v_exp_f32_e32 v59, v59
	v_mfma_f32_16x16x32_bf16 v[88:91], v[12:15], v[44:47], 0
	v_add_f32_e32 v149, v149, v52
	v_add_f32_e32 v150, v150, v53
	v_add_f32_e32 v151, v151, v54
	v_mfma_f32_16x16x32_bf16 v[92:95], v[16:19], v[44:47], 0
	v_add_f32_e32 v152, v152, v55
	v_cvt_pk_bf16_f32 v52, v52, v53
	v_cvt_pk_bf16_f32 v53, v54, v55
	ds_read_b64 v[4:5], v225 offset:0
	ds_read_b64 v[8:9], v225 offset:4096
	ds_read_b64 v[12:13], v225 offset:8192
	ds_read_b64 v[16:17], v225 offset:12288
	ds_read_b64 v[6:7], v226 offset:0
	ds_read_b64 v[10:11], v226 offset:4096
	ds_read_b64 v[14:15], v226 offset:8192
	ds_read_b64 v[18:19], v226 offset:12288
	v_sub_f32_e32 v60, v60, v245
	v_sub_f32_e32 v61, v61, v245
	v_sub_f32_e32 v62, v62, v245
	v_sub_f32_e32 v63, v63, v245
	v_exp_f32_e32 v60, v60
	v_exp_f32_e32 v61, v61
	v_exp_f32_e32 v62, v62
	v_exp_f32_e32 v63, v63
	v_add_f32_e32 v149, v149, v56
	v_add_f32_e32 v150, v150, v57
	v_add_f32_e32 v151, v151, v58
	v_add_f32_e32 v152, v152, v59
	v_cvt_pk_bf16_f32 v54, v56, v57
	v_cvt_pk_bf16_f32 v55, v58, v59
	v_sub_f32_e32 v64, v64, v245
	v_sub_f32_e32 v65, v65, v245
	v_mfma_f32_16x16x32_bf16 v[80:83], v[20:23], v[52:55], v[80:83]
	v_sub_f32_e32 v66, v66, v245
	v_sub_f32_e32 v67, v67, v245
	v_exp_f32_e32 v64, v64
	v_mfma_f32_16x16x32_bf16 v[84:87], v[24:27], v[52:55], v[84:87]
	v_exp_f32_e32 v65, v65
	v_exp_f32_e32 v66, v66
	v_exp_f32_e32 v67, v67
	v_mfma_f32_16x16x32_bf16 v[88:91], v[28:31], v[52:55], v[88:91]
	v_add_f32_e32 v149, v149, v60
	v_add_f32_e32 v150, v150, v61
	v_add_f32_e32 v151, v151, v62
	v_mfma_f32_16x16x32_bf16 v[92:95], v[32:35], v[52:55], v[92:95]
	v_add_f32_e32 v152, v152, v63
	v_cvt_pk_bf16_f32 v60, v60, v61
	v_cvt_pk_bf16_f32 v61, v62, v63
	ds_read_b64 v[20:21], v227 offset:0
	ds_read_b64 v[24:25], v227 offset:4096
	ds_read_b64 v[28:29], v227 offset:8192
	ds_read_b64 v[32:33], v227 offset:12288
	ds_read_b64 v[22:23], v228 offset:0
	ds_read_b64 v[26:27], v228 offset:4096
	ds_read_b64 v[30:31], v228 offset:8192
	ds_read_b64 v[34:35], v228 offset:12288
	v_sub_f32_e32 v68, v68, v245
	v_sub_f32_e32 v69, v69, v245
	v_sub_f32_e32 v70, v70, v245
	v_sub_f32_e32 v71, v71, v245
	v_exp_f32_e32 v68, v68
	v_exp_f32_e32 v69, v69
	v_exp_f32_e32 v70, v70
	v_exp_f32_e32 v71, v71
	v_add_f32_e32 v149, v149, v64
	v_add_f32_e32 v150, v150, v65
	v_add_f32_e32 v151, v151, v66
	v_add_f32_e32 v152, v152, v67
	v_cvt_pk_bf16_f32 v62, v64, v65
	v_cvt_pk_bf16_f32 v63, v66, v67
	s_waitcnt lgkmcnt(8)
	v_sub_f32_e32 v72, v72, v245
	v_sub_f32_e32 v73, v73, v245
	v_mfma_f32_16x16x32_bf16 v[80:83], v[4:7], v[60:63], v[80:83]
	v_sub_f32_e32 v74, v74, v245
	v_sub_f32_e32 v75, v75, v245
	v_exp_f32_e32 v72, v72
	v_mfma_f32_16x16x32_bf16 v[84:87], v[8:11], v[60:63], v[84:87]
	v_exp_f32_e32 v73, v73
	v_exp_f32_e32 v74, v74
	v_exp_f32_e32 v75, v75
	v_mfma_f32_16x16x32_bf16 v[88:91], v[12:15], v[60:63], v[88:91]
	v_add_f32_e32 v149, v149, v68
	v_add_f32_e32 v150, v150, v69
	v_add_f32_e32 v151, v151, v70
	v_mfma_f32_16x16x32_bf16 v[92:95], v[16:19], v[60:63], v[92:95]
	v_add_f32_e32 v152, v152, v71
	v_cvt_pk_bf16_f32 v68, v68, v69
	v_cvt_pk_bf16_f32 v69, v70, v71
	ds_read_b64 v[4:5], v229 offset:0
	ds_read_b64 v[8:9], v229 offset:4096
	ds_read_b64 v[12:13], v229 offset:8192
	ds_read_b64 v[16:17], v229 offset:12288
	v_mov_b32_e32 v6, 0
	v_mov_b32_e32 v7, 0
	v_mov_b32_e32 v10, 0
	v_mov_b32_e32 v11, 0
	v_mov_b32_e32 v14, 0
	v_mov_b32_e32 v15, 0
	v_mov_b32_e32 v18, 0
	v_mov_b32_e32 v19, 0
	v_sub_f32_e32 v76, v76, v245
	v_sub_f32_e32 v77, v77, v245
	v_sub_f32_e32 v78, v78, v245
	v_sub_f32_e32 v79, v79, v245
	v_exp_f32_e32 v76, v76
	v_exp_f32_e32 v77, v77
	v_exp_f32_e32 v78, v78
	v_exp_f32_e32 v79, v79
	v_add_f32_e32 v149, v149, v72
	v_add_f32_e32 v150, v150, v73
	v_add_f32_e32 v151, v151, v74
	v_add_f32_e32 v152, v152, v75
	v_cvt_pk_bf16_f32 v70, v72, v73
	v_cvt_pk_bf16_f32 v71, v74, v75
	s_waitcnt lgkmcnt(4)
	v_add_f32_e32 v149, v149, v76
	v_add_f32_e32 v150, v150, v77
	v_mfma_f32_16x16x32_bf16 v[80:83], v[20:23], v[68:71], v[80:83]
	v_add_f32_e32 v151, v151, v78
	v_add_f32_e32 v152, v152, v79
	v_mfma_f32_16x16x32_bf16 v[84:87], v[24:27], v[68:71], v[84:87]
	v_cvt_pk_bf16_f32 v76, v76, v77
	v_cvt_pk_bf16_f32 v77, v78, v79
	v_mfma_f32_16x16x32_bf16 v[88:91], v[28:31], v[68:71], v[88:91]
	v_mov_b32_e32 v78, 0
	v_mov_b32_e32 v79, 0
	v_mfma_f32_16x16x32_bf16 v[92:95], v[32:35], v[68:71], v[92:95]
	v_add_f32_e32 v149, v149, v150
	v_add_f32_e32 v151, v151, v152
	v_add_f32_e32 v246, v149, v151
	ds_bpermute_b32 v148, v239, v246
	s_waitcnt lgkmcnt(1)
	v_mfma_f32_16x16x32_bf16 v[80:83], v[4:7], v[76:79], v[80:83]
	v_mfma_f32_16x16x32_bf16 v[84:87], v[8:11], v[76:79], v[84:87]
	v_mfma_f32_16x16x32_bf16 v[88:91], v[12:15], v[76:79], v[88:91]
	v_mfma_f32_16x16x32_bf16 v[92:95], v[16:19], v[76:79], v[92:95]
	s_waitcnt lgkmcnt(0)
	v_add_f32_e32 v246, v246, v148
	ds_bpermute_b32 v148, v240, v246
	s_waitcnt lgkmcnt(0)
	v_add_f32_e32 v246, v246, v148
	v_rcp_f32_e32 v149, v246
	v_log_f32_e32 v150, v246
	s_nop 0
	v_add_f32_e32 v151, v245, v150
	v_mul_f32_e32 v151, 0x3f317218, v151
	v_max_f32_e32 v152, v121, v151
	v_sub_f32_e32 v153, v121, v152
	v_sub_f32_e32 v154, v151, v152
	v_mul_f32_e32 v153, 0x3fb8aa3b, v153
	v_mul_f32_e32 v154, 0x3fb8aa3b, v154
	v_exp_f32_e32 v153, v153
	v_exp_f32_e32 v154, v154
	s_nop 0
	v_add_f32_e32 v155, v153, v154
	v_rcp_f32_e32 v146, v155
	v_log_f32_e32 v150, v155
	s_nop 0
	v_mul_f32_e32 v154, v154, v146
	v_mul_f32_e32 v146, v153, v146
	v_mul_f32_e32 v147, v149, v154
	v_mul_f32_e32 v150, 0x3f317218, v150
	v_add_f32_e32 v140, v152, v150
	v_mul_f32_e32 v80, v80, v147
	v_mul_f32_e32 v81, v81, v147
	v_mul_f32_e32 v82, v82, v147
	v_mul_f32_e32 v83, v83, v147
	v_mul_f32_e32 v84, v84, v147
	v_mul_f32_e32 v85, v85, v147
	v_mul_f32_e32 v86, v86, v147
	v_mul_f32_e32 v87, v87, v147
	v_mul_f32_e32 v88, v88, v147
	v_mul_f32_e32 v89, v89, v147
	v_mul_f32_e32 v90, v90, v147
	v_mul_f32_e32 v91, v91, v147
	v_mul_f32_e32 v92, v92, v147
	v_mul_f32_e32 v93, v93, v147
	v_mul_f32_e32 v94, v94, v147
	v_mul_f32_e32 v95, v95, v147
	v_lshlrev_b32_e32 v141, 16, v122
	v_and_b32_e32 v142, 0xffff0000, v122
	v_lshlrev_b32_e32 v143, 16, v123
	v_and_b32_e32 v144, 0xffff0000, v123
	v_fmac_f32_e32 v80, v146, v141
	v_fmac_f32_e32 v81, v146, v142
	v_fmac_f32_e32 v82, v146, v143
	v_fmac_f32_e32 v83, v146, v144
	v_cvt_pk_bf16_f32 v132, v80, v81
	v_cvt_pk_bf16_f32 v133, v82, v83
	v_lshlrev_b32_e32 v141, 16, v124
	v_and_b32_e32 v142, 0xffff0000, v124
	v_lshlrev_b32_e32 v143, 16, v125
	v_and_b32_e32 v144, 0xffff0000, v125
	v_fmac_f32_e32 v84, v146, v141
	v_fmac_f32_e32 v85, v146, v142
	v_fmac_f32_e32 v86, v146, v143
	v_fmac_f32_e32 v87, v146, v144
	v_cvt_pk_bf16_f32 v134, v84, v85
	v_cvt_pk_bf16_f32 v135, v86, v87
	v_lshlrev_b32_e32 v141, 16, v126
	v_and_b32_e32 v142, 0xffff0000, v126
	v_lshlrev_b32_e32 v143, 16, v127
	v_and_b32_e32 v144, 0xffff0000, v127
	v_fmac_f32_e32 v88, v146, v141
	v_fmac_f32_e32 v89, v146, v142
	v_fmac_f32_e32 v90, v146, v143
	v_fmac_f32_e32 v91, v146, v144
	v_cvt_pk_bf16_f32 v136, v88, v89
	v_cvt_pk_bf16_f32 v137, v90, v91
	v_lshlrev_b32_e32 v141, 16, v128
	v_and_b32_e32 v142, 0xffff0000, v128
	v_lshlrev_b32_e32 v143, 16, v129
	v_and_b32_e32 v144, 0xffff0000, v129
	v_fmac_f32_e32 v92, v146, v141
	v_fmac_f32_e32 v93, v146, v142
	v_fmac_f32_e32 v94, v146, v143
	v_fmac_f32_e32 v95, v146, v144
	v_cvt_pk_bf16_f32 v138, v92, v93
	v_cvt_pk_bf16_f32 v139, v94, v95
	s_mov_b64 s[26:27], s[86:87]
	s_mov_b64 s[28:29], s[88:89]
	s_mov_b64 s[86:87], s[12:13]
	s_mov_b64 s[88:89], s[14:15]
	s_mov_b32 s4, s83
	s_mov_b32 s5, s84
	s_waitcnt vmcnt(0)
	s_barrier
	ds_read_b128 v[4:7], v230 offset:16384
	ds_read_b128 v[8:11], v231 offset:16384
	ds_read_b128 v[12:15], v230 offset:18432
	ds_read_b128 v[16:19], v231 offset:18432
	ds_read_b128 v[20:23], v230 offset:20480
	ds_read_b128 v[24:27], v231 offset:20480
	ds_read_b128 v[28:31], v230 offset:22528
	ds_read_b128 v[32:35], v231 offset:22528
	ds_read_b128 v[36:39], v230 offset:24576
	ds_read_b128 v[40:43], v231 offset:24576
	global_store_dwordx2 v237, v[132:133], s[26:27]
	global_store_dwordx2 v237, v[134:135], s[26:27] offset:32
	global_store_dwordx2 v237, v[136:137], s[26:27] offset:64
	global_store_dwordx2 v237, v[138:139], s[26:27] offset:96
	s_mov_b64 s[90:91], exec
	s_mov_b64 exec, 0xffff
	global_store_dword v238, v140, s[28:29]
	s_mov_b64 exec, s[90:91]
	s_add_u32 s84, s5, s4
	s_xor_b32 s83, s4, 1
	s_mul_i32 s74, s84, 256
	s_lshl_b32 s75, s83, 7
	s_add_u32 s74, s74, s75
	s_lshl_b32 s75, s74, 7
	s_add_u32 s16, s60, s75
	s_addc_u32 s17, s61, 0
	s_lshl_b32 s75, s74, 1
	s_add_u32 s24, s64, s75
	s_addc_u32 s25, s65, 0
	s_add_u32 m0, s70, 0xc000
	s_nop 0
	global_load_lds_dwordx4 v232, s[16:17]
	s_add_u32 m0, s70, 0xe000
	s_nop 0
	global_load_lds_dwordx4 v233, s[16:17]
	s_add_u32 m0, s70, 0x1c000
	s_nop 0
	global_load_lds_dwordx4 v234, s[24:25]
	s_add_u32 m0, s70, 0x1e000
	s_nop 0
	global_load_lds_dwordx4 v235, s[24:25]
	s_lshl_b32 s74, s83, 11
	s_add_u32 s74, s74, s84
	s_lshl_b32 s75, s74, 7
	s_add_u32 s10, s30, s75
	s_addc_u32 s11, s31, 0
	s_add_u32 s12, s34, s75
	s_addc_u32 s13, s35, 0
	s_lshl_b32 s75, s74, 2
	s_add_u32 s14, s58, s75
	s_addc_u32 s15, s59, 0
	global_load_dwordx4 v[104:107], v236, s[10:11]
	global_load_dwordx4 v[108:111], v236, s[10:11] offset:64
	global_load_dwordx2 v[122:123], v237, s[12:13]
	global_load_dwordx2 v[124:125], v237, s[12:13] offset:32
	global_load_dwordx2 v[126:127], v237, s[12:13] offset:64
	global_load_dwordx2 v[128:129], v237, s[12:13] offset:96
	global_load_dword v121, v238, s[14:15]
	s_waitcnt lgkmcnt(0)
	v_mfma_f32_16x16x32_bf16 v[44:47], v[4:7], v[96:99], 0
	v_mfma_f32_16x16x32_bf16 v[48:51], v[12:15], v[96:99], 0
	v_mfma_f32_16x16x32_bf16 v[52:55], v[20:23], v[96:99], 0
	v_mfma_f32_16x16x32_bf16 v[56:59], v[28:31], v[96:99], 0
	v_mfma_f32_16x16x32_bf16 v[60:63], v[36:39], v[96:99], 0
	v_mfma_f32_16x16x32_bf16 v[44:47], v[8:11], v[100:103], v[44:47]
	v_mfma_f32_16x16x32_bf16 v[48:51], v[16:19], v[100:103], v[48:51]
	v_mfma_f32_16x16x32_bf16 v[52:55], v[24:27], v[100:103], v[52:55]
	v_mfma_f32_16x16x32_bf16 v[56:59], v[32:35], v[100:103], v[56:59]
	v_mfma_f32_16x16x32_bf16 v[60:63], v[40:43], v[100:103], v[60:63]
	ds_read_b128 v[4:7], v230 offset:26624
	ds_read_b128 v[8:11], v231 offset:26624
	ds_read_b128 v[12:15], v230 offset:28672
	ds_read_b128 v[16:19], v231 offset:28672
	ds_read_b128 v[20:23], v230 offset:30720
	ds_read_b128 v[24:27], v231 offset:30720
	ds_read_b128 v[28:31], v230 offset:32768
	ds_read_b128 v[32:35], v231 offset:32768
	s_nop 1
	v_fma_f32 v44, v44, s79, v185
	v_fma_f32 v45, v45, s79, v186
	v_fma_f32 v46, v46, s79, v187
	v_fma_f32 v47, v47, s79, v188
	v_fma_f32 v48, v48, s79, v189
	v_fma_f32 v49, v49, s79, v190
	s_waitcnt lgkmcnt(0)
	v_mfma_f32_16x16x32_bf16 v[64:67], v[4:7], v[96:99], 0
	v_fma_f32 v50, v50, s79, v191
	v_fma_f32 v51, v51, s79, v192
	v_mfma_f32_16x16x32_bf16 v[68:71], v[12:15], v[96:99], 0
	v_fma_f32 v52, v52, s79, v193
	v_fma_f32 v53, v53, s79, v194
	v_mfma_f32_16x16x32_bf16 v[72:75], v[20:23], v[96:99], 0
	v_fma_f32 v54, v54, s79, v195
	v_fma_f32 v55, v55, s79, v196
	v_mfma_f32_16x16x32_bf16 v[76:79], v[28:31], v[96:99], 0
	v_fma_f32 v56, v56, s79, v197
	v_fma_f32 v57, v57, s79, v198
	v_mfma_f32_16x16x32_bf16 v[64:67], v[8:11], v[100:103], v[64:67]
	v_fma_f32 v58, v58, s79, v199
	v_fma_f32 v59, v59, s79, v200
	v_mfma_f32_16x16x32_bf16 v[68:71], v[16:19], v[100:103], v[68:71]
	v_fma_f32 v60, v60, s79, v201
	v_fma_f32 v61, v61, s79, v202
	v_mfma_f32_16x16x32_bf16 v[72:75], v[24:27], v[100:103], v[72:75]
	v_fma_f32 v62, v62, s79, v203
	v_fma_f32 v63, v63, s79, v204
	v_mfma_f32_16x16x32_bf16 v[76:79], v[32:35], v[100:103], v[76:79]
	ds_read_b64 v[4:5], v221 offset:16384
	ds_read_b64 v[8:9], v221 offset:20480
	ds_read_b64 v[12:13], v221 offset:24576
	ds_read_b64 v[16:17], v221 offset:28672
	ds_read_b64 v[6:7], v222 offset:16384
	ds_read_b64 v[10:11], v222 offset:20480
	ds_read_b64 v[14:15], v222 offset:24576
	ds_read_b64 v[18:19], v222 offset:28672
	s_nop 1
	v_fma_f32 v64, v64, s79, v205
	v_fma_f32 v65, v65, s79, v206
	v_fma_f32 v66, v66, s79, v207
	v_fma_f32 v67, v67, s79, v208
	v_fma_f32 v68, v68, s79, v209
	v_fma_f32 v69, v69, s79, v210
	v_fma_f32 v70, v70, s79, v211
	v_fma_f32 v71, v71, s79, v212
	v_fma_f32 v72, v72, s79, v213
	v_fma_f32 v73, v73, s79, v214
	v_fma_f32 v74, v74, s79, v215
	v_fma_f32 v75, v75, s79, v216
	v_fma_f32 v76, v76, s79, v217
	v_fma_f32 v77, v77, s79, v218
	v_fma_f32 v78, v78, s79, v219
	v_fma_f32 v79, v79, s79, v220
	ds_read_b64 v[20:21], v223 offset:16384
	ds_read_b64 v[24:25], v223 offset:20480
	ds_read_b64 v[28:29], v223 offset:24576
	ds_read_b64 v[32:33], v223 offset:28672
	ds_read_b64 v[22:23], v224 offset:16384
	ds_read_b64 v[26:27], v224 offset:20480
	ds_read_b64 v[30:31], v224 offset:24576
	ds_read_b64 v[34:35], v224 offset:28672
	s_cmp_lg_u32 s4, 0
	s_cbranch_scc1 .Lat991_i2_nomask
	s_cmp_le_u32 s6, 0
	s_cbranch_scc1 .Lat991_i2_nomask
	v_mov_b32_e32 v44, v244
	v_mov_b32_e32 v45, v244
	v_mov_b32_e32 v46, v244
	v_mov_b32_e32 v47, v244
	s_cmp_le_u32 s6, 1
	s_cbranch_scc1 .Lat991_i2_nomask
	v_mov_b32_e32 v48, v244
	v_mov_b32_e32 v49, v244
	v_mov_b32_e32 v50, v244
	v_mov_b32_e32 v51, v244
	s_cmp_le_u32 s6, 2
	s_cbranch_scc1 .Lat991_i2_nomask
	v_mov_b32_e32 v52, v244
	v_mov_b32_e32 v53, v244
	v_mov_b32_e32 v54, v244
	v_mov_b32_e32 v55, v244
	s_cmp_le_u32 s6, 3
	s_cbranch_scc1 .Lat991_i2_nomask
	v_mov_b32_e32 v56, v244
	v_mov_b32_e32 v57, v244
	v_mov_b32_e32 v58, v244
	v_mov_b32_e32 v59, v244
	s_cmp_le_u32 s6, 4
	s_cbranch_scc1 .Lat991_i2_nomask
	v_mov_b32_e32 v60, v244
	v_mov_b32_e32 v61, v244
	v_mov_b32_e32 v62, v244
	v_mov_b32_e32 v63, v244
	s_cmp_le_u32 s6, 5
	s_cbranch_scc1 .Lat991_i2_nomask
	v_mov_b32_e32 v64, v244
	v_mov_b32_e32 v65, v244
	v_mov_b32_e32 v66, v244
	v_mov_b32_e32 v67, v244
	s_cmp_le_u32 s6, 6
	s_cbranch_scc1 .Lat991_i2_nomask
	v_mov_b32_e32 v68, v244
	v_mov_b32_e32 v69, v244
	v_mov_b32_e32 v70, v244
	v_mov_b32_e32 v71, v244
	s_cmp_le_u32 s6, 7
	s_cbranch_scc1 .Lat991_i2_nomask
	v_mov_b32_e32 v72, v244
	v_mov_b32_e32 v73, v244
	v_mov_b32_e32 v74, v244
	v_mov_b32_e32 v75, v244
.Lat991_i2_nomask:
	v_max3_f32 v245, v44, v45, v46
	v_max3_f32 v245, v245, v47, v48
	v_max3_f32 v245, v245, v49, v50
	v_max3_f32 v245, v245, v51, v52
	v_max3_f32 v245, v245, v53, v54
	v_max3_f32 v245, v245, v55, v56
	v_max3_f32 v245, v245, v57, v58
	v_max3_f32 v245, v245, v59, v60
	v_max3_f32 v245, v245, v61, v62
	v_max3_f32 v245, v245, v63, v64
	v_max3_f32 v245, v245, v65, v66
	v_max3_f32 v245, v245, v67, v68
	v_max3_f32 v245, v245, v69, v70
	v_max3_f32 v245, v245, v71, v72
	v_max3_f32 v245, v245, v73, v74
	v_max3_f32 v245, v245, v75, v76
	v_max3_f32 v245, v245, v77, v78
	v_max_f32_e32 v245, v245, v79
	ds_bpermute_b32 v148, v239, v245
	s_waitcnt lgkmcnt(0)
	v_max_f32_e32 v245, v245, v148
	ds_bpermute_b32 v148, v240, v245
	s_waitcnt lgkmcnt(0)
	v_max_f32_e32 v245, v245, v148
	v_sub_f32_e32 v44, v44, v245
	v_sub_f32_e32 v45, v45, v245
	v_sub_f32_e32 v46, v46, v245
	v_sub_f32_e32 v47, v47, v245
	v_exp_f32_e32 v44, v44
	v_exp_f32_e32 v45, v45
	v_exp_f32_e32 v46, v46
	v_exp_f32_e32 v47, v47
	v_sub_f32_e32 v48, v48, v245
	v_sub_f32_e32 v49, v49, v245
	v_sub_f32_e32 v50, v50, v245
	v_sub_f32_e32 v51, v51, v245
	v_exp_f32_e32 v48, v48
	v_exp_f32_e32 v49, v49
	v_exp_f32_e32 v50, v50
	v_exp_f32_e32 v51, v51
	v_mov_b32_e32 v149, v44
	v_mov_b32_e32 v150, v45
	v_mov_b32_e32 v151, v46
	v_mov_b32_e32 v152, v47
	v_cvt_pk_bf16_f32 v44, v44, v45
	v_cvt_pk_bf16_f32 v45, v46, v47
	v_sub_f32_e32 v52, v52, v245
	v_sub_f32_e32 v53, v53, v245
	v_sub_f32_e32 v54, v54, v245
	v_sub_f32_e32 v55, v55, v245
	v_exp_f32_e32 v52, v52
	v_exp_f32_e32 v53, v53
	v_exp_f32_e32 v54, v54
	v_exp_f32_e32 v55, v55
	v_add_f32_e32 v149, v149, v48
	v_add_f32_e32 v150, v150, v49
	v_add_f32_e32 v151, v151, v50
	v_add_f32_e32 v152, v152, v51
	v_cvt_pk_bf16_f32 v46, v48, v49
	v_cvt_pk_bf16_f32 v47, v50, v51
	s_waitcnt lgkmcnt(0)
	v_sub_f32_e32 v56, v56, v245
	v_sub_f32_e32 v57, v57, v245
	v_mfma_f32_16x16x32_bf16 v[80:83], v[4:7], v[44:47], 0
	v_sub_f32_e32 v58, v58, v245
	v_sub_f32_e32 v59, v59, v245
	v_exp_f32_e32 v56, v56
	v_mfma_f32_16x16x32_bf16 v[84:87], v[8:11], v[44:47], 0
	v_exp_f32_e32 v57, v57
	v_exp_f32_e32 v58, v58
	v_exp_f32_e32 v59, v59
	v_mfma_f32_16x16x32_bf16 v[88:91], v[12:15], v[44:47], 0
	v_add_f32_e32 v149, v149, v52
	v_add_f32_e32 v150, v150, v53
	v_add_f32_e32 v151, v151, v54
	v_mfma_f32_16x16x32_bf16 v[92:95], v[16:19], v[44:47], 0
	v_add_f32_e32 v152, v152, v55
	v_cvt_pk_bf16_f32 v52, v52, v53
	v_cvt_pk_bf16_f32 v53, v54, v55
	ds_read_b64 v[4:5], v225 offset:16384
	ds_read_b64 v[8:9], v225 offset:20480
	ds_read_b64 v[12:13], v225 offset:24576
	ds_read_b64 v[16:17], v225 offset:28672
	ds_read_b64 v[6:7], v226 offset:16384
	ds_read_b64 v[10:11], v226 offset:20480
	ds_read_b64 v[14:15], v226 offset:24576
	ds_read_b64 v[18:19], v226 offset:28672
	v_sub_f32_e32 v60, v60, v245
	v_sub_f32_e32 v61, v61, v245
	v_sub_f32_e32 v62, v62, v245
	v_sub_f32_e32 v63, v63, v245
	v_exp_f32_e32 v60, v60
	v_exp_f32_e32 v61, v61
	v_exp_f32_e32 v62, v62
	v_exp_f32_e32 v63, v63
	v_add_f32_e32 v149, v149, v56
	v_add_f32_e32 v150, v150, v57
	v_add_f32_e32 v151, v151, v58
	v_add_f32_e32 v152, v152, v59
	v_cvt_pk_bf16_f32 v54, v56, v57
	v_cvt_pk_bf16_f32 v55, v58, v59
	v_sub_f32_e32 v64, v64, v245
	v_sub_f32_e32 v65, v65, v245
	v_mfma_f32_16x16x32_bf16 v[80:83], v[20:23], v[52:55], v[80:83]
	v_sub_f32_e32 v66, v66, v245
	v_sub_f32_e32 v67, v67, v245
	v_exp_f32_e32 v64, v64
	v_mfma_f32_16x16x32_bf16 v[84:87], v[24:27], v[52:55], v[84:87]
	v_exp_f32_e32 v65, v65
	v_exp_f32_e32 v66, v66
	v_exp_f32_e32 v67, v67
	v_mfma_f32_16x16x32_bf16 v[88:91], v[28:31], v[52:55], v[88:91]
	v_add_f32_e32 v149, v149, v60
	v_add_f32_e32 v150, v150, v61
	v_add_f32_e32 v151, v151, v62
	v_mfma_f32_16x16x32_bf16 v[92:95], v[32:35], v[52:55], v[92:95]
	v_add_f32_e32 v152, v152, v63
	v_cvt_pk_bf16_f32 v60, v60, v61
	v_cvt_pk_bf16_f32 v61, v62, v63
	ds_read_b64 v[20:21], v227 offset:16384
	ds_read_b64 v[24:25], v227 offset:20480
	ds_read_b64 v[28:29], v227 offset:24576
	ds_read_b64 v[32:33], v227 offset:28672
	ds_read_b64 v[22:23], v228 offset:16384
	ds_read_b64 v[26:27], v228 offset:20480
	ds_read_b64 v[30:31], v228 offset:24576
	ds_read_b64 v[34:35], v228 offset:28672
	v_sub_f32_e32 v68, v68, v245
	v_sub_f32_e32 v69, v69, v245
	v_sub_f32_e32 v70, v70, v245
	v_sub_f32_e32 v71, v71, v245
	v_exp_f32_e32 v68, v68
	v_exp_f32_e32 v69, v69
	v_exp_f32_e32 v70, v70
	v_exp_f32_e32 v71, v71
	v_add_f32_e32 v149, v149, v64
	v_add_f32_e32 v150, v150, v65
	v_add_f32_e32 v151, v151, v66
	v_add_f32_e32 v152, v152, v67
	v_cvt_pk_bf16_f32 v62, v64, v65
	v_cvt_pk_bf16_f32 v63, v66, v67
	s_waitcnt lgkmcnt(8)
	v_sub_f32_e32 v72, v72, v245
	v_sub_f32_e32 v73, v73, v245
	v_mfma_f32_16x16x32_bf16 v[80:83], v[4:7], v[60:63], v[80:83]
	v_sub_f32_e32 v74, v74, v245
	v_sub_f32_e32 v75, v75, v245
	v_exp_f32_e32 v72, v72
	v_mfma_f32_16x16x32_bf16 v[84:87], v[8:11], v[60:63], v[84:87]
	v_exp_f32_e32 v73, v73
	v_exp_f32_e32 v74, v74
	v_exp_f32_e32 v75, v75
	v_mfma_f32_16x16x32_bf16 v[88:91], v[12:15], v[60:63], v[88:91]
	v_add_f32_e32 v149, v149, v68
	v_add_f32_e32 v150, v150, v69
	v_add_f32_e32 v151, v151, v70
	v_mfma_f32_16x16x32_bf16 v[92:95], v[16:19], v[60:63], v[92:95]
	v_add_f32_e32 v152, v152, v71
	v_cvt_pk_bf16_f32 v68, v68, v69
	v_cvt_pk_bf16_f32 v69, v70, v71
	ds_read_b64 v[4:5], v229 offset:16384
	ds_read_b64 v[8:9], v229 offset:20480
	ds_read_b64 v[12:13], v229 offset:24576
	ds_read_b64 v[16:17], v229 offset:28672
	v_mov_b32_e32 v6, 0
	v_mov_b32_e32 v7, 0
	v_mov_b32_e32 v10, 0
	v_mov_b32_e32 v11, 0
	v_mov_b32_e32 v14, 0
	v_mov_b32_e32 v15, 0
	v_mov_b32_e32 v18, 0
	v_mov_b32_e32 v19, 0
	v_sub_f32_e32 v76, v76, v245
	v_sub_f32_e32 v77, v77, v245
	v_sub_f32_e32 v78, v78, v245
	v_sub_f32_e32 v79, v79, v245
	v_exp_f32_e32 v76, v76
	v_exp_f32_e32 v77, v77
	v_exp_f32_e32 v78, v78
	v_exp_f32_e32 v79, v79
	v_add_f32_e32 v149, v149, v72
	v_add_f32_e32 v150, v150, v73
	v_add_f32_e32 v151, v151, v74
	v_add_f32_e32 v152, v152, v75
	v_cvt_pk_bf16_f32 v70, v72, v73
	v_cvt_pk_bf16_f32 v71, v74, v75
	s_waitcnt lgkmcnt(4)
	v_add_f32_e32 v149, v149, v76
	v_add_f32_e32 v150, v150, v77
	v_mfma_f32_16x16x32_bf16 v[80:83], v[20:23], v[68:71], v[80:83]
	v_add_f32_e32 v151, v151, v78
	v_add_f32_e32 v152, v152, v79
	v_mfma_f32_16x16x32_bf16 v[84:87], v[24:27], v[68:71], v[84:87]
	v_cvt_pk_bf16_f32 v76, v76, v77
	v_cvt_pk_bf16_f32 v77, v78, v79
	v_mfma_f32_16x16x32_bf16 v[88:91], v[28:31], v[68:71], v[88:91]
	v_mov_b32_e32 v78, 0
	v_mov_b32_e32 v79, 0
	v_mfma_f32_16x16x32_bf16 v[92:95], v[32:35], v[68:71], v[92:95]
	v_add_f32_e32 v149, v149, v150
	v_add_f32_e32 v151, v151, v152
	v_add_f32_e32 v246, v149, v151
	ds_bpermute_b32 v148, v239, v246
	s_waitcnt lgkmcnt(1)
	v_mfma_f32_16x16x32_bf16 v[80:83], v[4:7], v[76:79], v[80:83]
	v_mfma_f32_16x16x32_bf16 v[84:87], v[8:11], v[76:79], v[84:87]
	v_mfma_f32_16x16x32_bf16 v[88:91], v[12:15], v[76:79], v[88:91]
	v_mfma_f32_16x16x32_bf16 v[92:95], v[16:19], v[76:79], v[92:95]
	s_waitcnt lgkmcnt(0)
	v_add_f32_e32 v246, v246, v148
	ds_bpermute_b32 v148, v240, v246
	s_waitcnt lgkmcnt(0)
	v_add_f32_e32 v246, v246, v148
	v_rcp_f32_e32 v149, v246
	v_log_f32_e32 v150, v246
	s_nop 0
	v_add_f32_e32 v151, v245, v150
	v_mul_f32_e32 v151, 0x3f317218, v151
	v_max_f32_e32 v152, v120, v151
	v_sub_f32_e32 v153, v120, v152
	v_sub_f32_e32 v154, v151, v152
	v_mul_f32_e32 v153, 0x3fb8aa3b, v153
	v_mul_f32_e32 v154, 0x3fb8aa3b, v154
	v_exp_f32_e32 v153, v153
	v_exp_f32_e32 v154, v154
	s_nop 0
	v_add_f32_e32 v155, v153, v154
	v_rcp_f32_e32 v146, v155
	v_log_f32_e32 v150, v155
	s_nop 0
	v_mul_f32_e32 v154, v154, v146
	v_mul_f32_e32 v146, v153, v146
	v_mul_f32_e32 v147, v149, v154
	v_mul_f32_e32 v150, 0x3f317218, v150
	v_add_f32_e32 v140, v152, v150
	v_mul_f32_e32 v80, v80, v147
	v_mul_f32_e32 v81, v81, v147
	v_mul_f32_e32 v82, v82, v147
	v_mul_f32_e32 v83, v83, v147
	v_mul_f32_e32 v84, v84, v147
	v_mul_f32_e32 v85, v85, v147
	v_mul_f32_e32 v86, v86, v147
	v_mul_f32_e32 v87, v87, v147
	v_mul_f32_e32 v88, v88, v147
	v_mul_f32_e32 v89, v89, v147
	v_mul_f32_e32 v90, v90, v147
	v_mul_f32_e32 v91, v91, v147
	v_mul_f32_e32 v92, v92, v147
	v_mul_f32_e32 v93, v93, v147
	v_mul_f32_e32 v94, v94, v147
	v_mul_f32_e32 v95, v95, v147
	v_lshlrev_b32_e32 v141, 16, v112
	v_and_b32_e32 v142, 0xffff0000, v112
	v_lshlrev_b32_e32 v143, 16, v113
	v_and_b32_e32 v144, 0xffff0000, v113
	v_fmac_f32_e32 v80, v146, v141
	v_fmac_f32_e32 v81, v146, v142
	v_fmac_f32_e32 v82, v146, v143
	v_fmac_f32_e32 v83, v146, v144
	v_cvt_pk_bf16_f32 v132, v80, v81
	v_cvt_pk_bf16_f32 v133, v82, v83
	v_lshlrev_b32_e32 v141, 16, v114
	v_and_b32_e32 v142, 0xffff0000, v114
	v_lshlrev_b32_e32 v143, 16, v115
	v_and_b32_e32 v144, 0xffff0000, v115
	v_fmac_f32_e32 v84, v146, v141
	v_fmac_f32_e32 v85, v146, v142
	v_fmac_f32_e32 v86, v146, v143
	v_fmac_f32_e32 v87, v146, v144
	v_cvt_pk_bf16_f32 v134, v84, v85
	v_cvt_pk_bf16_f32 v135, v86, v87
	v_lshlrev_b32_e32 v141, 16, v116
	v_and_b32_e32 v142, 0xffff0000, v116
	v_lshlrev_b32_e32 v143, 16, v117
	v_and_b32_e32 v144, 0xffff0000, v117
	v_fmac_f32_e32 v88, v146, v141
	v_fmac_f32_e32 v89, v146, v142
	v_fmac_f32_e32 v90, v146, v143
	v_fmac_f32_e32 v91, v146, v144
	v_cvt_pk_bf16_f32 v136, v88, v89
	v_cvt_pk_bf16_f32 v137, v90, v91
	v_lshlrev_b32_e32 v141, 16, v118
	v_and_b32_e32 v142, 0xffff0000, v118
	v_lshlrev_b32_e32 v143, 16, v119
	v_and_b32_e32 v144, 0xffff0000, v119
	v_fmac_f32_e32 v92, v146, v141
	v_fmac_f32_e32 v93, v146, v142
	v_fmac_f32_e32 v94, v146, v143
	v_fmac_f32_e32 v95, v146, v144
	v_cvt_pk_bf16_f32 v138, v92, v93
	v_cvt_pk_bf16_f32 v139, v94, v95
	s_mov_b64 s[26:27], s[86:87]
	s_mov_b64 s[28:29], s[88:89]
	s_mov_b64 s[86:87], s[12:13]
	s_mov_b64 s[88:89], s[14:15]
	s_mov_b32 s4, s83
	s_mov_b32 s5, s84
	s_waitcnt vmcnt(0)
	s_barrier
	ds_read_b128 v[4:7], v230 offset:32768
	ds_read_b128 v[8:11], v231 offset:32768
	ds_read_b128 v[12:15], v230 offset:34816
	ds_read_b128 v[16:19], v231 offset:34816
	ds_read_b128 v[20:23], v230 offset:36864
	ds_read_b128 v[24:27], v231 offset:36864
	ds_read_b128 v[28:31], v230 offset:38912
	ds_read_b128 v[32:35], v231 offset:38912
	ds_read_b128 v[36:39], v230 offset:40960
	ds_read_b128 v[40:43], v231 offset:40960
	global_store_dwordx2 v237, v[132:133], s[26:27]
	global_store_dwordx2 v237, v[134:135], s[26:27] offset:32
	global_store_dwordx2 v237, v[136:137], s[26:27] offset:64
	global_store_dwordx2 v237, v[138:139], s[26:27] offset:96
	s_mov_b64 s[90:91], exec
	s_mov_b64 exec, 0xffff
	global_store_dword v238, v140, s[28:29]
	s_mov_b64 exec, s[90:91]
	s_cmp_eq_u32 s7, 1
	s_cbranch_scc1 .Lat991_i3_nonext
	s_add_u32 s84, s5, s4
	s_xor_b32 s83, s4, 1
	s_mul_i32 s74, s84, 256
	s_lshl_b32 s75, s83, 7
	s_add_u32 s74, s74, s75
	s_lshl_b32 s75, s74, 7
	s_add_u32 s16, s60, s75
	s_addc_u32 s17, s61, 0
	s_lshl_b32 s75, s74, 1
	s_add_u32 s24, s64, s75
	s_addc_u32 s25, s65, 0
	s_add_u32 m0, s70, 0x0
	s_nop 0
	global_load_lds_dwordx4 v232, s[16:17]
	s_add_u32 m0, s70, 0x2000
	s_nop 0
	global_load_lds_dwordx4 v233, s[16:17]
	s_add_u32 m0, s70, 0x10000
	s_nop 0
	global_load_lds_dwordx4 v234, s[24:25]
	s_add_u32 m0, s70, 0x12000
	s_nop 0
	global_load_lds_dwordx4 v235, s[24:25]
	s_lshl_b32 s74, s83, 11
	s_add_u32 s74, s74, s84
	s_lshl_b32 s75, s74, 7
	s_add_u32 s10, s30, s75
	s_addc_u32 s11, s31, 0
	s_add_u32 s12, s34, s75
	s_addc_u32 s13, s35, 0
	s_lshl_b32 s75, s74, 2
	s_add_u32 s14, s58, s75
	s_addc_u32 s15, s59, 0
	global_load_dwordx4 v[96:99], v236, s[10:11]
	global_load_dwordx4 v[100:103], v236, s[10:11] offset:64
	global_load_dwordx2 v[112:113], v237, s[12:13]
	global_load_dwordx2 v[114:115], v237, s[12:13] offset:32
	global_load_dwordx2 v[116:117], v237, s[12:13] offset:64
	global_load_dwordx2 v[118:119], v237, s[12:13] offset:96
	global_load_dword v120, v238, s[14:15]

.Lat991_i3_nomask:
	v_max3_f32 v245, v44, v45, v46
	v_max3_f32 v245, v245, v47, v48
	v_max3_f32 v245, v245, v49, v50
	v_max3_f32 v245, v245, v51, v52
	v_max3_f32 v245, v245, v53, v54
	v_max3_f32 v245, v245, v55, v56
	v_max3_f32 v245, v245, v57, v58
	v_max3_f32 v245, v245, v59, v60
	v_max3_f32 v245, v245, v61, v62
	v_max3_f32 v245, v245, v63, v64
	v_max3_f32 v245, v245, v65, v66
	v_max3_f32 v245, v245, v67, v68
	v_max3_f32 v245, v245, v69, v70
	v_max3_f32 v245, v245, v71, v72
	v_max3_f32 v245, v245, v73, v74
	v_max3_f32 v245, v245, v75, v76
	v_max3_f32 v245, v245, v77, v78
	v_max_f32_e32 v245, v245, v79
	ds_bpermute_b32 v148, v239, v245
	s_waitcnt lgkmcnt(0)
	v_max_f32_e32 v245, v245, v148
	ds_bpermute_b32 v148, v240, v245
	s_waitcnt lgkmcnt(0)
	v_max_f32_e32 v245, v245, v148
	v_sub_f32_e32 v44, v44, v245
	v_sub_f32_e32 v45, v45, v245
	v_sub_f32_e32 v46, v46, v245
	v_sub_f32_e32 v47, v47, v245
	v_exp_f32_e32 v44, v44
	v_exp_f32_e32 v45, v45
	v_exp_f32_e32 v46, v46
	v_exp_f32_e32 v47, v47
	v_sub_f32_e32 v48, v48, v245
	v_sub_f32_e32 v49, v49, v245
	v_sub_f32_e32 v50, v50, v245
	v_sub_f32_e32 v51, v51, v245
	v_exp_f32_e32 v48, v48
	v_exp_f32_e32 v49, v49
	v_exp_f32_e32 v50, v50
	v_exp_f32_e32 v51, v51
	v_mov_b32_e32 v149, v44
	v_mov_b32_e32 v150, v45
	v_mov_b32_e32 v151, v46
	v_mov_b32_e32 v152, v47
	v_cvt_pk_bf16_f32 v44, v44, v45
	v_cvt_pk_bf16_f32 v45, v46, v47
	v_sub_f32_e32 v52, v52, v245
	v_sub_f32_e32 v53, v53, v245
	v_sub_f32_e32 v54, v54, v245
	v_sub_f32_e32 v55, v55, v245
	v_exp_f32_e32 v52, v52
	v_exp_f32_e32 v53, v53
	v_exp_f32_e32 v54, v54
	v_exp_f32_e32 v55, v55
	v_add_f32_e32 v149, v149, v48
	v_add_f32_e32 v150, v150, v49
	v_add_f32_e32 v151, v151, v50
	v_add_f32_e32 v152, v152, v51
	v_cvt_pk_bf16_f32 v46, v48, v49
	v_cvt_pk_bf16_f32 v47, v50, v51
	s_waitcnt lgkmcnt(0)
	v_sub_f32_e32 v56, v56, v245
	v_sub_f32_e32 v57, v57, v245
	v_mfma_f32_16x16x32_bf16 v[80:83], v[4:7], v[44:47], 0
	v_sub_f32_e32 v58, v58, v245
	v_sub_f32_e32 v59, v59, v245
	v_exp_f32_e32 v56, v56
	v_mfma_f32_16x16x32_bf16 v[84:87], v[8:11], v[44:47], 0
	v_exp_f32_e32 v57, v57
	v_exp_f32_e32 v58, v58
	v_exp_f32_e32 v59, v59
	v_mfma_f32_16x16x32_bf16 v[88:91], v[12:15], v[44:47], 0
	v_add_f32_e32 v149, v149, v52
	v_add_f32_e32 v150, v150, v53
	v_add_f32_e32 v151, v151, v54
	v_mfma_f32_16x16x32_bf16 v[92:95], v[16:19], v[44:47], 0
	v_add_f32_e32 v152, v152, v55
	v_cvt_pk_bf16_f32 v52, v52, v53
	v_cvt_pk_bf16_f32 v53, v54, v55
	ds_read_b64 v[4:5], v225 offset:32768
	ds_read_b64 v[8:9], v225 offset:36864
	ds_read_b64 v[12:13], v225 offset:40960
	ds_read_b64 v[16:17], v225 offset:45056
	ds_read_b64 v[6:7], v226 offset:32768
	ds_read_b64 v[10:11], v226 offset:36864
	ds_read_b64 v[14:15], v226 offset:40960
	ds_read_b64 v[18:19], v226 offset:45056
	v_sub_f32_e32 v60, v60, v245
	v_sub_f32_e32 v61, v61, v245
	v_sub_f32_e32 v62, v62, v245
	v_sub_f32_e32 v63, v63, v245
	v_exp_f32_e32 v60, v60
	v_exp_f32_e32 v61, v61
	v_exp_f32_e32 v62, v62
	v_exp_f32_e32 v63, v63
	v_add_f32_e32 v149, v149, v56
	v_add_f32_e32 v150, v150, v57
	v_add_f32_e32 v151, v151, v58
	v_add_f32_e32 v152, v152, v59
	v_cvt_pk_bf16_f32 v54, v56, v57
	v_cvt_pk_bf16_f32 v55, v58, v59
	v_sub_f32_e32 v64, v64, v245
	v_sub_f32_e32 v65, v65, v245
	v_mfma_f32_16x16x32_bf16 v[80:83], v[20:23], v[52:55], v[80:83]
	v_sub_f32_e32 v66, v66, v245
	v_sub_f32_e32 v67, v67, v245
	v_exp_f32_e32 v64, v64
	v_mfma_f32_16x16x32_bf16 v[84:87], v[24:27], v[52:55], v[84:87]
	v_exp_f32_e32 v65, v65
	v_exp_f32_e32 v66, v66
	v_exp_f32_e32 v67, v67
	v_mfma_f32_16x16x32_bf16 v[88:91], v[28:31], v[52:55], v[88:91]
	v_add_f32_e32 v149, v149, v60
	v_add_f32_e32 v150, v150, v61
	v_add_f32_e32 v151, v151, v62
	v_mfma_f32_16x16x32_bf16 v[92:95], v[32:35], v[52:55], v[92:95]
	v_add_f32_e32 v152, v152, v63
	v_cvt_pk_bf16_f32 v60, v60, v61
	v_cvt_pk_bf16_f32 v61, v62, v63
	ds_read_b64 v[20:21], v227 offset:32768
	ds_read_b64 v[24:25], v227 offset:36864
	ds_read_b64 v[28:29], v227 offset:40960
	ds_read_b64 v[32:33], v227 offset:45056
	ds_read_b64 v[22:23], v228 offset:32768
	ds_read_b64 v[26:27], v228 offset:36864
	ds_read_b64 v[30:31], v228 offset:40960
	ds_read_b64 v[34:35], v228 offset:45056
	v_sub_f32_e32 v68, v68, v245
	v_sub_f32_e32 v69, v69, v245
	v_sub_f32_e32 v70, v70, v245
	v_sub_f32_e32 v71, v71, v245
	v_exp_f32_e32 v68, v68
	v_exp_f32_e32 v69, v69
	v_exp_f32_e32 v70, v70
	v_exp_f32_e32 v71, v71
	v_add_f32_e32 v149, v149, v64
	v_add_f32_e32 v150, v150, v65
	v_add_f32_e32 v151, v151, v66
	v_add_f32_e32 v152, v152, v67
	v_cvt_pk_bf16_f32 v62, v64, v65
	v_cvt_pk_bf16_f32 v63, v66, v67
	s_waitcnt lgkmcnt(8)
	v_sub_f32_e32 v72, v72, v245
	v_sub_f32_e32 v73, v73, v245
	v_mfma_f32_16x16x32_bf16 v[80:83], v[4:7], v[60:63], v[80:83]
	v_sub_f32_e32 v74, v74, v245
	v_sub_f32_e32 v75, v75, v245
	v_exp_f32_e32 v72, v72
	v_mfma_f32_16x16x32_bf16 v[84:87], v[8:11], v[60:63], v[84:87]
	v_exp_f32_e32 v73, v73
	v_exp_f32_e32 v74, v74
	v_exp_f32_e32 v75, v75
	v_mfma_f32_16x16x32_bf16 v[88:91], v[12:15], v[60:63], v[88:91]
	v_add_f32_e32 v149, v149, v68
	v_add_f32_e32 v150, v150, v69
	v_add_f32_e32 v151, v151, v70
	v_mfma_f32_16x16x32_bf16 v[92:95], v[16:19], v[60:63], v[92:95]
	v_add_f32_e32 v152, v152, v71
	v_cvt_pk_bf16_f32 v68, v68, v69
	v_cvt_pk_bf16_f32 v69, v70, v71
	ds_read_b64 v[4:5], v229 offset:32768
	ds_read_b64 v[8:9], v229 offset:36864
	ds_read_b64 v[12:13], v229 offset:40960
	ds_read_b64 v[16:17], v229 offset:45056
	v_mov_b32_e32 v6, 0
	v_mov_b32_e32 v7, 0
	v_mov_b32_e32 v10, 0
	v_mov_b32_e32 v11, 0
	v_mov_b32_e32 v14, 0
	v_mov_b32_e32 v15, 0
	v_mov_b32_e32 v18, 0
	v_mov_b32_e32 v19, 0
	v_sub_f32_e32 v76, v76, v245
	v_sub_f32_e32 v77, v77, v245
	v_sub_f32_e32 v78, v78, v245
	v_sub_f32_e32 v79, v79, v245
	v_exp_f32_e32 v76, v76
	v_exp_f32_e32 v77, v77
	v_exp_f32_e32 v78, v78
	v_exp_f32_e32 v79, v79
	v_add_f32_e32 v149, v149, v72
	v_add_f32_e32 v150, v150, v73
	v_add_f32_e32 v151, v151, v74
	v_add_f32_e32 v152, v152, v75
	v_cvt_pk_bf16_f32 v70, v72, v73
	v_cvt_pk_bf16_f32 v71, v74, v75
	s_waitcnt lgkmcnt(4)
	v_add_f32_e32 v149, v149, v76
	v_add_f32_e32 v150, v150, v77
	v_mfma_f32_16x16x32_bf16 v[80:83], v[20:23], v[68:71], v[80:83]
	v_add_f32_e32 v151, v151, v78
	v_add_f32_e32 v152, v152, v79
	v_mfma_f32_16x16x32_bf16 v[84:87], v[24:27], v[68:71], v[84:87]
	v_cvt_pk_bf16_f32 v76, v76, v77
	v_cvt_pk_bf16_f32 v77, v78, v79
	v_mfma_f32_16x16x32_bf16 v[88:91], v[28:31], v[68:71], v[88:91]
	v_mov_b32_e32 v78, 0
	v_mov_b32_e32 v79, 0
	v_mfma_f32_16x16x32_bf16 v[92:95], v[32:35], v[68:71], v[92:95]
	v_add_f32_e32 v149, v149, v150
	v_add_f32_e32 v151, v151, v152
	v_add_f32_e32 v246, v149, v151
	ds_bpermute_b32 v148, v239, v246
	s_waitcnt lgkmcnt(1)
	v_mfma_f32_16x16x32_bf16 v[80:83], v[4:7], v[76:79], v[80:83]
	v_mfma_f32_16x16x32_bf16 v[84:87], v[8:11], v[76:79], v[84:87]
	v_mfma_f32_16x16x32_bf16 v[88:91], v[12:15], v[76:79], v[88:91]
	v_mfma_f32_16x16x32_bf16 v[92:95], v[16:19], v[76:79], v[92:95]
	s_waitcnt lgkmcnt(0)
	v_add_f32_e32 v246, v246, v148
	ds_bpermute_b32 v148, v240, v246
	s_waitcnt lgkmcnt(0)
	v_add_f32_e32 v246, v246, v148
	v_rcp_f32_e32 v149, v246
	v_log_f32_e32 v150, v246
	s_nop 0
	v_add_f32_e32 v151, v245, v150
	v_mul_f32_e32 v151, 0x3f317218, v151
	v_max_f32_e32 v152, v121, v151
	v_sub_f32_e32 v153, v121, v152
	v_sub_f32_e32 v154, v151, v152
	v_mul_f32_e32 v153, 0x3fb8aa3b, v153
	v_mul_f32_e32 v154, 0x3fb8aa3b, v154
	v_exp_f32_e32 v153, v153
	v_exp_f32_e32 v154, v154
	s_nop 0
	v_add_f32_e32 v155, v153, v154
	v_rcp_f32_e32 v146, v155
	v_log_f32_e32 v150, v155
	s_nop 0
	v_mul_f32_e32 v154, v154, v146
	v_mul_f32_e32 v146, v153, v146
	v_mul_f32_e32 v147, v149, v154
	v_mul_f32_e32 v150, 0x3f317218, v150
	v_add_f32_e32 v140, v152, v150
	v_mul_f32_e32 v80, v80, v147
	v_mul_f32_e32 v81, v81, v147
	v_mul_f32_e32 v82, v82, v147
	v_mul_f32_e32 v83, v83, v147
	v_mul_f32_e32 v84, v84, v147
	v_mul_f32_e32 v85, v85, v147
	v_mul_f32_e32 v86, v86, v147
	v_mul_f32_e32 v87, v87, v147
	v_mul_f32_e32 v88, v88, v147
	v_mul_f32_e32 v89, v89, v147
	v_mul_f32_e32 v90, v90, v147
	v_mul_f32_e32 v91, v91, v147
	v_mul_f32_e32 v92, v92, v147
	v_mul_f32_e32 v93, v93, v147
	v_mul_f32_e32 v94, v94, v147
	v_mul_f32_e32 v95, v95, v147
	v_lshlrev_b32_e32 v141, 16, v122
	v_and_b32_e32 v142, 0xffff0000, v122
	v_lshlrev_b32_e32 v143, 16, v123
	v_and_b32_e32 v144, 0xffff0000, v123
	v_fmac_f32_e32 v80, v146, v141
	v_fmac_f32_e32 v81, v146, v142
	v_fmac_f32_e32 v82, v146, v143
	v_fmac_f32_e32 v83, v146, v144
	v_cvt_pk_bf16_f32 v132, v80, v81
	v_cvt_pk_bf16_f32 v133, v82, v83
	v_lshlrev_b32_e32 v141, 16, v124
	v_and_b32_e32 v142, 0xffff0000, v124
	v_lshlrev_b32_e32 v143, 16, v125
	v_and_b32_e32 v144, 0xffff0000, v125
	v_fmac_f32_e32 v84, v146, v141
	v_fmac_f32_e32 v85, v146, v142
	v_fmac_f32_e32 v86, v146, v143
	v_fmac_f32_e32 v87, v146, v144
	v_cvt_pk_bf16_f32 v134, v84, v85
	v_cvt_pk_bf16_f32 v135, v86, v87
	v_lshlrev_b32_e32 v141, 16, v126
	v_and_b32_e32 v142, 0xffff0000, v126
	v_lshlrev_b32_e32 v143, 16, v127
	v_and_b32_e32 v144, 0xffff0000, v127
	v_fmac_f32_e32 v88, v146, v141
	v_fmac_f32_e32 v89, v146, v142
	v_fmac_f32_e32 v90, v146, v143
	v_fmac_f32_e32 v91, v146, v144
	v_cvt_pk_bf16_f32 v136, v88, v89
	v_cvt_pk_bf16_f32 v137, v90, v91
	v_lshlrev_b32_e32 v141, 16, v128
	v_and_b32_e32 v142, 0xffff0000, v128
	v_lshlrev_b32_e32 v143, 16, v129
	v_and_b32_e32 v144, 0xffff0000, v129
	v_fmac_f32_e32 v92, v146, v141
	v_fmac_f32_e32 v93, v146, v142
	v_fmac_f32_e32 v94, v146, v143
	v_fmac_f32_e32 v95, v146, v144
	v_cvt_pk_bf16_f32 v138, v92, v93
	v_cvt_pk_bf16_f32 v139, v94, v95
	s_mov_b64 s[26:27], s[86:87]
	s_mov_b64 s[28:29], s[88:89]
	s_mov_b64 s[86:87], s[12:13]
	s_mov_b64 s[88:89], s[14:15]
	s_mov_b32 s4, s83
	s_mov_b32 s5, s84
	s_add_u32 s7, s7, 1
	s_cmp_lt_u32 s7, 2
	s_cbranch_scc1 .Lat991_loop
	s_setprio 0
	global_store_dwordx2 v237, v[132:133], s[26:27]
	global_store_dwordx2 v237, v[134:135], s[26:27] offset:32
	global_store_dwordx2 v237, v[136:137], s[26:27] offset:64
	global_store_dwordx2 v237, v[138:139], s[26:27] offset:96
	s_mov_b64 s[90:91], exec
	s_mov_b64 exec, 0xffff
	global_store_dword v238, v140, s[28:29]
	s_mov_b64 exec, s[90:91]
	s_waitcnt vmcnt(0)
	s_barrier
	s_waitcnt vmcnt(0)
	s_barrier
	s_mov_b64 s[4:5], exec
	v_readlane_b32 s0, v252, 2
	v_readlane_b32 s1, v252, 3
	v_readlane_b32 s64, v253, 15
	v_readlane_b32 s34, v252, 27
	v_readlane_b32 s56, v253, 19
	v_readlane_b32 s16, v253, 21
	v_readlane_b32 s36, v252, 29
	v_readlane_b32 s70, v252, 31
	v_readlane_b32 s74, v252, 33
	v_readlane_b32 s76, v252, 35
	v_readlane_b32 s78, v252, 37
	s_and_b64 s[0:1], s[4:5], s[0:1]
	v_readlane_b32 s85, v253, 23
	v_readlane_b32 s92, v253, 24
	v_readlane_b32 s65, v253, 16
	v_readlane_b32 s63, v252, 26
	v_readlane_b32 s66, v253, 18
	v_readlane_b32 s35, v252, 28
	v_readlane_b32 s57, v253, 20
	v_readlane_b32 s17, v253, 22
	v_readlane_b32 s37, v252, 30
	v_readlane_b32 s71, v252, 32
	v_readlane_b32 s75, v252, 34
	v_readlane_b32 s77, v252, 36
	v_readlane_b32 s79, v252, 38
	v_readlane_b32 s93, v253, 25
	s_mov_b64 exec, s[0:1]
	s_cbranch_execz .LBB0_1061
	v_mov_b32_e32 v0, 0x20000
	ds_read_b64 v[0:1], v0
	s_getreg_b32 s44, hwreg(HW_REG_XCC_ID, 0, 4)
	s_lshl_b32 s44, s44, 7
	s_add_u32 s44, s44, 0xdc03600
	v_mov_b32_e32 v2, s44
	v_mov_b32_e32 v4, 1
	s_waitcnt vmcnt(0) lgkmcnt(0)
	global_atomic_add v5, v2, v4, s[42:43] sc0
	buffer_inv sc1
	s_add_u32 s100, s100, 1
	v_readfirstlane_b32 s46, v0
	v_readfirstlane_b32 s47, v1
	v_mov_b32_e32 v2, 0xdc03e00
	s_nop 3
	s_mul_i32 s48, s46, s100
	s_mul_i32 s49, s47, s100
	s_waitcnt vmcnt(1)
	v_readfirstlane_b32 s50, v5
	s_nop 3
	s_add_u32 s50, s50, 1
	s_cmp_lg_u32 s50, s48
	s_cbranch_scc1 .Lxb9_poll
	buffer_wbl2 sc1
	s_waitcnt vmcnt(0)
	global_atomic_add v2, v4, s[42:43]
